# all bit-identical micro-trims together: v95 + attention V-address hoist + attention DMA addresses via SGPR bases + redundant QK-block waits removed (A) + gemm B-fragment LDS addresses hoisted
# baseline (speedup 1.0000x reference)
;   #define CMASK(P0,P1,t) do{}while(0)
;   #define CMASK(P0,P1,t) do{}while(0)
; template<int THRL,bool FIXREF,bool HALFK> __device__ __forceinline__ void attn_unit(float mref,long rowbase,int q0,const bf16*Qh,int PQ,const bf16*__restrict__ Kh_,int PK,const bf16*__restrict__ Vh_,int PV,bf16*Oh,int PO,const bf16*Gh,int PG,u32x4(&okeep)[4],int omode,float lam,float oml,const float ...
;   const int tid=fresh_tid(),lane=tid&63,r32=lane&31,hi=lane>>5; const int wid=__builtin_amdgcn_readfirstlane(tid>>6);
;   const bf16*Qw=Qh+(rowbase+q0+wid*QBLK)*PQ;
;   const bf16*Kh=Kh_+rowbase*PK,*Vh=Vh_+rowbase*PV;
;   const unsigned lds0=(unsigned)(uintptr_t)shm;
;   float*wsf=(float*)(shm+LDS_WS)+wid*64;
;   const bf16*ksrc=Kh+(long)lane*PK+wid*8;
;   const bf16*vsrc=Vh+(long)(16*(wid&3)+(lane>>2))*PV+(wid>>2)*32+(lane&3)*8;
;   const unsigned kdst=lds0+LDS_K+wid*1024, vdst=lds0+LDS_V+wid*1024;
;     ...
;   const int vb0=(int)(lds0+LDS_V)+((lane>>4)&1)*32+(lane&3)*8+(4*hi+((lane&15)>>2))*64;
;   const char*Kbase=shm+LDS_K; bf16x8 kf[8];
;   const lds_cptr shm3=(lds_cptr)shm; const lds_cptr kp0=shm3+LDS_K+hi*1024+r32*16; const lds_cptr vp0=shm3+LDS_V+((lane>>4)&1)*32+(lane&3)*8+(4*hi+((lane&15)>>2))*64;
;   constexpr int NT=SEQ/KVBLK;
;   if(Gh){ const bf16*Gw=Gh+(rowbase+q0+wid*QBLK)*PG;
;     #pragma unroll
;     for(int i=0;i<4;++i) glds16(Gw+(long)(i*8+(lane>>3))*PG+(lane&7)*8,(unsigned)__builtin_amdgcn_readfirstlane(lds0+LDS_GST+wid*4096+i*1024)); }
;   DMA_K(0,0);DMA_V(0,0);DMA_K(1,SLOTB);
;   bf16x8 qr[4];
;   #pragma unroll
;   for(int d0=0;d0<4;++d0)qr[d0]=*reinterpret_cast<const bf16x8*>(&Qw[(long)r32*PQ+d0*16+hi*8]);
;   float mhat=0.f,l_reg=0.f;f32x16 o[2];o[0]=f32x16{};o[1]=f32x16{};f32x16 negm=f32x16{};
;   if constexpr(FIXREF){ mhat=mref; _Pragma("unroll") for(int r=0;r<16;++r)negm[r]=-mref; }
;   asm volatile("":"+v"(negm));
;     ...
;   bool resc=false;
;     ...
;   f32x16 pA0,pA1,pB0,pB1;
;   int sl_prev=0,sl_cur=0,sl_next=SLOTB;
;     ...
;   DMA_K(2,2*SLOTB);
;   WAIT_BAR(3);
;   qkt<HALFK?2:4>(pA0,pA1,Kbase,qr,negm,r32,hi);asm volatile("s_nop 15\n\ts_nop 7":"+v"(pA0),"+v"(pA1));CMASK(pA0,pA1,0);
;   START(pA0,pA1);
;   _Pragma("unroll") for(int r=0;r<16;++r)pA1[r]=__builtin_amdgcn_exp2f(pA1[r]);
;   WAIT_BAR(0);
;   DMA_K(3,0);DMA_V(1,SLOTB);
;   ROT();
;   if constexpr(HALFK){ kload2(kf,kp0+sl_cur,0); kload2(kf,kp0+sl_cur,1); } else kload8(kf,kp0+sl_cur);
;   WAIT_BAR(2);
.LBB0_450:
	s_bfe_u32 s16, s58, 0x20004
	s_lshl_b32 s59, s16, 6
	s_and_b32 s67, s59, 0x80
	s_ashr_i32 s42, s58, 6
	s_lshl_b32 s16, s16, 7
	s_add_u32 s46, s2, s16
	s_addc_u32 s47, s3, 0
	s_lshl_b32 s17, s58, 2
	s_and_b32 s17, s17, 0x80
	s_add_u32 s60, s14, s17
	s_addc_u32 s61, s15, 0
	s_add_u32 s62, s20, s17
	s_addc_u32 s63, s28, 0
	s_add_u32 s65, s34, s16
	v_mov_b32_e32 v104, v218
	s_addc_u32 s66, s35, 0
	s_ashr_i32 s43, s42, 31
	s_lshl_b32 s40, s58, 8
	s_lshl_b64 s[16:17], s[42:43], 12
	v_readfirstlane_b32 s64, v104
	s_and_b32 s40, s40, 0xf00
	s_ashr_i32 s73, s64, 6
	s_or_b32 s16, s16, s40
	s_lshl_b32 s40, s73, 5
	s_ashr_i32 s41, s40, 31
	s_add_u32 s16, s16, s40
	s_addc_u32 s17, s17, s41
	s_lshl_b64 s[40:41], s[16:17], 9
	s_add_u32 s48, s46, s40
	s_addc_u32 s49, s47, s41
	s_lshl_b64 s[40:41], s[42:43], 20
	s_add_u32 s46, s60, s40
	s_addc_u32 s47, s61, s41
	s_mul_i32 s69, s42, 0x1e00000
	s_mul_hi_i32 s68, s42, 0x1e00000
	s_add_u32 s60, s62, s69
	v_and_b32_e32 v205, 63, v104
	s_addc_u32 s61, s63, s68
	s_lshl_b32 s42, s73, 3
	v_lshlrev_b32_e32 v0, 8, v205
	s_ashr_i32 s43, s42, 31
	v_lshl_add_u64 v[18:19], s[46:47], 0, v[0:1]
	s_lshl_b64 s[42:43], s[42:43], 1
	v_lshl_add_u64 v[210:211], v[18:19], 0, s[42:43]
	s_lshl_b32 s46, s73, 4
	v_bfe_u32 v18, v104, 2, 4
	v_and_or_b32 v18, s46, 48, v18
	s_ashr_i32 s46, s64, 3
	s_andn2_b32 s46, s46, 31
	s_ashr_i32 s47, s46, 31
	s_lshl_b64 s[46:47], s[46:47], 1
	s_lshl_b32 s63, s73, 10
	v_mul_u32_u24_e32 v18, 0xf00, v18
	s_cmp_lg_u32 0, -1
	v_lshlrev_b32_e32 v102, 1, v18
	v_mov_b32_e32 v103, v1
	s_cselect_b32 s75, 0, 0
	v_lshl_add_u64 v[18:19], s[60:61], 0, v[102:103]
	v_lshlrev_b32_e32 v22, 3, v104
	s_add_i32 s62, s63, s75
	s_mul_i32 s60, s17, 0x1e00
	s_mul_hi_u32 s70, s16, 0x1e00
	v_and_b32_e32 v229, 24, v22
	s_add_i32 s61, s62, 0x6000
	s_add_i32 s60, s70, s60
	s_mul_i32 s70, s16, 0x1e00
	v_lshl_add_u64 v[18:19], v[18:19], 0, s[46:47]
	v_lshlrev_b32_e32 v20, 1, v229
	v_mov_b32_e32 v21, v1
	s_add_u32 s70, s65, s70
	v_bfe_u32 v203, v104, 3, 3
	v_and_b32_e32 v206, 56, v22
	v_lshl_add_u64 v[208:209], v[18:19], 0, v[20:21]
	s_addc_u32 s71, s66, s60
	v_lshlrev_b32_e32 v18, 1, v206
	v_mov_b32_e32 v19, v1
	s_lshl_b32 s60, s73, 12
	v_mul_u32_u24_e32 v20, 0xf00, v203
	v_lshl_add_u64 v[18:19], s[70:71], 0, v[18:19]
	v_lshlrev_b32_e32 v20, 1, v20
	s_add_i32 s65, s75, s60
	v_lshl_add_u64 v[18:19], v[18:19], 0, v[20:21]
	s_add_i32 s66, s65, 0x14800
	s_mov_b32 s70, m0
	s_mov_b32 m0, s66
	s_nop 0
	global_load_lds_dwordx4 v[18:19], off
	s_mov_b32 m0, s70
	v_lshl_add_u64 v[20:21], v[18:19], 0, s[30:31]
	s_add_i32 s66, s65, 0x14c00
	s_mov_b32 s70, m0
	s_mov_b32 m0, s66
	s_nop 0
	global_load_lds_dwordx4 v[20:21], off
	s_mov_b32 m0, s70
	v_lshl_add_u64 v[20:21], v[18:19], 0, s[56:57]
	s_add_i32 s66, s65, 0x15000
	s_mov_b32 s70, m0
	s_mov_b32 m0, s66
	s_nop 0
	global_load_lds_dwordx4 v[20:21], off
	s_mov_b32 m0, s70
	v_lshl_add_u64 v[18:19], v[18:19], 0, s[8:9]
	s_add_i32 s65, s65, 0x15400
	s_mov_b32 s66, m0
	s_mov_b32 m0, s65
	s_nop 0
	global_load_lds_dwordx4 v[18:19], off
	s_mov_b32 m0, s66
	s_mov_b32 s65, m0
	s_mov_b32 m0, s62
	s_nop 0
	global_load_lds_dwordx4 v[210:211], off
	s_mov_b32 m0, s65
	s_mov_b64 s[70:71], 0x4000
	v_and_b32_e32 v216, 31, v104
	s_mov_b32 s65, m0
	s_mov_b32 m0, s61
	s_nop 0
	global_load_lds_dwordx4 v[208:209], off
	s_mov_b32 m0, s65
	v_lshl_add_u64 v[18:19], v[210:211], 0, s[70:71]
	v_bfe_u32 v217, v104, 5, 1
	s_add_i32 s65, s62, 0x2000
	s_mov_b32 s66, m0
	s_mov_b32 m0, s65
	s_nop 0
	global_load_lds_dwordx4 v[18:19], off
	s_mov_b32 m0, s66
	v_lshlrev_b32_e32 v18, 9, v216
	v_lshl_or_b32 v18, v217, 4, v18
	global_load_dwordx4 v[174:177], v18, s[48:49]
	global_load_dwordx4 v[170:173], v18, s[48:49] offset:32
	global_load_dwordx4 v[162:165], v18, s[48:49] offset:64
	global_load_dwordx4 v[154:157], v18, s[48:49] offset:96
	v_mov_b64_e32 v[64:65], v[16:17]
	v_lshlrev_b32_e32 v18, 10, v217
	v_lshlrev_b32_e32 v19, 4, v216
	v_mov_b64_e32 v[62:63], v[14:15]
	v_mov_b64_e32 v[60:61], v[12:13]
	v_mov_b64_e32 v[58:59], v[10:11]
	v_mov_b64_e32 v[56:57], v[8:9]
	v_mov_b64_e32 v[54:55], v[6:7]
	v_mov_b64_e32 v[52:53], v[4:5]
	v_mov_b64_e32 v[50:51], v[2:3]
	v_add3_u32 v228, 0, v18, v19
	v_lshl_add_u64 v[18:19], v[210:211], 0, s[10:11]
	s_add_i32 s48, s62, 0x4000
	s_mov_b32 s49, m0
	s_mov_b32 m0, s48
	s_nop 0
	global_load_lds_dwordx4 v[18:19], off
	s_mov_b32 m0, s49
	s_waitcnt vmcnt(3) lgkmcnt(0)
	s_barrier
	ds_read_b128 v[18:21], v228
	ds_read_b128 v[66:69], v228 offset:512
	s_or_b32 s69, s69, s67
	s_waitcnt vmcnt(3) lgkmcnt(1)
	v_mfma_f32_32x32x16_bf16 v[34:49], v[18:21], v[174:177], v[50:65]
	v_mov_b32_e32 v232, 0
	s_mov_b32 s48, -1
	s_mov_b32 s66, 0
	s_movk_i32 s65, 0x2000
	s_movk_i32 s49, 0x4000
	s_waitcnt lgkmcnt(0)
	v_mfma_f32_32x32x16_bf16 v[18:33], v[66:69], v[174:177], v[50:65]
	ds_read_b128 v[66:69], v228 offset:2048
	ds_read_b128 v[70:73], v228 offset:2560
	s_waitcnt vmcnt(2) lgkmcnt(1)
	v_mfma_f32_32x32x16_bf16 v[34:49], v[66:69], v[170:173], v[34:49]
	s_waitcnt lgkmcnt(0)
	v_mfma_f32_32x32x16_bf16 v[18:33], v[70:73], v[170:173], v[18:33]
	ds_read_b128 v[66:69], v228 offset:4096
	ds_read_b128 v[70:73], v228 offset:4608
	s_waitcnt vmcnt(1) lgkmcnt(1)
	v_mfma_f32_32x32x16_bf16 v[34:49], v[66:69], v[162:165], v[34:49]
	ds_read_b128 v[66:69], v228 offset:6144
	s_waitcnt lgkmcnt(1)
	v_mfma_f32_32x32x16_bf16 v[18:33], v[70:73], v[162:165], v[18:33]
	ds_read_b128 v[70:73], v228 offset:6656
	s_waitcnt vmcnt(0) lgkmcnt(1)
	v_mfma_f32_32x32x16_bf16 v[34:49], v[66:69], v[154:157], v[34:49]
	v_lshlrev_b32_e32 v66, 1, v104
	v_lshlrev_b32_e32 v67, 4, v104
	v_and_b32_e32 v231, 32, v66
	v_and_b32_e32 v66, 0xc0, v67
	v_lshl_or_b32 v230, v217, 8, v66
	v_add_u32_e32 v66, 0, v231
	v_add3_u32 v227, v66, v229, v230
	s_waitcnt lgkmcnt(0)
	v_mfma_f32_32x32x16_bf16 v[18:33], v[70:73], v[154:157], v[18:33]
	s_nop 15
	s_nop 7
	s_waitcnt vmcnt(0) lgkmcnt(0)
	s_barrier
; #define WAIT_BAR(N) asm volatile("s_waitcnt vmcnt(" #N ") lgkmcnt(0)\n\ts_barrier":::"memory")
; __device__ __forceinline__ void kload2(bf16x8*kf,lds_cptr kp,int j){ kf[2*j]=*(const __attribute__((address_space(3))) bf16x8*)(kp+j*2048); kf[2*j+1]=*(const __attribute__((address_space(3))) bf16x8*)(kp+j*2048+512); }
;   #define DMA_K(t,slot) glds16(ksrc+(long)(t)*KVBLK*PK,(unsigned)__builtin_amdgcn_readfirstlane(kdst+(slot)))
;   #define DMA_V(t,slot) glds16(vsrc+(long)(t)*KVBLK*PV,(unsigned)__builtin_amdgcn_readfirstlane(vdst+(slot)))
;   #define ROT() do{sl_prev=sl_cur;sl_cur=sl_next;sl_next=(sl_next==(NSLOT-1)*SLOTB)?0:sl_next+SLOTB;}while(0)
; template<int THRL,bool FIXREF,bool HALFK> __device__ __forceinline__ void attn_unit(float mref,long rowbase,int q0,const bf16*Qh,int PQ,const bf16*__restrict__ Kh_,int PK,const bf16*__restrict__ Vh_,int PV,bf16*Oh,int PO,const bf16*Gh,int PG,u32x4(&okeep)[4],int omode,float lam,float oml,const float ...
;     ...
;   START(pA0,pA1);
;   _Pragma("unroll") for(int r=0;r<16;++r)pA1[r]=__builtin_amdgcn_exp2f(pA1[r]);
;   WAIT_BAR(0);
;   DMA_K(3,0);DMA_V(1,SLOTB);
;   ROT();
;   if constexpr(HALFK){ kload2(kf,kp0+sl_cur,0); kload2(kf,kp0+sl_cur,1); } else kload8(kf,kp0+sl_cur);
;   WAIT_BAR(2);
	s_nop 2
	v_exp_f32_e32 v82, v34
	v_exp_f32_e32 v83, v35
	s_nop 6
	v_exp_f32_e32 v66, v18
	v_exp_f32_e32 v67, v19
	v_lshl_add_u64 v[18:19], v[210:211], 0, s[12:13]
	s_mov_b32 s70, m0
	s_mov_b32 m0, s62
	s_nop 0
	global_load_lds_dwordx4 v[18:19], off
	s_mov_b32 m0, s70
	v_lshl_add_u64 v[18:19], v[208:209], 0, s[22:23]
	s_add_i32 s70, s62, 0x8000
	s_mov_b32 s71, m0
	s_mov_b32 m0, s70
	s_nop 0
	global_load_lds_dwordx4 v[18:19], off
	s_mov_b32 m0, s71
	ds_read_b128 v[98:101], v228 offset:8192
	ds_read_b128 v[182:185], v228 offset:8704
	ds_read_b128 v[186:189], v228 offset:10240
	ds_read_b128 v[178:181], v228 offset:10752
	ds_read_b128 v[142:145], v228 offset:12288
	ds_read_b128 v[138:141], v228 offset:12800
	ds_read_b128 v[134:137], v228 offset:14336
	ds_read_b128 v[130:133], v228 offset:14848
	s_add_u32 s46, s46, s69
	s_addc_u32 s47, s47, s68
	s_add_u32 s42, s50, s42
	s_addc_u32 s43, s51, s43
	s_add_u32 s42, s42, s67
	v_exp_f32_e32 v84, v36
	v_exp_f32_e32 v85, v37
	v_exp_f32_e32 v86, v38
	v_exp_f32_e32 v87, v39
	v_exp_f32_e32 v88, v40
	v_exp_f32_e32 v89, v41
	v_exp_f32_e32 v90, v42
	v_exp_f32_e32 v91, v43
	v_exp_f32_e32 v92, v44
	v_exp_f32_e32 v93, v45
	v_exp_f32_e32 v94, v46
	v_exp_f32_e32 v95, v47
	v_exp_f32_e32 v96, v48
	v_exp_f32_e32 v97, v49
	v_exp_f32_e32 v68, v20
	v_exp_f32_e32 v69, v21
	v_exp_f32_e32 v70, v22
	v_exp_f32_e32 v71, v23
	v_exp_f32_e32 v72, v24
	v_exp_f32_e32 v73, v25
	v_exp_f32_e32 v74, v26
	v_exp_f32_e32 v75, v27
	v_exp_f32_e32 v76, v28
	v_exp_f32_e32 v77, v29
	v_exp_f32_e32 v78, v30
	v_exp_f32_e32 v79, v31
	v_exp_f32_e32 v80, v32
	v_exp_f32_e32 v81, v33
	v_and_b32_e32 v18, 3, v104
	s_addc_u32 s43, s43, 0
	s_waitcnt vmcnt(2) lgkmcnt(0)
	s_barrier
	v_lshl_or_b32 v18, v18, 4, s46
	s_add_u32 s40, s42, s40
	v_subrev_u32_e32 v18, s46, v18
	s_addc_u32 s41, s43, s41
	v_add_u32_e32 v212, v18, v102
	s_add_u32 s82, s0, s46
	s_addc_u32 s83, s1, s47
	v_mov_b32_e32 v214, v0
	s_mov_b32 s80, s40
	s_mov_b32 s81, s41
	v_mov_b32_e32 v18, 0
	v_mov_b32_e32 v19, v232
	v_mov_b32_e32 v20, v232
	v_mov_b32_e32 v21, v232
	v_mov_b32_e32 v22, v232
	v_mov_b32_e32 v23, v232
	v_mov_b32_e32 v24, v232
	v_mov_b32_e32 v25, v232
	v_mov_b32_e32 v26, v232
	v_mov_b32_e32 v27, v232
	v_mov_b32_e32 v28, v232
	v_mov_b32_e32 v29, v232
	v_mov_b32_e32 v30, v232
	v_mov_b32_e32 v31, v232
	v_mov_b32_e32 v32, v232
	v_mov_b32_e32 v33, v232
	v_mov_b32_e32 v34, 0
	v_mov_b32_e32 v35, v232
	v_mov_b32_e32 v36, v232
	v_mov_b32_e32 v37, v232
	v_mov_b32_e32 v38, v232
	v_mov_b32_e32 v39, v232
	v_mov_b32_e32 v40, v232
	v_mov_b32_e32 v41, v232
	v_mov_b32_e32 v42, v232
	v_mov_b32_e32 v43, v232
	v_mov_b32_e32 v44, v232
	v_mov_b32_e32 v45, v232
	v_mov_b32_e32 v46, v232
	v_mov_b32_e32 v47, v232
	v_mov_b32_e32 v48, v232
	v_mov_b32_e32 v49, v232
	v_add_u32_e32 v0, s66, v227
.LBB0_451:
	ds_read_b64_tr_b16 v[234:235], v0 offset:24576
	ds_read_b64_tr_b16 v[236:237], v0 offset:25088
	v_add_f32_e32 v102, v82, v83
	v_add_f32_e32 v102, v84, v102
	v_add_f32_e32 v102, v85, v102
	v_add_f32_e32 v102, v86, v102
	v_add_f32_e32 v102, v87, v102
	v_cvt_pk_bf16_f32 v166, v82, v83
	v_cvt_pk_bf16_f32 v167, v84, v85
	v_mfma_f32_32x32x16_bf16 v[114:129], v[98:101], v[174:177], v[50:65]
	ds_read_b64_tr_b16 v[82:83], v0 offset:28672
	ds_read_b64_tr_b16 v[84:85], v0 offset:29184
	v_add_f32_e32 v98, v88, v102
	v_add_f32_e32 v98, v89, v98
	v_add_f32_e32 v98, v90, v98
	v_add_f32_e32 v146, v91, v98
	v_mfma_f32_32x32x16_bf16 v[98:113], v[182:185], v[174:177], v[50:65]
	v_cvt_pk_bf16_f32 v168, v86, v87
	v_cvt_pk_bf16_f32 v169, v88, v89
	ds_read_b64_tr_b16 v[86:87], v0 offset:25600
	ds_read_b64_tr_b16 v[88:89], v0 offset:26112
	v_add_f32_e32 v146, v92, v146
	v_add_f32_e32 v146, v93, v146
	v_add_f32_e32 v146, v94, v146
	v_add_f32_e32 v146, v95, v146
	v_cvt_pk_bf16_f32 v158, v90, v91
	v_cvt_pk_bf16_f32 v159, v92, v93
	v_mfma_f32_32x32x16_bf16 v[114:129], v[186:189], v[170:173], v[114:129]
	ds_read_b64_tr_b16 v[90:91], v0 offset:29696
	ds_read_b64_tr_b16 v[92:93], v0 offset:30208
	v_mfma_f32_32x32x16_bf16 v[98:113], v[178:181], v[170:173], v[98:113]
	v_add_f32_e32 v146, v96, v146
	v_add_f32_e32 v146, v97, v146
	v_add_f32_e32 v146, v66, v146
	v_add_f32_e32 v146, v67, v146
	v_cvt_pk_bf16_f32 v160, v94, v95
	v_cvt_pk_bf16_f32 v161, v96, v97
	ds_read_b64_tr_b16 v[94:95], v0 offset:26624
	ds_read_b64_tr_b16 v[96:97], v0 offset:27136
	v_mfma_f32_32x32x16_bf16 v[114:129], v[142:145], v[162:165], v[114:129]
	v_add_f32_e32 v142, v68, v146
	v_add_f32_e32 v142, v69, v142
	v_add_f32_e32 v142, v70, v142
	v_add_f32_e32 v142, v71, v142
	v_cvt_pk_bf16_f32 v150, v66, v67
	v_cvt_pk_bf16_f32 v151, v68, v69
	ds_read_b64_tr_b16 v[66:67], v0 offset:30720
	ds_read_b64_tr_b16 v[68:69], v0 offset:31232
	v_mfma_f32_32x32x16_bf16 v[98:113], v[138:141], v[162:165], v[98:113]
	v_add_f32_e32 v138, v72, v142
	v_add_f32_e32 v138, v73, v138
	v_add_f32_e32 v138, v74, v138
	v_add_f32_e32 v138, v75, v138
	v_cvt_pk_bf16_f32 v152, v70, v71
	v_cvt_pk_bf16_f32 v153, v72, v73
	ds_read_b64_tr_b16 v[70:71], v0 offset:27648
	ds_read_b64_tr_b16 v[72:73], v0 offset:28160
	v_mfma_f32_32x32x16_bf16 v[114:129], v[134:137], v[154:157], v[114:129]
	v_add_f32_e32 v134, v76, v138
	v_add_f32_e32 v134, v77, v134
	v_add_f32_e32 v134, v78, v134
	v_add_f32_e32 v134, v79, v134
	v_cvt_pk_bf16_f32 v146, v74, v75
	v_cvt_pk_bf16_f32 v147, v76, v77
	ds_read_b64_tr_b16 v[74:75], v0 offset:31744
	ds_read_b64_tr_b16 v[76:77], v0 offset:32256
	v_mfma_f32_32x32x16_bf16 v[98:113], v[130:133], v[154:157], v[98:113]
	v_add_f32_e32 v0, v80, v134
	v_add_f32_e32 v0, v81, v0
	v_cvt_pk_bf16_f32 v148, v78, v79
	v_cvt_pk_bf16_f32 v149, v80, v81
	s_add_u32 s84, s80, s12
	s_addc_u32 s85, s81, s13
	s_add_i32 s40, s65, s62
	s_mov_b32 s41, m0
	s_mov_b32 m0, s40
	s_nop 0
	global_load_lds_dwordx4 v214, s[84:85]
	s_mov_b32 m0, s41
	s_add_u32 s84, s82, s22
	s_addc_u32 s85, s83, s23
	s_add_i32 s40, s49, s61
	s_mov_b32 s41, m0
	s_mov_b32 m0, s40
	s_nop 0
	global_load_lds_dwordx4 v212, s[84:85]
	s_mov_b32 m0, s41
	v_add_f32_e32 v0, v232, v0
	s_waitcnt lgkmcnt(14)
; #define WAIT_BAR(N) asm volatile("s_waitcnt vmcnt(" #N ") lgkmcnt(0)\n\ts_barrier":::"memory")
;   #define RESC() do{ if(!FIXREF&&resc){ asm volatile("s_waitcnt lgkmcnt(0)":::"memory"); \
;       _Pragma("unroll") for(int d_=0;d_<2;++d_) _Pragma("unroll") for(int r=0;r<16;++r)o[d_][r]*=wsf[crow(r,hi)]; } }while(0)
;   #define ROT() do{sl_prev=sl_cur;sl_cur=sl_next;sl_next=(sl_next==(NSLOT-1)*SLOTB)?0:sl_next+SLOTB;}while(0)
; template<int THRL,bool FIXREF,bool HALFK> __device__ __forceinline__ void attn_unit(float mref,long rowbase,int q0,const bf16*Qh,int PQ,const bf16*__restrict__ Kh_,int PK,const bf16*__restrict__ Vh_,int PV,bf16*Oh,int PO,const bf16*Gh,int PG,u32x4(&okeep)[4],int omode,float lam,float oml,const float ...
;     ...
;   for(;t+5<NT;t+=2){
;     STEP(pB0,pB1,pA0,pA1,t,true,true,true);     WAIT_BAR(2); RESC(); ROT();
;     STEP(pA0,pA1,pB0,pB1,t+1,true,true,true);   WAIT_BAR(2); RESC(); ROT();
;   }
	v_mfma_f32_32x32x16_bf16 v[18:33], v[166:169], v[234:237], v[18:33]
	v_exp_f32_e32 v114, v114
	v_exp_f32_e32 v115, v115
	v_exp_f32_e32 v116, v116
	v_exp_f32_e32 v117, v117
	s_waitcnt lgkmcnt(12)
	v_mfma_f32_32x32x16_bf16 v[34:49], v[166:169], v[82:85], v[34:49]
	v_exp_f32_e32 v118, v118
	v_exp_f32_e32 v119, v119
	v_exp_f32_e32 v120, v120
	v_exp_f32_e32 v121, v121
	v_add_u32_e32 v82, s49, v228
	ds_read_b128 v[78:81], v82
	ds_read_b128 v[134:137], v82 offset:512
	s_waitcnt lgkmcnt(12)
	v_mfma_f32_32x32x16_bf16 v[18:33], v[158:161], v[86:89], v[18:33]
	v_exp_f32_e32 v122, v122
	v_exp_f32_e32 v123, v123
	v_exp_f32_e32 v124, v124
	v_exp_f32_e32 v125, v125
	ds_read_b128 v[138:141], v82 offset:2048
	ds_read_b128 v[142:145], v82 offset:2560
	s_waitcnt lgkmcnt(12)
	v_mfma_f32_32x32x16_bf16 v[34:49], v[158:161], v[90:93], v[34:49]
	v_exp_f32_e32 v126, v126
	v_exp_f32_e32 v127, v127
	v_exp_f32_e32 v128, v128
	v_exp_f32_e32 v129, v129
	ds_read_b128 v[178:181], v82 offset:4096
	ds_read_b128 v[182:185], v82 offset:4608
	s_waitcnt lgkmcnt(12)
	v_mfma_f32_32x32x16_bf16 v[18:33], v[150:153], v[94:97], v[18:33]
	v_exp_f32_e32 v98, v98
	v_exp_f32_e32 v99, v99
	v_exp_f32_e32 v100, v100
	v_exp_f32_e32 v101, v101
	ds_read_b128 v[186:189], v82 offset:6144
	ds_read_b128 v[130:133], v82 offset:6656
	s_waitcnt lgkmcnt(12)
	v_mfma_f32_32x32x16_bf16 v[34:49], v[150:153], v[66:69], v[34:49]
	v_exp_f32_e32 v102, v102
	v_exp_f32_e32 v103, v103
	v_exp_f32_e32 v104, v104
	v_exp_f32_e32 v105, v105
	s_waitcnt lgkmcnt(10)
	v_mfma_f32_32x32x16_bf16 v[18:33], v[146:149], v[70:73], v[18:33]
	v_exp_f32_e32 v106, v106
	v_exp_f32_e32 v107, v107
	v_exp_f32_e32 v108, v108
	v_exp_f32_e32 v109, v109
	s_waitcnt lgkmcnt(8)
	v_mfma_f32_32x32x16_bf16 v[34:49], v[146:149], v[74:77], v[34:49]
	v_exp_f32_e32 v110, v110
	v_exp_f32_e32 v111, v111
	v_exp_f32_e32 v112, v112
	v_exp_f32_e32 v113, v113
	s_add_i32 s40, s49, 0x2000
	s_cmpk_lg_i32 s49, 0x4000
	s_cselect_b32 s40, s40, 0
	v_add_u32_e32 v232, s65, v227
	s_waitcnt vmcnt(2) lgkmcnt(0)
	s_barrier
	ds_read_b64_tr_b16 v[234:235], v232 offset:24576
	ds_read_b64_tr_b16 v[236:237], v232 offset:25088
	v_mfma_f32_32x32x16_bf16 v[82:97], v[78:81], v[174:177], v[50:65]
	v_add_f32_e32 v66, v114, v115
	v_add_f32_e32 v66, v116, v66
	v_add_f32_e32 v66, v117, v66
	v_add_f32_e32 v66, v118, v66
	v_add_f32_e32 v66, v119, v66
	v_cvt_pk_bf16_f32 v166, v114, v115
	v_cvt_pk_bf16_f32 v167, v116, v117
	ds_read_b64_tr_b16 v[114:115], v232 offset:28672
	ds_read_b64_tr_b16 v[116:117], v232 offset:29184
	v_add_f32_e32 v66, v120, v66
	v_add_f32_e32 v66, v121, v66
	v_add_f32_e32 v66, v122, v66
	v_add_f32_e32 v146, v123, v66
	v_mfma_f32_32x32x16_bf16 v[66:81], v[134:137], v[174:177], v[50:65]
	v_cvt_pk_bf16_f32 v168, v118, v119
	v_cvt_pk_bf16_f32 v169, v120, v121
	ds_read_b64_tr_b16 v[118:119], v232 offset:25600
	ds_read_b64_tr_b16 v[120:121], v232 offset:26112
	v_mfma_f32_32x32x16_bf16 v[82:97], v[138:141], v[170:173], v[82:97]
	v_add_f32_e32 v134, v124, v146
	v_add_f32_e32 v134, v125, v134
	v_add_f32_e32 v134, v126, v134
	v_add_f32_e32 v134, v127, v134
	v_cvt_pk_bf16_f32 v158, v122, v123
	v_cvt_pk_bf16_f32 v159, v124, v125
	ds_read_b64_tr_b16 v[122:123], v232 offset:29696
	ds_read_b64_tr_b16 v[124:125], v232 offset:30208
	v_mfma_f32_32x32x16_bf16 v[66:81], v[142:145], v[170:173], v[66:81]
	v_add_f32_e32 v134, v128, v134
	v_add_f32_e32 v134, v129, v134
	v_add_f32_e32 v134, v98, v134
	v_add_f32_e32 v134, v99, v134
	v_cvt_pk_bf16_f32 v160, v126, v127
	v_cvt_pk_bf16_f32 v161, v128, v129
	ds_read_b64_tr_b16 v[126:127], v232 offset:26624
	ds_read_b64_tr_b16 v[128:129], v232 offset:27136
	v_mfma_f32_32x32x16_bf16 v[82:97], v[178:181], v[162:165], v[82:97]
	v_add_f32_e32 v134, v100, v134
	v_add_f32_e32 v134, v101, v134
	v_add_f32_e32 v134, v102, v134
	v_add_f32_e32 v134, v103, v134
	v_cvt_pk_bf16_f32 v150, v98, v99
	v_cvt_pk_bf16_f32 v151, v100, v101
	ds_read_b64_tr_b16 v[238:239], v232 offset:30720
	ds_read_b64_tr_b16 v[240:241], v232 offset:31232
	v_mfma_f32_32x32x16_bf16 v[66:81], v[182:185], v[162:165], v[66:81]
	v_add_f32_e32 v98, v104, v134
	v_add_f32_e32 v98, v105, v98
	v_add_f32_e32 v98, v106, v98
	v_add_f32_e32 v98, v107, v98
	v_cvt_pk_bf16_f32 v152, v102, v103
	v_cvt_pk_bf16_f32 v153, v104, v105
	ds_read_b64_tr_b16 v[102:103], v232 offset:27648
	ds_read_b64_tr_b16 v[104:105], v232 offset:28160
	v_mfma_f32_32x32x16_bf16 v[82:97], v[186:189], v[154:157], v[82:97]
	v_add_f32_e32 v98, v108, v98
	v_add_f32_e32 v98, v109, v98
	v_add_f32_e32 v98, v110, v98
	v_add_f32_e32 v98, v111, v98
	v_cvt_pk_bf16_f32 v146, v106, v107
	v_cvt_pk_bf16_f32 v147, v108, v109
	ds_read_b64_tr_b16 v[106:107], v232 offset:31744
	ds_read_b64_tr_b16 v[108:109], v232 offset:32256
	v_mfma_f32_32x32x16_bf16 v[66:81], v[130:133], v[154:157], v[66:81]
	v_add_f32_e32 v98, v112, v98
	v_add_f32_e32 v98, v113, v98
	v_cvt_pk_bf16_f32 v148, v110, v111
	v_cvt_pk_bf16_f32 v149, v112, v113
	s_nop 0
	v_add_f32_e32 v232, v0, v98
	s_add_u32 s84, s80, s92
	s_addc_u32 s85, s81, s93
	s_add_i32 s41, s49, s62
	s_mov_b32 s42, m0
	s_mov_b32 m0, s41
	s_nop 0
	global_load_lds_dwordx4 v214, s[84:85]
	s_mov_b32 m0, s42
	s_add_u32 s82, s82, s4
	s_addc_u32 s83, s83, s5
	s_add_i32 s41, s40, s61
	s_mov_b32 s42, m0
	s_mov_b32 m0, s41
	s_nop 0
	global_load_lds_dwordx4 v212, s[82:83]
	s_mov_b32 m0, s42
	s_waitcnt lgkmcnt(14)
	v_mfma_f32_32x32x16_bf16 v[18:33], v[166:169], v[234:237], v[18:33]
	v_exp_f32_e32 v82, v82
	v_exp_f32_e32 v83, v83
	v_exp_f32_e32 v84, v84
	v_exp_f32_e32 v85, v85
	s_waitcnt lgkmcnt(12)
; #define WAIT_BAR(N) asm volatile("s_waitcnt vmcnt(" #N ") lgkmcnt(0)\n\ts_barrier":::"memory")
;   #define RESC() do{ if(!FIXREF&&resc){ asm volatile("s_waitcnt lgkmcnt(0)":::"memory"); \
;       _Pragma("unroll") for(int d_=0;d_<2;++d_) _Pragma("unroll") for(int r=0;r<16;++r)o[d_][r]*=wsf[crow(r,hi)]; } }while(0)
;   #define ROT() do{sl_prev=sl_cur;sl_cur=sl_next;sl_next=(sl_next==(NSLOT-1)*SLOTB)?0:sl_next+SLOTB;}while(0)
;   #define ENDW(tt) do{ if((tt)+3<NT){WAIT_BAR(2);} else if((tt)+2<NT){WAIT_BAR(1);} else {WAIT_BAR(0);} }while(0)
; template<int THRL,bool FIXREF,bool HALFK> __device__ __forceinline__ void attn_unit(float mref,long rowbase,int q0,const bf16*Qh,int PQ,const bf16*__restrict__ Kh_,int PK,const bf16*__restrict__ Vh_,int PV,bf16*Oh,int PO,const bf16*Gh,int PG,u32x4(&okeep)[4],int omode,float lam,float oml,const float ...
;     ...
;   for(;t+5<NT;t+=2){
;     STEP(pB0,pB1,pA0,pA1,t,true,true,true);     WAIT_BAR(2); RESC(); ROT();
;     STEP(pA0,pA1,pB0,pB1,t+1,true,true,true);   WAIT_BAR(2); RESC(); ROT();
;   }
;     ...
;   for(;t+1<NT;t+=2){
;     STEP(pB0,pB1,pA0,pA1,t,(t+3<NT),(t+1<NT),(t+1<NT));       ENDW(t);   RESC(); ROT();
	v_mfma_f32_32x32x16_bf16 v[34:49], v[166:169], v[114:117], v[34:49]
	v_exp_f32_e32 v86, v86
	v_exp_f32_e32 v87, v87
	v_exp_f32_e32 v88, v88
	v_exp_f32_e32 v89, v89
	v_add_u32_e32 v0, s40, v228
	ds_read_b128 v[98:101], v0
	ds_read_b128 v[182:185], v0 offset:512
	s_waitcnt lgkmcnt(12)
	v_mfma_f32_32x32x16_bf16 v[18:33], v[158:161], v[118:121], v[18:33]
	v_exp_f32_e32 v90, v90
	v_exp_f32_e32 v91, v91
	v_exp_f32_e32 v92, v92
	v_exp_f32_e32 v93, v93
	ds_read_b128 v[186:189], v0 offset:2048
	ds_read_b128 v[178:181], v0 offset:2560
	s_waitcnt lgkmcnt(12)
	v_mfma_f32_32x32x16_bf16 v[34:49], v[158:161], v[122:125], v[34:49]
	v_exp_f32_e32 v94, v94
	v_exp_f32_e32 v95, v95
	v_exp_f32_e32 v96, v96
	v_exp_f32_e32 v97, v97
	ds_read_b128 v[142:145], v0 offset:4096
	ds_read_b128 v[138:141], v0 offset:4608
	s_waitcnt lgkmcnt(12)
	v_mfma_f32_32x32x16_bf16 v[18:33], v[150:153], v[126:129], v[18:33]
	v_exp_f32_e32 v66, v66
	v_exp_f32_e32 v67, v67
	v_exp_f32_e32 v68, v68
	v_exp_f32_e32 v69, v69
	ds_read_b128 v[134:137], v0 offset:6144
	ds_read_b128 v[130:133], v0 offset:6656
	s_waitcnt lgkmcnt(12)
	v_mfma_f32_32x32x16_bf16 v[34:49], v[150:153], v[238:241], v[34:49]
	v_exp_f32_e32 v70, v70
	v_exp_f32_e32 v71, v71
	v_exp_f32_e32 v72, v72
	v_exp_f32_e32 v73, v73
	s_waitcnt lgkmcnt(10)
	v_mfma_f32_32x32x16_bf16 v[18:33], v[146:149], v[102:105], v[18:33]
	v_exp_f32_e32 v74, v74
	v_exp_f32_e32 v75, v75
	v_exp_f32_e32 v76, v76
	v_exp_f32_e32 v77, v77
	s_waitcnt lgkmcnt(8)
	v_mfma_f32_32x32x16_bf16 v[34:49], v[146:149], v[106:109], v[34:49]
	v_exp_f32_e32 v78, v78
	v_exp_f32_e32 v79, v79
	v_exp_f32_e32 v80, v80
	v_exp_f32_e32 v81, v81
	s_add_i32 s41, s40, 0x2000
	s_cmpk_lg_i32 s40, 0x4000
	s_mov_b32 s66, s49
	v_add_u32_e32 v0, s66, v227
	s_cselect_b32 s49, s41, 0
	s_add_i32 s48, s48, 2
	s_add_u32 s80, s80, s10
	s_addc_u32 s81, s81, s11
	s_mov_b32 s65, s40
	s_cmp_gt_u32 s48, 56
	s_waitcnt vmcnt(2) lgkmcnt(0)
	s_barrier
	s_cbranch_scc0 .LBB0_451
	s_and_b32 s41, s64, 0x3fffffc0
	s_cmp_lg_u32 0, -1
	s_cselect_b32 s40, 0, 0
	s_add_i32 s42, s40, 0x6000
	v_add_u32_e32 v0, s42, v231
	s_lshl_b32 s41, s41, 2
	s_add_i32 s42, s41, 0
	v_add3_u32 v0, v0, v229, v230
	ds_read_b64_tr_b16 v[212:213], v227 offset:32768
	ds_read_b64_tr_b16 v[214:215], v227 offset:33280
	v_add_f32_e32 v102, v82, v83
	v_add_f32_e32 v102, v84, v102
	v_add_f32_e32 v102, v85, v102
	v_add_f32_e32 v102, v86, v102
	v_add_f32_e32 v102, v87, v102
	v_cvt_pk_bf16_f32 v166, v82, v83
	v_cvt_pk_bf16_f32 v167, v84, v85
	s_waitcnt lgkmcnt(9)
	v_mfma_f32_32x32x16_bf16 v[114:129], v[98:101], v[174:177], v[50:65]
	ds_read_b64_tr_b16 v[82:83], v227 offset:36864
	ds_read_b64_tr_b16 v[84:85], v227 offset:37376
	v_add_f32_e32 v98, v88, v102
	v_add_f32_e32 v98, v89, v98
	v_add_f32_e32 v98, v90, v98
	v_add_f32_e32 v146, v91, v98
	v_cvt_pk_bf16_f32 v168, v86, v87
	v_cvt_pk_bf16_f32 v169, v88, v89
	s_waitcnt lgkmcnt(10)
	v_mfma_f32_32x32x16_bf16 v[98:113], v[182:185], v[174:177], v[50:65]
	ds_read_b64_tr_b16 v[86:87], v227 offset:33792
	ds_read_b64_tr_b16 v[88:89], v227 offset:34304
	v_add_f32_e32 v146, v92, v146
	v_add_f32_e32 v146, v93, v146
	v_add_f32_e32 v146, v94, v146
	v_add_f32_e32 v146, v95, v146
	v_cvt_pk_bf16_f32 v158, v90, v91
	v_cvt_pk_bf16_f32 v159, v92, v93
	s_waitcnt lgkmcnt(11)
	v_mfma_f32_32x32x16_bf16 v[114:129], v[186:189], v[170:173], v[114:129]
	ds_read_b64_tr_b16 v[90:91], v227 offset:37888
	ds_read_b64_tr_b16 v[92:93], v227 offset:38400
	v_add_f32_e32 v146, v96, v146
	v_add_f32_e32 v146, v97, v146
	v_add_f32_e32 v146, v66, v146
	v_add_f32_e32 v146, v67, v146
	v_cvt_pk_bf16_f32 v160, v94, v95
	v_cvt_pk_bf16_f32 v161, v96, v97
	s_waitcnt lgkmcnt(12)
	v_mfma_f32_32x32x16_bf16 v[98:113], v[178:181], v[170:173], v[98:113]
	ds_read_b64_tr_b16 v[94:95], v227 offset:34816
	ds_read_b64_tr_b16 v[96:97], v227 offset:35328
	s_waitcnt lgkmcnt(13)
	v_mfma_f32_32x32x16_bf16 v[114:129], v[142:145], v[162:165], v[114:129]
	v_add_f32_e32 v142, v68, v146
	v_add_f32_e32 v142, v69, v142
	v_add_f32_e32 v142, v70, v142
	v_add_f32_e32 v142, v71, v142
	v_cvt_pk_bf16_f32 v150, v66, v67
	v_cvt_pk_bf16_f32 v151, v68, v69
	ds_read_b64_tr_b16 v[66:67], v227 offset:38912
	ds_read_b64_tr_b16 v[68:69], v227 offset:39424
	s_waitcnt lgkmcnt(14)
	v_mfma_f32_32x32x16_bf16 v[98:113], v[138:141], v[162:165], v[98:113]
	v_add_f32_e32 v138, v72, v142
	v_add_f32_e32 v138, v73, v138
	v_add_f32_e32 v138, v74, v138
	v_add_f32_e32 v138, v75, v138
	v_cvt_pk_bf16_f32 v152, v70, v71
	v_cvt_pk_bf16_f32 v153, v72, v73
	ds_read_b64_tr_b16 v[70:71], v227 offset:35840
	ds_read_b64_tr_b16 v[72:73], v227 offset:36352
	s_waitcnt lgkmcnt(14)
	v_mfma_f32_32x32x16_bf16 v[114:129], v[134:137], v[154:157], v[114:129]
	v_add_f32_e32 v134, v76, v138
	v_add_f32_e32 v134, v77, v134
	v_add_f32_e32 v134, v78, v134
	v_add_f32_e32 v134, v79, v134
	v_cvt_pk_bf16_f32 v146, v74, v75
	v_cvt_pk_bf16_f32 v147, v76, v77
	ds_read_b64_tr_b16 v[74:75], v227 offset:39936
	ds_read_b64_tr_b16 v[76:77], v227 offset:40448
	v_mfma_f32_32x32x16_bf16 v[98:113], v[130:133], v[154:157], v[98:113]
	v_add_f32_e32 v130, v80, v134
	v_add_f32_e32 v130, v81, v130
	v_add_f32_e32 v130, 0, v130
	v_cvt_pk_bf16_f32 v148, v78, v79
	v_cvt_pk_bf16_f32 v149, v80, v81
	s_mov_b64 s[46:47], 0xf8000
	s_add_i32 s40, s40, s63
	v_lshl_add_u64 v[78:79], v[210:211], 0, s[46:47]
	s_add_i32 s41, s40, 0x4000
	s_mov_b32 s43, m0
	s_mov_b32 m0, s41
	s_nop 0
	global_load_lds_dwordx4 v[78:79], off
	s_mov_b32 m0, s43
	v_lshl_add_u64 v[78:79], v[208:209], 0, s[18:19]
	s_mov_b32 s41, m0
	s_mov_b32 m0, s61
	s_nop 0
	global_load_lds_dwordx4 v[78:79], off
	s_mov_b32 m0, s41
	v_add_f32_e32 v229, v232, v130
	s_waitcnt lgkmcnt(14)
;   #define RESC() do{ if(!FIXREF&&resc){ asm volatile("s_waitcnt lgkmcnt(0)":::"memory"); \
;       _Pragma("unroll") for(int d_=0;d_<2;++d_) _Pragma("unroll") for(int r=0;r<16;++r)o[d_][r]*=wsf[crow(r,hi)]; } }while(0)
;   #define ROT() do{sl_prev=sl_cur;sl_cur=sl_next;sl_next=(sl_next==(NSLOT-1)*SLOTB)?0:sl_next+SLOTB;}while(0)
;   #define ENDW(tt) do{ if((tt)+3<NT){WAIT_BAR(2);} else if((tt)+2<NT){WAIT_BAR(1);} else {WAIT_BAR(0);} }while(0)
; template<int THRL,bool FIXREF,bool HALFK> __device__ __forceinline__ void attn_unit(float mref,long rowbase,int q0,const bf16*Qh,int PQ,const bf16*__restrict__ Kh_,int PK,const bf16*__restrict__ Vh_,int PV,bf16*Oh,int PO,const bf16*Gh,int PG,u32x4(&okeep)[4],int omode,float lam,float oml,const float ...
;     ...
;   for(;t+1<NT;t+=2){
;     STEP(pB0,pB1,pA0,pA1,t,(t+3<NT),(t+1<NT),(t+1<NT));       ENDW(t);   RESC(); ROT();
	v_mfma_f32_32x32x16_bf16 v[18:33], v[166:169], v[212:215], v[18:33]
	v_exp_f32_e32 v114, v114
	v_exp_f32_e32 v115, v115
	v_exp_f32_e32 v116, v116
	v_exp_f32_e32 v117, v117
	s_waitcnt lgkmcnt(12)
	v_mfma_f32_32x32x16_bf16 v[34:49], v[166:169], v[82:85], v[34:49]
	v_exp_f32_e32 v118, v118
	v_exp_f32_e32 v119, v119
	v_exp_f32_e32 v120, v120
	v_exp_f32_e32 v121, v121
	ds_read_b128 v[78:81], v228
	ds_read_b128 v[178:181], v228 offset:512
	s_waitcnt lgkmcnt(12)
	v_mfma_f32_32x32x16_bf16 v[18:33], v[158:161], v[86:89], v[18:33]
	v_exp_f32_e32 v122, v122
	v_exp_f32_e32 v123, v123
	v_exp_f32_e32 v124, v124
	v_exp_f32_e32 v125, v125
	ds_read_b128 v[86:89], v228 offset:2048
	ds_read_b128 v[182:185], v228 offset:2560
	s_waitcnt lgkmcnt(12)
	v_mfma_f32_32x32x16_bf16 v[34:49], v[158:161], v[90:93], v[34:49]
	v_exp_f32_e32 v126, v126
	v_exp_f32_e32 v127, v127
	v_exp_f32_e32 v128, v128
	v_exp_f32_e32 v129, v129
	ds_read_b128 v[90:93], v228 offset:4096
	ds_read_b128 v[186:189], v228 offset:4608
	s_waitcnt lgkmcnt(12)
	v_mfma_f32_32x32x16_bf16 v[18:33], v[150:153], v[94:97], v[18:33]
	v_exp_f32_e32 v98, v98
	v_exp_f32_e32 v99, v99
	v_exp_f32_e32 v100, v100
	v_exp_f32_e32 v101, v101
	ds_read_b128 v[94:97], v228 offset:6144
	ds_read_b128 v[82:85], v228 offset:6656
	s_waitcnt lgkmcnt(12)
	v_mfma_f32_32x32x16_bf16 v[34:49], v[150:153], v[66:69], v[34:49]
	v_exp_f32_e32 v102, v102
	v_exp_f32_e32 v103, v103
	v_exp_f32_e32 v104, v104
	v_exp_f32_e32 v105, v105
	s_waitcnt lgkmcnt(10)
	v_mfma_f32_32x32x16_bf16 v[18:33], v[146:149], v[70:73], v[18:33]
	v_exp_f32_e32 v106, v106
	v_exp_f32_e32 v107, v107
	v_exp_f32_e32 v108, v108
	v_exp_f32_e32 v109, v109
	s_waitcnt lgkmcnt(8)
	v_mfma_f32_32x32x16_bf16 v[34:49], v[146:149], v[74:77], v[34:49]
	v_exp_f32_e32 v110, v110
	v_exp_f32_e32 v111, v111
	v_exp_f32_e32 v112, v112
	v_exp_f32_e32 v113, v113
	s_waitcnt vmcnt(2) lgkmcnt(0)
	s_barrier
	ds_read_b64_tr_b16 v[212:213], v227 offset:40960
	ds_read_b64_tr_b16 v[214:215], v227 offset:41472
	v_add_f32_e32 v66, v114, v115
	v_add_f32_e32 v66, v116, v66
	v_add_f32_e32 v66, v117, v66
	v_add_f32_e32 v66, v118, v66
	v_add_f32_e32 v66, v119, v66
	v_cvt_pk_bf16_f32 v166, v114, v115
	v_cvt_pk_bf16_f32 v167, v116, v117
	s_waitcnt lgkmcnt(9)
	v_mfma_f32_32x32x16_bf16 v[130:145], v[78:81], v[174:177], v[50:65]
	ds_read_b64_tr_b16 v[114:115], v227 offset:45056
	ds_read_b64_tr_b16 v[116:117], v227 offset:45568
	v_add_f32_e32 v66, v120, v66
	v_add_f32_e32 v66, v121, v66
	v_add_f32_e32 v66, v122, v66
	v_add_f32_e32 v146, v123, v66
	s_waitcnt lgkmcnt(10)
	v_mfma_f32_32x32x16_bf16 v[66:81], v[178:181], v[174:177], v[50:65]
	v_cvt_pk_bf16_f32 v168, v118, v119
	v_cvt_pk_bf16_f32 v169, v120, v121
	ds_read_b64_tr_b16 v[118:119], v227 offset:41984
	ds_read_b64_tr_b16 v[120:121], v227 offset:42496
	s_waitcnt lgkmcnt(11)
	v_mfma_f32_32x32x16_bf16 v[130:145], v[86:89], v[170:173], v[130:145]
	v_add_f32_e32 v86, v124, v146
	v_add_f32_e32 v86, v125, v86
	v_add_f32_e32 v86, v126, v86
	v_add_f32_e32 v146, v127, v86
	v_cvt_pk_bf16_f32 v158, v122, v123
	v_cvt_pk_bf16_f32 v159, v124, v125
	ds_read_b64_tr_b16 v[86:87], v227 offset:46080
	ds_read_b64_tr_b16 v[88:89], v227 offset:46592
	s_waitcnt lgkmcnt(12)
	v_mfma_f32_32x32x16_bf16 v[66:81], v[182:185], v[170:173], v[66:81]
	v_add_f32_e32 v122, v128, v146
	v_add_f32_e32 v122, v129, v122
	v_add_f32_e32 v122, v98, v122
	v_add_f32_e32 v146, v99, v122
	v_cvt_pk_bf16_f32 v160, v126, v127
	v_cvt_pk_bf16_f32 v161, v128, v129
	ds_read_b64_tr_b16 v[122:123], v227 offset:43008
	ds_read_b64_tr_b16 v[124:125], v227 offset:43520
	s_waitcnt lgkmcnt(13)
	v_mfma_f32_32x32x16_bf16 v[130:145], v[90:93], v[162:165], v[130:145]
	v_add_f32_e32 v90, v100, v146
	v_add_f32_e32 v90, v101, v90
	v_add_f32_e32 v90, v102, v90
	v_add_f32_e32 v126, v103, v90
	v_cvt_pk_bf16_f32 v150, v98, v99
	v_cvt_pk_bf16_f32 v151, v100, v101
	ds_read_b64_tr_b16 v[90:91], v227 offset:47104
	ds_read_b64_tr_b16 v[92:93], v227 offset:47616
	s_waitcnt lgkmcnt(14)
	v_mfma_f32_32x32x16_bf16 v[66:81], v[186:189], v[162:165], v[66:81]
	v_add_f32_e32 v98, v104, v126
	v_add_f32_e32 v98, v105, v98
	v_add_f32_e32 v98, v106, v98
	v_add_f32_e32 v98, v107, v98
	v_cvt_pk_bf16_f32 v152, v102, v103
	v_cvt_pk_bf16_f32 v153, v104, v105
	ds_read_b64_tr_b16 v[102:103], v227 offset:44032
	ds_read_b64_tr_b16 v[104:105], v227 offset:44544
	s_waitcnt lgkmcnt(14)
	v_mfma_f32_32x32x16_bf16 v[130:145], v[94:97], v[154:157], v[130:145]
	v_add_f32_e32 v94, v108, v98
	v_add_f32_e32 v94, v109, v94
	v_add_f32_e32 v94, v110, v94
	v_add_f32_e32 v98, v111, v94
	v_cvt_pk_bf16_f32 v146, v106, v107
	v_cvt_pk_bf16_f32 v147, v108, v109
	ds_read_b64_tr_b16 v[94:95], v227 offset:48128
	ds_read_b64_tr_b16 v[96:97], v227 offset:48640
	v_mfma_f32_32x32x16_bf16 v[66:81], v[82:85], v[154:157], v[66:81]
	v_add_f32_e32 v82, v112, v98
	v_add_f32_e32 v82, v113, v82
	v_add_f32_e32 v82, 0, v82
	v_cvt_pk_bf16_f32 v148, v110, v111
	v_cvt_pk_bf16_f32 v149, v112, v113
	s_mov_b64 s[46:47], 0xfc000
	v_add_f32_e32 v229, v229, v82
	v_lshl_add_u64 v[82:83], v[210:211], 0, s[46:47]
	s_mov_b32 s41, m0
	s_mov_b32 m0, s62
	s_nop 0
	global_load_lds_dwordx4 v[82:83], off
	s_mov_b32 m0, s41
	v_lshl_add_u64 v[82:83], v[208:209], 0, s[6:7]
	s_add_i32 s41, s40, 0x8000
	s_mov_b32 s43, m0
	s_mov_b32 m0, s41
	s_nop 0
	global_load_lds_dwordx4 v[82:83], off
	s_mov_b32 m0, s43
	s_waitcnt lgkmcnt(14)
	v_mfma_f32_32x32x16_bf16 v[18:33], v[166:169], v[212:215], v[18:33]
	v_exp_f32_e32 v130, v130
	v_exp_f32_e32 v131, v131
	v_exp_f32_e32 v132, v132
	v_exp_f32_e32 v133, v133
	s_waitcnt lgkmcnt(12)
;   #define RESC() do{ if(!FIXREF&&resc){ asm volatile("s_waitcnt lgkmcnt(0)":::"memory"); \
;       _Pragma("unroll") for(int d_=0;d_<2;++d_) _Pragma("unroll") for(int r=0;r<16;++r)o[d_][r]*=wsf[crow(r,hi)]; } }while(0)
;   #define ROT() do{sl_prev=sl_cur;sl_cur=sl_next;sl_next=(sl_next==(NSLOT-1)*SLOTB)?0:sl_next+SLOTB;}while(0)
;   #define ENDW(tt) do{ if((tt)+3<NT){WAIT_BAR(2);} else if((tt)+2<NT){WAIT_BAR(1);} else {WAIT_BAR(0);} }while(0)
; template<int THRL,bool FIXREF,bool HALFK> __device__ __forceinline__ void attn_unit(float mref,long rowbase,int q0,const bf16*Qh,int PQ,const bf16*__restrict__ Kh_,int PK,const bf16*__restrict__ Vh_,int PV,bf16*Oh,int PO,const bf16*Gh,int PG,u32x4(&okeep)[4],int omode,float lam,float oml,const float ...
;     ...
;   for(;t+1<NT;t+=2){
;     STEP(pB0,pB1,pA0,pA1,t,(t+3<NT),(t+1<NT),(t+1<NT));       ENDW(t);   RESC(); ROT();
;     STEP(pA0,pA1,pB0,pB1,t+1,(t+4<NT),(t+2<NT),(t+2<NT));     ENDW(t+1); RESC(); ROT();
	v_mfma_f32_32x32x16_bf16 v[34:49], v[166:169], v[114:117], v[34:49]
	v_exp_f32_e32 v134, v134
	v_exp_f32_e32 v135, v135
	v_exp_f32_e32 v136, v136
	v_exp_f32_e32 v137, v137
	ds_read_b128 v[82:85], v228 offset:8192
	ds_read_b128 v[106:109], v228 offset:8704
	s_waitcnt lgkmcnt(12)
	v_mfma_f32_32x32x16_bf16 v[18:33], v[158:161], v[118:121], v[18:33]
	v_exp_f32_e32 v138, v138
	v_exp_f32_e32 v139, v139
	v_exp_f32_e32 v140, v140
	v_exp_f32_e32 v141, v141
	ds_read_b128 v[110:113], v228 offset:10240
	ds_read_b128 v[178:181], v228 offset:10752
	s_waitcnt lgkmcnt(12)
	v_mfma_f32_32x32x16_bf16 v[34:49], v[158:161], v[86:89], v[34:49]
	v_exp_f32_e32 v142, v142
	v_exp_f32_e32 v143, v143
	v_exp_f32_e32 v144, v144
	v_exp_f32_e32 v145, v145
	ds_read_b128 v[182:185], v228 offset:12288
	ds_read_b128 v[186:189], v228 offset:12800
	s_waitcnt lgkmcnt(12)
	v_mfma_f32_32x32x16_bf16 v[18:33], v[150:153], v[122:125], v[18:33]
	v_exp_f32_e32 v66, v66
	v_exp_f32_e32 v67, v67
	v_exp_f32_e32 v68, v68
	v_exp_f32_e32 v69, v69
	ds_read_b128 v[210:213], v228 offset:14336
	ds_read_b128 v[98:101], v228 offset:14848
	s_waitcnt lgkmcnt(12)
	v_mfma_f32_32x32x16_bf16 v[34:49], v[150:153], v[90:93], v[34:49]
	v_exp_f32_e32 v70, v70
	v_exp_f32_e32 v71, v71
	v_exp_f32_e32 v72, v72
	v_exp_f32_e32 v73, v73
	s_waitcnt lgkmcnt(10)
	v_mfma_f32_32x32x16_bf16 v[18:33], v[146:149], v[102:105], v[18:33]
	v_exp_f32_e32 v74, v74
	v_exp_f32_e32 v75, v75
	v_exp_f32_e32 v76, v76
	v_exp_f32_e32 v77, v77
	s_waitcnt lgkmcnt(8)
	v_mfma_f32_32x32x16_bf16 v[34:49], v[146:149], v[94:97], v[34:49]
	v_exp_f32_e32 v78, v78
	v_exp_f32_e32 v79, v79
	v_exp_f32_e32 v80, v80
	v_exp_f32_e32 v81, v81
	s_waitcnt vmcnt(2) lgkmcnt(0)
	s_barrier
	ds_read_b64_tr_b16 v[102:103], v227 offset:24576
	ds_read_b64_tr_b16 v[104:105], v227 offset:25088
	v_add_f32_e32 v86, v130, v131
	v_add_f32_e32 v86, v132, v86
	v_add_f32_e32 v86, v133, v86
	v_add_f32_e32 v86, v134, v86
	v_add_f32_e32 v86, v135, v86
	v_cvt_pk_bf16_f32 v166, v130, v131
	v_cvt_pk_bf16_f32 v167, v132, v133
	s_waitcnt lgkmcnt(9)
	v_mfma_f32_32x32x16_bf16 v[114:129], v[82:85], v[174:177], v[50:65]
	ds_read_b64_tr_b16 v[130:131], v227 offset:28672
	ds_read_b64_tr_b16 v[132:133], v227 offset:29184
	v_add_f32_e32 v82, v136, v86
	v_add_f32_e32 v82, v137, v82
	v_add_f32_e32 v82, v138, v82
	v_add_f32_e32 v146, v139, v82
	v_cvt_pk_bf16_f32 v168, v134, v135
	v_cvt_pk_bf16_f32 v169, v136, v137
	s_waitcnt lgkmcnt(10)
	v_mfma_f32_32x32x16_bf16 v[82:97], v[106:109], v[174:177], v[50:65]
	ds_read_b64_tr_b16 v[106:107], v227 offset:25600
	ds_read_b64_tr_b16 v[108:109], v227 offset:26112
	s_waitcnt lgkmcnt(11)
	v_mfma_f32_32x32x16_bf16 v[114:129], v[110:113], v[170:173], v[114:129]
	v_add_f32_e32 v110, v140, v146
	v_add_f32_e32 v110, v141, v110
	v_add_f32_e32 v110, v142, v110
	v_add_f32_e32 v134, v143, v110
	v_cvt_pk_bf16_f32 v158, v138, v139
	v_cvt_pk_bf16_f32 v159, v140, v141
	ds_read_b64_tr_b16 v[110:111], v227 offset:29696
	ds_read_b64_tr_b16 v[112:113], v227 offset:30208
	v_add_f32_e32 v134, v144, v134
	v_add_f32_e32 v134, v145, v134
	v_add_f32_e32 v134, v66, v134
	v_add_f32_e32 v138, v67, v134
	v_cvt_pk_bf16_f32 v160, v142, v143
	v_cvt_pk_bf16_f32 v161, v144, v145
	s_waitcnt lgkmcnt(12)
	v_mfma_f32_32x32x16_bf16 v[82:97], v[178:181], v[170:173], v[82:97]
	ds_read_b64_tr_b16 v[134:135], v227 offset:26624
	ds_read_b64_tr_b16 v[136:137], v227 offset:27136
	v_add_f32_e32 v138, v68, v138
	v_add_f32_e32 v138, v69, v138
	v_add_f32_e32 v138, v70, v138
	v_add_f32_e32 v138, v71, v138
	v_cvt_pk_bf16_f32 v150, v66, v67
	v_cvt_pk_bf16_f32 v151, v68, v69
	s_waitcnt lgkmcnt(13)
	v_mfma_f32_32x32x16_bf16 v[114:129], v[182:185], v[162:165], v[114:129]
	ds_read_b64_tr_b16 v[66:67], v227 offset:30720
	ds_read_b64_tr_b16 v[68:69], v227 offset:31232
	v_add_f32_e32 v138, v72, v138
	v_add_f32_e32 v138, v73, v138
	v_add_f32_e32 v138, v74, v138
	v_add_f32_e32 v138, v75, v138
	v_cvt_pk_bf16_f32 v152, v70, v71
	v_cvt_pk_bf16_f32 v153, v72, v73
	s_waitcnt lgkmcnt(14)
	v_mfma_f32_32x32x16_bf16 v[82:97], v[186:189], v[162:165], v[82:97]
	ds_read_b64_tr_b16 v[70:71], v227 offset:27648
	ds_read_b64_tr_b16 v[72:73], v227 offset:28160
	v_add_f32_e32 v138, v76, v138
	v_add_f32_e32 v138, v77, v138
	v_add_f32_e32 v138, v78, v138
	v_add_f32_e32 v138, v79, v138
	v_cvt_pk_bf16_f32 v146, v74, v75
	v_cvt_pk_bf16_f32 v147, v76, v77
	s_waitcnt lgkmcnt(14)
	v_mfma_f32_32x32x16_bf16 v[114:129], v[210:213], v[154:157], v[114:129]
	ds_read_b64_tr_b16 v[74:75], v227 offset:31744
	ds_read_b64_tr_b16 v[76:77], v227 offset:32256
	v_mfma_f32_32x32x16_bf16 v[82:97], v[98:101], v[154:157], v[82:97]
	v_add_f32_e32 v98, v80, v138
	v_add_f32_e32 v98, v81, v98
	v_add_f32_e32 v98, 0, v98
	v_cvt_pk_bf16_f32 v148, v78, v79
	v_cvt_pk_bf16_f32 v149, v80, v81
	v_lshl_add_u64 v[78:79], v[208:209], 0, s[94:95]
	s_add_i32 s40, s40, 0xa000
	s_mov_b32 s41, m0
	s_mov_b32 m0, s40
	s_nop 0
	global_load_lds_dwordx4 v[78:79], off
	s_mov_b32 m0, s41
	v_add_f32_e32 v214, v229, v98
	s_waitcnt lgkmcnt(14)
	v_mfma_f32_32x32x16_bf16 v[18:33], v[166:169], v[102:105], v[18:33]
	v_exp_f32_e32 v114, v114
	v_exp_f32_e32 v115, v115
	v_exp_f32_e32 v116, v116
	v_exp_f32_e32 v117, v117
	s_waitcnt lgkmcnt(12)
	v_mfma_f32_32x32x16_bf16 v[34:49], v[166:169], v[130:133], v[34:49]
	v_exp_f32_e32 v118, v118
	v_exp_f32_e32 v119, v119
	v_exp_f32_e32 v120, v120
	v_exp_f32_e32 v121, v121
	ds_read_b128 v[78:81], v228 offset:16384
	ds_read_b128 v[138:141], v228 offset:16896
	s_waitcnt lgkmcnt(12)
	v_mfma_f32_32x32x16_bf16 v[18:33], v[158:161], v[106:109], v[18:33]
	v_exp_f32_e32 v122, v122
	v_exp_f32_e32 v123, v123
	v_exp_f32_e32 v124, v124
	v_exp_f32_e32 v125, v125
	ds_read_b128 v[142:145], v228 offset:18432
	ds_read_b128 v[178:181], v228 offset:18944
	s_waitcnt lgkmcnt(12)
	v_mfma_f32_32x32x16_bf16 v[34:49], v[158:161], v[110:113], v[34:49]
	v_exp_f32_e32 v126, v126
	v_exp_f32_e32 v127, v127
	v_exp_f32_e32 v128, v128
	v_exp_f32_e32 v129, v129
	ds_read_b128 v[182:185], v228 offset:20480
	ds_read_b128 v[186:189], v228 offset:20992
	s_waitcnt lgkmcnt(12)
	v_mfma_f32_32x32x16_bf16 v[18:33], v[150:153], v[134:137], v[18:33]
	v_exp_f32_e32 v82, v82
	v_exp_f32_e32 v83, v83
	v_exp_f32_e32 v84, v84
	v_exp_f32_e32 v85, v85
	ds_read_b128 v[134:137], v228 offset:22528
	ds_read_b128 v[130:133], v228 offset:23040
	s_waitcnt lgkmcnt(12)
	v_mfma_f32_32x32x16_bf16 v[34:49], v[150:153], v[66:69], v[34:49]
	v_exp_f32_e32 v86, v86
	v_exp_f32_e32 v87, v87
	v_exp_f32_e32 v88, v88
	v_exp_f32_e32 v89, v89
	s_waitcnt lgkmcnt(10)
	v_mfma_f32_32x32x16_bf16 v[18:33], v[146:149], v[70:73], v[18:33]
	v_exp_f32_e32 v90, v90
	v_exp_f32_e32 v91, v91
	v_exp_f32_e32 v92, v92
	v_exp_f32_e32 v93, v93
	s_waitcnt lgkmcnt(8)
	v_mfma_f32_32x32x16_bf16 v[34:49], v[146:149], v[74:77], v[34:49]
	v_exp_f32_e32 v94, v94
	v_exp_f32_e32 v95, v95
	v_exp_f32_e32 v96, v96
	v_exp_f32_e32 v97, v97
	s_waitcnt vmcnt(1) lgkmcnt(0)
	s_barrier
;   #define RESC() do{ if(!FIXREF&&resc){ asm volatile("s_waitcnt lgkmcnt(0)":::"memory"); \
;       _Pragma("unroll") for(int d_=0;d_<2;++d_) _Pragma("unroll") for(int r=0;r<16;++r)o[d_][r]*=wsf[crow(r,hi)]; } }while(0)
;   #define ROT() do{sl_prev=sl_cur;sl_cur=sl_next;sl_next=(sl_next==(NSLOT-1)*SLOTB)?0:sl_next+SLOTB;}while(0)
;   #define ENDW(tt) do{ if((tt)+3<NT){WAIT_BAR(2);} else if((tt)+2<NT){WAIT_BAR(1);} else {WAIT_BAR(0);} }while(0)
; template<int THRL,bool FIXREF,bool HALFK> __device__ __forceinline__ void attn_unit(float mref,long rowbase,int q0,const bf16*Qh,int PQ,const bf16*__restrict__ Kh_,int PK,const bf16*__restrict__ Vh_,int PV,bf16*Oh,int PO,const bf16*Gh,int PG,u32x4(&okeep)[4],int omode,float lam,float oml,const float ...
;     ...
;   for(;t+1<NT;t+=2){
;     STEP(pB0,pB1,pA0,pA1,t,(t+3<NT),(t+1<NT),(t+1<NT));       ENDW(t);   RESC(); ROT();
;     STEP(pA0,pA1,pB0,pB1,t+1,(t+4<NT),(t+2<NT),(t+2<NT));     ENDW(t+1); RESC(); ROT();
	ds_read_b64_tr_b16 v[210:211], v227 offset:32768
	ds_read_b64_tr_b16 v[212:213], v227 offset:33280
	v_add_f32_e32 v66, v114, v115
	v_add_f32_e32 v66, v116, v66
	v_add_f32_e32 v66, v117, v66
	v_add_f32_e32 v66, v118, v66
	v_add_f32_e32 v66, v119, v66
	v_cvt_pk_bf16_f32 v166, v114, v115
	v_cvt_pk_bf16_f32 v167, v116, v117
	s_waitcnt lgkmcnt(9)
	v_mfma_f32_32x32x16_bf16 v[98:113], v[78:81], v[174:177], v[50:65]
	ds_read_b64_tr_b16 v[114:115], v227 offset:36864
	ds_read_b64_tr_b16 v[116:117], v227 offset:37376
	v_add_f32_e32 v66, v120, v66
	v_add_f32_e32 v66, v121, v66
	v_add_f32_e32 v66, v122, v66
	v_add_f32_e32 v146, v123, v66
	s_waitcnt lgkmcnt(10)
	v_mfma_f32_32x32x16_bf16 v[66:81], v[138:141], v[174:177], v[50:65]
	v_cvt_pk_bf16_f32 v168, v118, v119
	v_cvt_pk_bf16_f32 v169, v120, v121
	ds_read_b64_tr_b16 v[138:139], v227 offset:33792
	ds_read_b64_tr_b16 v[140:141], v227 offset:34304
	v_add_f32_e32 v118, v124, v146
	v_add_f32_e32 v118, v125, v118
	v_add_f32_e32 v118, v126, v118
	v_add_f32_e32 v118, v127, v118
	v_cvt_pk_bf16_f32 v158, v122, v123
	v_cvt_pk_bf16_f32 v159, v124, v125
	s_waitcnt lgkmcnt(11)
	v_mfma_f32_32x32x16_bf16 v[98:113], v[142:145], v[170:173], v[98:113]
	ds_read_b64_tr_b16 v[120:121], v227 offset:37888
	ds_read_b64_tr_b16 v[122:123], v227 offset:38400
	s_waitcnt lgkmcnt(12)
	v_mfma_f32_32x32x16_bf16 v[66:81], v[178:181], v[170:173], v[66:81]
	v_add_f32_e32 v118, v128, v118
	v_add_f32_e32 v118, v129, v118
	v_add_f32_e32 v118, v82, v118
	v_add_f32_e32 v118, v83, v118
	v_cvt_pk_bf16_f32 v160, v126, v127
	v_cvt_pk_bf16_f32 v161, v128, v129
	ds_read_b64_tr_b16 v[124:125], v227 offset:34816
	ds_read_b64_tr_b16 v[126:127], v227 offset:35328
	v_add_f32_e32 v118, v84, v118
	v_add_f32_e32 v118, v85, v118
	v_add_f32_e32 v118, v86, v118
	v_add_f32_e32 v118, v87, v118
	v_cvt_pk_bf16_f32 v150, v82, v83
	v_cvt_pk_bf16_f32 v151, v84, v85
	s_waitcnt lgkmcnt(13)
	v_mfma_f32_32x32x16_bf16 v[98:113], v[182:185], v[162:165], v[98:113]
	ds_read_b64_tr_b16 v[82:83], v227 offset:38912
	ds_read_b64_tr_b16 v[84:85], v227 offset:39424
	s_waitcnt lgkmcnt(14)
	v_mfma_f32_32x32x16_bf16 v[66:81], v[186:189], v[162:165], v[66:81]
	v_add_f32_e32 v118, v88, v118
	v_add_f32_e32 v118, v89, v118
	v_add_f32_e32 v118, v90, v118
	v_add_f32_e32 v118, v91, v118
	v_cvt_pk_bf16_f32 v152, v86, v87
	v_cvt_pk_bf16_f32 v153, v88, v89
	ds_read_b64_tr_b16 v[86:87], v227 offset:35840
	ds_read_b64_tr_b16 v[88:89], v227 offset:36352
	v_add_f32_e32 v118, v92, v118
	v_add_f32_e32 v118, v93, v118
	v_add_f32_e32 v118, v94, v118
	v_add_f32_e32 v118, v95, v118
	v_cvt_pk_bf16_f32 v146, v90, v91
	v_cvt_pk_bf16_f32 v147, v92, v93
	s_waitcnt lgkmcnt(14)
	v_mfma_f32_32x32x16_bf16 v[98:113], v[134:137], v[154:157], v[98:113]
	ds_read_b64_tr_b16 v[90:91], v227 offset:39936
	ds_read_b64_tr_b16 v[92:93], v227 offset:40448
	v_mfma_f32_32x32x16_bf16 v[66:81], v[130:133], v[154:157], v[66:81]
	v_add_f32_e32 v118, v96, v118
	v_add_f32_e32 v118, v97, v118
	v_add_f32_e32 v118, 0, v118
	v_cvt_pk_bf16_f32 v148, v94, v95
	v_cvt_pk_bf16_f32 v149, v96, v97
	v_lshl_add_u64 v[94:95], v[208:209], 0, s[26:27]
	s_mov_b32 s40, m0
	s_mov_b32 m0, s61
	s_nop 0
	global_load_lds_dwordx4 v[94:95], off
	s_mov_b32 m0, s40
	v_add_f32_e32 v118, v214, v118
	s_waitcnt lgkmcnt(14)
	v_mfma_f32_32x32x16_bf16 v[18:33], v[166:169], v[210:213], v[18:33]
	v_exp_f32_e32 v98, v98
	v_exp_f32_e32 v99, v99
	v_exp_f32_e32 v100, v100
	v_exp_f32_e32 v101, v101
	s_waitcnt lgkmcnt(12)
	v_mfma_f32_32x32x16_bf16 v[34:49], v[166:169], v[114:117], v[34:49]
	v_exp_f32_e32 v102, v102
	v_exp_f32_e32 v103, v103
	v_exp_f32_e32 v104, v104
	v_exp_f32_e32 v105, v105
	ds_read_b128 v[128:131], v228
	ds_read_b128 v[132:135], v228 offset:512
	s_waitcnt lgkmcnt(12)
	v_mfma_f32_32x32x16_bf16 v[18:33], v[158:161], v[138:141], v[18:33]
	v_exp_f32_e32 v106, v106
	v_exp_f32_e32 v107, v107
	v_exp_f32_e32 v108, v108
	v_exp_f32_e32 v109, v109
	ds_read_b128 v[136:139], v228 offset:2048
	ds_read_b128 v[140:143], v228 offset:2560
	s_waitcnt lgkmcnt(12)
	v_mfma_f32_32x32x16_bf16 v[34:49], v[158:161], v[120:123], v[34:49]
	v_exp_f32_e32 v110, v110
	v_exp_f32_e32 v111, v111
	v_exp_f32_e32 v112, v112
	v_exp_f32_e32 v113, v113
	ds_read_b128 v[120:123], v228 offset:4096
	ds_read_b128 v[178:181], v228 offset:4608
	s_waitcnt lgkmcnt(12)
	v_mfma_f32_32x32x16_bf16 v[18:33], v[150:153], v[124:127], v[18:33]
	v_exp_f32_e32 v66, v66
	v_exp_f32_e32 v67, v67
	v_exp_f32_e32 v68, v68
	v_exp_f32_e32 v69, v69
	ds_read_b128 v[124:127], v228 offset:6144
	ds_read_b128 v[114:117], v228 offset:6656
	s_waitcnt lgkmcnt(12)
	v_mfma_f32_32x32x16_bf16 v[34:49], v[150:153], v[82:85], v[34:49]
	v_exp_f32_e32 v70, v70
	v_exp_f32_e32 v71, v71
	v_exp_f32_e32 v72, v72
	v_exp_f32_e32 v73, v73
	s_waitcnt lgkmcnt(10)
	v_mfma_f32_32x32x16_bf16 v[18:33], v[146:149], v[86:89], v[18:33]
	v_exp_f32_e32 v74, v74
	v_exp_f32_e32 v75, v75
	v_exp_f32_e32 v76, v76
	v_exp_f32_e32 v77, v77
	s_waitcnt lgkmcnt(8)
	v_mfma_f32_32x32x16_bf16 v[34:49], v[146:149], v[90:93], v[34:49]
	v_exp_f32_e32 v78, v78
	v_exp_f32_e32 v79, v79
	v_exp_f32_e32 v80, v80
	v_exp_f32_e32 v81, v81
	s_waitcnt vmcnt(0) lgkmcnt(0)
	s_barrier
;   #define RESC() do{ if(!FIXREF&&resc){ asm volatile("s_waitcnt lgkmcnt(0)":::"memory"); \
;       _Pragma("unroll") for(int d_=0;d_<2;++d_) _Pragma("unroll") for(int r=0;r<16;++r)o[d_][r]*=wsf[crow(r,hi)]; } }while(0)
; template<int THRL,bool FIXREF,bool HALFK> __device__ __forceinline__ void attn_unit(float mref,long rowbase,int q0,const bf16*Qh,int PQ,const bf16*__restrict__ Kh_,int PK,const bf16*__restrict__ Vh_,int PV,bf16*Oh,int PO,const bf16*Gh,int PG,u32x4(&okeep)[4],int omode,float lam,float oml,const float ...
;     ...
;   STEP(pB0,pB1,pA0,pA1,NT-1,false,false,false); RESC();
	ds_read_b64_tr_b16 v[182:183], v227 offset:40960
	ds_read_b64_tr_b16 v[184:185], v227 offset:41472
	v_add_f32_e32 v82, v98, v99
	v_add_f32_e32 v82, v100, v82
	v_add_f32_e32 v82, v101, v82
	v_add_f32_e32 v82, v102, v82
	v_add_f32_e32 v119, v103, v82
	v_cvt_pk_bf16_f32 v166, v98, v99
	v_cvt_pk_bf16_f32 v167, v100, v101
	s_waitcnt lgkmcnt(9)
	v_mfma_f32_32x32x16_bf16 v[82:97], v[128:131], v[174:177], v[50:65]
	ds_read_b64_tr_b16 v[98:99], v227 offset:45056
	ds_read_b64_tr_b16 v[100:101], v227 offset:45568
	v_add_f32_e32 v119, v104, v119
	v_add_f32_e32 v119, v105, v119
	v_add_f32_e32 v119, v106, v119
	v_add_f32_e32 v119, v107, v119
	v_cvt_pk_bf16_f32 v168, v102, v103
	v_cvt_pk_bf16_f32 v169, v104, v105
	s_waitcnt lgkmcnt(10)
	v_mfma_f32_32x32x16_bf16 v[50:65], v[132:135], v[174:177], v[50:65]
	ds_read_b64_tr_b16 v[102:103], v227 offset:41984
	ds_read_b64_tr_b16 v[104:105], v227 offset:42496
	v_add_f32_e32 v119, v108, v119
	v_add_f32_e32 v119, v109, v119
	v_add_f32_e32 v119, v110, v119
	v_add_f32_e32 v119, v111, v119
	v_cvt_pk_bf16_f32 v158, v106, v107
	v_cvt_pk_bf16_f32 v159, v108, v109
	s_waitcnt lgkmcnt(11)
	v_mfma_f32_32x32x16_bf16 v[82:97], v[136:139], v[170:173], v[82:97]
	ds_read_b64_tr_b16 v[106:107], v227 offset:46080
	ds_read_b64_tr_b16 v[108:109], v227 offset:46592
	v_add_f32_e32 v119, v112, v119
	v_add_f32_e32 v119, v113, v119
	v_add_f32_e32 v119, v66, v119
	v_add_f32_e32 v119, v67, v119
	v_cvt_pk_bf16_f32 v160, v110, v111
	v_cvt_pk_bf16_f32 v161, v112, v113
	s_waitcnt lgkmcnt(12)
	v_mfma_f32_32x32x16_bf16 v[50:65], v[140:143], v[170:173], v[50:65]
	ds_read_b64_tr_b16 v[110:111], v227 offset:43008
	ds_read_b64_tr_b16 v[112:113], v227 offset:43520
	v_add_f32_e32 v119, v68, v119
	v_add_f32_e32 v119, v69, v119
	v_add_f32_e32 v119, v70, v119
	v_add_f32_e32 v119, v71, v119
	v_cvt_pk_bf16_f32 v150, v66, v67
	v_cvt_pk_bf16_f32 v151, v68, v69
	s_waitcnt lgkmcnt(13)
	v_mfma_f32_32x32x16_bf16 v[82:97], v[120:123], v[162:165], v[82:97]
	ds_read_b64_tr_b16 v[66:67], v227 offset:47104
	ds_read_b64_tr_b16 v[68:69], v227 offset:47616
	v_add_f32_e32 v119, v72, v119
	v_add_f32_e32 v119, v73, v119
	v_add_f32_e32 v119, v74, v119
	v_add_f32_e32 v119, v75, v119
	v_cvt_pk_bf16_f32 v152, v70, v71
	v_cvt_pk_bf16_f32 v153, v72, v73
	s_waitcnt lgkmcnt(14)
	v_mfma_f32_32x32x16_bf16 v[50:65], v[178:181], v[162:165], v[50:65]
	ds_read_b64_tr_b16 v[70:71], v227 offset:44032
	ds_read_b64_tr_b16 v[72:73], v227 offset:44544
	v_add_f32_e32 v119, v76, v119
	v_add_f32_e32 v119, v77, v119
	v_add_f32_e32 v119, v78, v119
	v_add_f32_e32 v119, v79, v119
	v_cvt_pk_bf16_f32 v146, v74, v75
	v_cvt_pk_bf16_f32 v147, v76, v77
	s_waitcnt lgkmcnt(14)
	v_mfma_f32_32x32x16_bf16 v[82:97], v[124:127], v[154:157], v[82:97]
	ds_read_b64_tr_b16 v[74:75], v227 offset:48128
	ds_read_b64_tr_b16 v[76:77], v227 offset:48640
	v_mfma_f32_32x32x16_bf16 v[50:65], v[114:117], v[154:157], v[50:65]
	v_add_f32_e32 v114, v80, v119
	v_add_f32_e32 v114, v81, v114
	v_add_f32_e32 v114, 0, v114
	v_cvt_pk_bf16_f32 v148, v78, v79
	v_cvt_pk_bf16_f32 v149, v80, v81
	s_waitcnt lgkmcnt(14)
	v_mfma_f32_32x32x16_bf16 v[18:33], v[166:169], v[182:185], v[18:33]
	s_nop 1
	v_exp_f32_e32 v82, v82
	v_exp_f32_e32 v83, v83
	v_exp_f32_e32 v84, v84
	v_exp_f32_e32 v85, v85
	s_waitcnt lgkmcnt(12)
	v_mfma_f32_32x32x16_bf16 v[34:49], v[166:169], v[98:101], v[34:49]
	v_exp_f32_e32 v86, v86
	v_exp_f32_e32 v87, v87
	v_exp_f32_e32 v88, v88
	v_exp_f32_e32 v89, v89
	s_waitcnt lgkmcnt(10)
	v_mfma_f32_32x32x16_bf16 v[18:33], v[158:161], v[102:105], v[18:33]
	v_exp_f32_e32 v90, v90
	v_exp_f32_e32 v91, v91
	v_exp_f32_e32 v92, v92
	v_exp_f32_e32 v93, v93
	s_waitcnt lgkmcnt(8)
	v_mfma_f32_32x32x16_bf16 v[34:49], v[158:161], v[106:109], v[34:49]
	v_exp_f32_e32 v94, v94
	v_exp_f32_e32 v95, v95
	v_exp_f32_e32 v96, v96
	v_exp_f32_e32 v97, v97
	s_waitcnt lgkmcnt(6)
; #define SBAR() __builtin_amdgcn_sched_barrier(0)
;   #define RESC() do{ if(!FIXREF&&resc){ asm volatile("s_waitcnt lgkmcnt(0)":::"memory"); \
;       _Pragma("unroll") for(int d_=0;d_<2;++d_) _Pragma("unroll") for(int r=0;r<16;++r)o[d_][r]*=wsf[crow(r,hi)]; } }while(0)
;   #define PKW(P,B) cvtpk_s(P[B],P[B+1])
; __device__ __forceinline__ void pv(f32x16*o,int vb,bf16x8 pa0,bf16x8 pa1,bf16x8 pa2,bf16x8 pa3){
;   #pragma unroll
;   for(int d0=0;d0<2;++d0){s16x4 lo[4],hi[4];
;     #pragma unroll
;     for(int ks=0;ks<4;++ks){
;       asm volatile("ds_read_b64_tr_b16 %0,%1 offset:%c2":"=&v"(lo[ks]):"v"(vb),"i"(d0*4096+ks*1024):"memory");
;       asm volatile("ds_read_b64_tr_b16 %0,%1 offset:%c2":"=&v"(hi[ks]):"v"(vb),"i"(d0*4096+ks*1024+512):"memory");}
;     asm volatile("s_waitcnt lgkmcnt(0)":::"memory");SBAR();
;     ...
;     o[d0]=__builtin_amdgcn_mfma_f32_32x32x16_bf16(pa0,PK(0),o[d0],0,0,0);
;     o[d0]=__builtin_amdgcn_mfma_f32_32x32x16_bf16(pa1,PK(1),o[d0],0,0,0);
;     o[d0]=__builtin_amdgcn_mfma_f32_32x32x16_bf16(pa2,PK(2),o[d0],0,0,0);
;     o[d0]=__builtin_amdgcn_mfma_f32_32x32x16_bf16(pa3,PK(3),o[d0],0,0,0);
;     ...
;   }
; }
; template<int THRL,bool FIXREF,bool HALFK> __device__ __forceinline__ void attn_unit(float mref,long rowbase,int q0,const bf16*Qh,int PQ,const bf16*__restrict__ Kh_,int PK,const bf16*__restrict__ Vh_,int PV,bf16*Oh,int PO,const bf16*Gh,int PG,u32x4(&okeep)[4],int omode,float lam,float oml,const float ...
;     ...
;   STEP(pB0,pB1,pA0,pA1,NT-1,false,false,false); RESC();
;   { float sacc=pB0[0]+pB0[1]; _Pragma("unroll") for(int r=2;r<16;++r)sacc+=pB0[r]; _Pragma("unroll") for(int r=0;r<16;++r)sacc+=pB1[r]; l_reg+=sacc;
;     pw0=(u32x4){PKW(pB0,0),PKW(pB0,2),PKW(pB0,4),PKW(pB0,6)};pw1=(u32x4){PKW(pB0,8),PKW(pB0,10),PKW(pB0,12),PKW(pB0,14)};pw2=(u32x4){PKW(pB1,0),PKW(pB1,2),PKW(pB1,4),PKW(pB1,6)};pw3=(u32x4){PKW(pB1,8),PKW(pB1,10),PKW(pB1,12),PKW(pB1,14)};
;     SBAR(); pv(o,vb0+sl_cur,PAF(0),PAF(1),PAF(2),PAF(3)); }
;     ...
;   {auto rr=__builtin_amdgcn_permlane32_swap(__float_as_uint(l_reg),__float_as_uint(l_reg),false,false);l_reg=__uint_as_float(rr[0])+__uint_as_float(rr[1]);}
;   if(hi==0)wsf[32+r32]=l_reg;asm volatile("s_waitcnt lgkmcnt(0)":::"memory");
	v_mfma_f32_32x32x16_bf16 v[18:33], v[150:153], v[110:113], v[18:33]
	v_exp_f32_e32 v50, v50
	v_exp_f32_e32 v51, v51
	v_exp_f32_e32 v52, v52
	v_exp_f32_e32 v53, v53
	s_waitcnt lgkmcnt(4)
	v_mfma_f32_32x32x16_bf16 v[34:49], v[150:153], v[66:69], v[34:49]
	v_exp_f32_e32 v54, v54
	v_exp_f32_e32 v55, v55
	v_exp_f32_e32 v56, v56
	v_exp_f32_e32 v57, v57
	s_waitcnt lgkmcnt(2)
	v_mfma_f32_32x32x16_bf16 v[18:33], v[146:149], v[70:73], v[18:33]
	v_exp_f32_e32 v58, v58
	v_exp_f32_e32 v59, v59
	v_exp_f32_e32 v60, v60
	v_exp_f32_e32 v61, v61
	s_waitcnt lgkmcnt(0)
	v_mfma_f32_32x32x16_bf16 v[34:49], v[146:149], v[74:77], v[34:49]
	v_exp_f32_e32 v62, v62
	v_exp_f32_e32 v63, v63
	v_exp_f32_e32 v64, v64
	v_exp_f32_e32 v65, v65
	v_add_f32_e32 v66, v82, v83
	v_add_f32_e32 v66, v84, v66
	v_add_f32_e32 v66, v85, v66
	v_add_f32_e32 v66, v86, v66
	v_add_f32_e32 v66, v87, v66
	v_add_f32_e32 v66, v88, v66
	v_add_f32_e32 v66, v89, v66
	v_add_f32_e32 v66, v90, v66
	v_add_f32_e32 v66, v91, v66
	v_add_f32_e32 v66, v92, v66
	v_add_f32_e32 v66, v93, v66
	v_add_f32_e32 v66, v94, v66
	v_add_f32_e32 v66, v95, v66
	v_add_f32_e32 v66, v96, v66
	v_add_f32_e32 v66, v97, v66
	v_add_f32_e32 v66, v50, v66
	v_add_f32_e32 v66, v51, v66
	v_add_f32_e32 v66, v52, v66
	v_add_f32_e32 v66, v53, v66
	v_add_f32_e32 v66, v54, v66
	v_add_f32_e32 v66, v55, v66
	v_add_f32_e32 v66, v56, v66
	v_add_f32_e32 v66, v57, v66
	v_add_f32_e32 v66, v58, v66
	v_add_f32_e32 v66, v59, v66
	v_add_f32_e32 v66, v60, v66
	v_add_f32_e32 v66, v61, v66
	v_add_f32_e32 v66, v62, v66
	v_add_f32_e32 v66, v63, v66
	v_add_f32_e32 v66, v64, v66
	v_add_f32_e32 v66, v65, v66
	v_add_f32_e32 v67, v118, v114
	v_add_f32_e32 v66, v67, v66
	v_cvt_pk_bf16_f32 v68, v82, v83
	v_cvt_pk_bf16_f32 v69, v84, v85
	v_cvt_pk_bf16_f32 v70, v86, v87
	v_cvt_pk_bf16_f32 v71, v88, v89
	v_cvt_pk_bf16_f32 v72, v90, v91
	v_cvt_pk_bf16_f32 v73, v92, v93
	v_cvt_pk_bf16_f32 v74, v94, v95
	v_cvt_pk_bf16_f32 v75, v96, v97
	v_cvt_pk_bf16_f32 v50, v50, v51
	v_cvt_pk_bf16_f32 v51, v52, v53
	v_cvt_pk_bf16_f32 v52, v54, v55
	v_cvt_pk_bf16_f32 v53, v56, v57
	v_cvt_pk_bf16_f32 v54, v58, v59
	v_cvt_pk_bf16_f32 v55, v60, v61
	v_cvt_pk_bf16_f32 v56, v62, v63
	v_cvt_pk_bf16_f32 v57, v64, v65
	ds_read_b64_tr_b16 v[58:59],v0 offset:0
	ds_read_b64_tr_b16 v[60:61],v0 offset:512
	ds_read_b64_tr_b16 v[62:63],v0 offset:1024
	ds_read_b64_tr_b16 v[64:65],v0 offset:1536
	ds_read_b64_tr_b16 v[76:77],v0 offset:2048
	ds_read_b64_tr_b16 v[78:79],v0 offset:2560
	ds_read_b64_tr_b16 v[80:81],v0 offset:3072
	ds_read_b64_tr_b16 v[82:83],v0 offset:3584
	s_waitcnt lgkmcnt(0)
	s_nop 0
	v_mfma_f32_32x32x16_bf16 v[18:33], v[68:71], v[58:61], v[18:33]
	ds_read_b64_tr_b16 v[58:59],v0 offset:4096
	ds_read_b64_tr_b16 v[60:61],v0 offset:4608
	v_mfma_f32_32x32x16_bf16 v[18:33], v[72:75], v[62:65], v[18:33]
	ds_read_b64_tr_b16 v[62:63],v0 offset:5120
	ds_read_b64_tr_b16 v[64:65],v0 offset:5632
	v_mfma_f32_32x32x16_bf16 v[18:33], v[50:53], v[76:79], v[18:33]
	ds_read_b64_tr_b16 v[76:77],v0 offset:6144
	ds_read_b64_tr_b16 v[78:79],v0 offset:6656
	v_mfma_f32_32x32x16_bf16 v[18:33], v[54:57], v[80:83], v[18:33]
	ds_read_b64_tr_b16 v[80:81],v0 offset:7168
	ds_read_b64_tr_b16 v[82:83],v0 offset:7680
	s_waitcnt lgkmcnt(0)
	v_mfma_f32_32x32x16_bf16 v[34:49], v[68:71], v[58:61], v[34:49]
	v_mov_b32_e32 v0, v66
	s_nop 1
	v_permlane32_swap_b32_e32 v66, v0
	v_cmp_gt_u32_e32 vcc, 32, v205
	v_mfma_f32_32x32x16_bf16 v[34:49], v[72:75], v[62:65], v[34:49]
	v_mfma_f32_32x32x16_bf16 v[34:49], v[50:53], v[76:79], v[34:49]
	v_mfma_f32_32x32x16_bf16 v[34:49], v[54:57], v[80:83], v[34:49]
	s_and_saveexec_b64 s[40:41], vcc
	s_cbranch_execz .LBB0_449
	v_lshl_add_u32 v50, v216, 2, s42
	v_add_f32_e32 v0, v66, v0
	ds_write_b32 v50, v0 offset:49280
	s_branch .LBB0_449

;   #define CMASK(P0,P1,t) do{}while(0)
;   #define CMASK(P0,P1,t) do{}while(0)
; template<int THRL,bool FIXREF,bool HALFK> __device__ __forceinline__ void attn_unit(float mref,long rowbase,int q0,const bf16*Qh,int PQ,const bf16*__restrict__ Kh_,int PK,const bf16*__restrict__ Vh_,int PV,bf16*Oh,int PO,const bf16*Gh,int PG,u32x4(&okeep)[4],int omode,float lam,float oml,const float ...
;   const int tid=fresh_tid(),lane=tid&63,r32=lane&31,hi=lane>>5; const int wid=__builtin_amdgcn_readfirstlane(tid>>6);
;   const bf16*Qw=Qh+(rowbase+q0+wid*QBLK)*PQ;
;   const bf16*Kh=Kh_+rowbase*PK,*Vh=Vh_+rowbase*PV;
;   const unsigned lds0=(unsigned)(uintptr_t)shm;
;   float*wsf=(float*)(shm+LDS_WS)+wid*64;
;   const bf16*ksrc=Kh+(long)lane*PK+wid*8;
;   const bf16*vsrc=Vh+(long)(16*(wid&3)+(lane>>2))*PV+(wid>>2)*32+(lane&3)*8;
;   const unsigned kdst=lds0+LDS_K+wid*1024, vdst=lds0+LDS_V+wid*1024;
;     ...
;   const int vb0=(int)(lds0+LDS_V)+((lane>>4)&1)*32+(lane&3)*8+(4*hi+((lane&15)>>2))*64;
;   const char*Kbase=shm+LDS_K; bf16x8 kf[8];
;   const lds_cptr shm3=(lds_cptr)shm; const lds_cptr kp0=shm3+LDS_K+hi*1024+r32*16; const lds_cptr vp0=shm3+LDS_V+((lane>>4)&1)*32+(lane&3)*8+(4*hi+((lane&15)>>2))*64;
;   constexpr int NT=SEQ/KVBLK;
;   if(Gh){ const bf16*Gw=Gh+(rowbase+q0+wid*QBLK)*PG;
;     #pragma unroll
;     for(int i=0;i<4;++i) glds16(Gw+(long)(i*8+(lane>>3))*PG+(lane&7)*8,(unsigned)__builtin_amdgcn_readfirstlane(lds0+LDS_GST+wid*4096+i*1024)); }
;   DMA_K(0,0);DMA_V(0,0);DMA_K(1,SLOTB);
;   bf16x8 qr[4];
;   #pragma unroll
;   for(int d0=0;d0<4;++d0)qr[d0]=*reinterpret_cast<const bf16x8*>(&Qw[(long)r32*PQ+d0*16+hi*8]);
;   float mhat=0.f,l_reg=0.f;f32x16 o[2];o[0]=f32x16{};o[1]=f32x16{};f32x16 negm=f32x16{};
;   if constexpr(FIXREF){ mhat=mref; _Pragma("unroll") for(int r=0;r<16;++r)negm[r]=-mref; }
;   asm volatile("":"+v"(negm));
;     ...
;   bool resc=false;
;     ...
;   f32x16 pA0,pA1,pB0,pB1;
;   int sl_prev=0,sl_cur=0,sl_next=SLOTB;
;     ...
;   DMA_K(2,2*SLOTB);
;   WAIT_BAR(3);
;   qkt<HALFK?2:4>(pA0,pA1,Kbase,qr,negm,r32,hi);asm volatile("s_nop 15\n\ts_nop 7":"+v"(pA0),"+v"(pA1));CMASK(pA0,pA1,0);
;   START(pA0,pA1);
;   _Pragma("unroll") for(int r=0;r<16;++r)pA1[r]=__builtin_amdgcn_exp2f(pA1[r]);
;   WAIT_BAR(0);
;   DMA_K(3,0);DMA_V(1,SLOTB);
;   ROT();
;   if constexpr(HALFK){ kload2(kf,kp0+sl_cur,0); kload2(kf,kp0+sl_cur,1); } else kload8(kf,kp0+sl_cur);
;   WAIT_BAR(2);
.LBB0_460:
	s_or_b32 s20, s88, s68
	s_xor_b64 s[42:43], s[42:43], -1
	s_xor_b64 s[40:41], s[48:49], -1
	s_lshl_b64 s[48:49], s[20:21], 1
	s_add_u32 s20, s2, s48
	s_addc_u32 s80, s3, s49
	s_lshl_b64 s[50:51], s[46:47], 9
	s_add_u32 s84, s20, s50
	s_addc_u32 s85, s80, s51
	s_add_u32 s48, s71, s48
	s_addc_u32 s49, s73, s49
	v_lshlrev_b32_e32 v0, 9, v209
	v_lshl_add_u64 v[18:19], s[48:49], 0, v[0:1]
	s_lshl_b32 s48, s79, 3
	s_ashr_i32 s49, s48, 31
	s_lshl_b64 s[48:49], s[48:49], 1
	v_lshl_add_u64 v[174:175], v[18:19], 0, s[48:49]
	s_lshl_b32 s20, s79, 4
	v_lshrrev_b32_e32 v18, 2, v209
	v_and_or_b32 v18, s20, 48, v18
	s_ashr_i32 s20, s83, 3
	s_and_b32 s50, s20, 0xffffffe0
	s_ashr_i32 s51, s50, 31
	v_mul_u32_u24_e32 v18, 0xf00, v18
	s_lshl_b64 s[50:51], s[50:51], 1
	s_lshl_b32 s82, s79, 10
	v_lshlrev_b32_e32 v104, 1, v18
	v_mov_b32_e32 v105, v1
	s_cmp_lg_u32 0, -1
	v_lshl_add_u64 v[18:19], s[16:17], 0, v[104:105]
	v_and_b32_e32 v215, 24, v211
	s_cselect_b32 s20, 0, 0
	v_lshl_add_u64 v[18:19], v[18:19], 0, s[50:51]
	v_lshlrev_b32_e32 v20, 1, v215
	v_mov_b32_e32 v21, v1
	s_add_i32 s81, s82, s20
	s_mov_b32 s20, m0
	s_mov_b32 m0, s81
	s_nop 0
	global_load_lds_dwordx4 v[174:175], off
	s_mov_b32 m0, s20
	v_and_b32_e32 v171, 31, v102
	v_lshl_add_u64 v[172:173], v[18:19], 0, v[20:21]
	s_add_i32 s80, s81, 0x6000
	s_mov_b32 s20, m0
	s_mov_b32 m0, s80
	s_nop 0
	global_load_lds_dwordx4 v[172:173], off
	s_mov_b32 m0, s20
	v_lshl_add_u64 v[18:19], v[174:175], 0, s[10:11]
	v_lshrrev_b32_e32 v212, 5, v209
	s_add_i32 s20, s81, 0x2000
	s_mov_b32 s86, m0
	s_mov_b32 m0, s20
	s_nop 0
	global_load_lds_dwordx4 v[18:19], off
	s_mov_b32 m0, s86
	v_lshlrev_b32_e32 v18, 9, v171
	v_lshl_or_b32 v18, v212, 4, v18
	global_load_dwordx4 v[166:169], v18, s[84:85]
	global_load_dwordx4 v[162:165], v18, s[84:85] offset:32
	v_mov_b64_e32 v[64:65], v[16:17]
	v_mov_b64_e32 v[62:63], v[14:15]
	v_mov_b64_e32 v[60:61], v[12:13]
	v_mov_b64_e32 v[58:59], v[10:11]
	v_mov_b64_e32 v[56:57], v[8:9]
	v_mov_b64_e32 v[54:55], v[6:7]
	v_mov_b64_e32 v[52:53], v[4:5]
	v_mov_b64_e32 v[50:51], v[2:3]
	v_lshlrev_b32_e32 v18, 10, v212
	v_lshlrev_b32_e32 v19, 4, v171
	v_add3_u32 v214, 0, v18, v19
	v_lshl_add_u64 v[18:19], v[174:175], 0, s[92:93]
	s_add_i32 s20, s81, 0x4000
	s_mov_b32 s84, m0
	s_mov_b32 m0, s20
	s_nop 0
	global_load_lds_dwordx4 v[18:19], off
	s_mov_b32 m0, s84
	s_waitcnt vmcnt(3) lgkmcnt(0)
	s_barrier
	ds_read_b128 v[18:21], v214
	ds_read_b128 v[66:69], v214 offset:512
	ds_read_b128 v[70:73], v214 offset:2560
	ds_read_b128 v[74:77], v214 offset:2048
	v_lshl_add_u64 v[98:99], v[174:175], 0, s[36:37]
	v_lshl_add_u64 v[100:101], v[172:173], 0, s[22:23]
	s_add_i32 s20, s81, 0x8000
	v_mov_b32_e32 v227, 0
	s_mov_b32 s84, -1
	s_mov_b32 s87, 0
	s_movk_i32 s86, 0x2000
	s_movk_i32 s85, 0x4000
	s_waitcnt vmcnt(1) lgkmcnt(3)
	v_mfma_f32_32x32x16_bf16 v[34:49], v[18:21], v[166:169], v[50:65]
	s_waitcnt lgkmcnt(2)
	v_mfma_f32_32x32x16_bf16 v[18:33], v[66:69], v[166:169], v[50:65]
	v_lshlrev_b32_e32 v66, 1, v102
	v_lshlrev_b32_e32 v67, 4, v102
	v_and_b32_e32 v216, 32, v66
	v_and_b32_e32 v66, 0xc0, v67
	v_lshl_or_b32 v217, v212, 8, v66
	v_add_u32_e32 v66, 0, v216
	v_add3_u32 v213, v66, v215, v217
	s_waitcnt vmcnt(0) lgkmcnt(0)
	v_mfma_f32_32x32x16_bf16 v[34:49], v[74:77], v[162:165], v[34:49]
	v_mfma_f32_32x32x16_bf16 v[18:33], v[70:73], v[162:165], v[18:33]
	s_nop 15
	s_nop 7
	s_waitcnt vmcnt(0) lgkmcnt(0)
	s_barrier
	s_mov_b32 s89, m0
	s_mov_b32 m0, s81
	s_nop 0
	global_load_lds_dwordx4 v[98:99], off
	s_mov_b32 m0, s89
	s_nop 0
	s_mov_b32 s89, m0
	s_mov_b32 m0, s20
	s_nop 0
	global_load_lds_dwordx4 v[100:101], off
	s_mov_b32 m0, s89
	s_nop 10
	v_exp_f32_e32 v66, v18
	ds_read_b128 v[98:101], v214 offset:8192
	ds_read_b128 v[134:137], v214 offset:8704
	ds_read_b128 v[138:141], v214 offset:10240
	ds_read_b128 v[130:133], v214 offset:10752
	v_and_b32_e32 v18, 3, v102
	s_add_i32 s20, s67, s88
	v_exp_f32_e32 v67, v19
	v_lshl_or_b32 v18, v18, 4, s50
	v_subrev_u32_e32 v18, s50, v18
	s_add_u32 s38, s34, s50
	s_addc_u32 s39, s35, s51
	s_lshl_b64 s[50:51], s[20:21], 1
	s_add_u32 s20, s77, s50
	v_exp_f32_e32 v82, v34
	v_exp_f32_e32 v83, v35
	v_exp_f32_e32 v84, v36
	v_exp_f32_e32 v85, v37
	v_exp_f32_e32 v86, v38
	v_exp_f32_e32 v87, v39
	v_exp_f32_e32 v88, v40
	v_exp_f32_e32 v89, v41
	v_exp_f32_e32 v90, v42
	v_exp_f32_e32 v91, v43
	v_exp_f32_e32 v92, v44
	v_exp_f32_e32 v93, v45
	v_exp_f32_e32 v94, v46
	v_exp_f32_e32 v95, v47
	v_exp_f32_e32 v96, v48
	v_exp_f32_e32 v97, v49
	v_exp_f32_e32 v68, v20
	v_exp_f32_e32 v69, v21
	v_exp_f32_e32 v70, v22
	v_exp_f32_e32 v71, v23
	v_exp_f32_e32 v72, v24
	v_exp_f32_e32 v73, v25
	v_exp_f32_e32 v74, v26
	v_exp_f32_e32 v75, v27
	v_exp_f32_e32 v76, v28
	v_exp_f32_e32 v77, v29
	v_exp_f32_e32 v78, v30
	v_exp_f32_e32 v79, v31
	v_exp_f32_e32 v80, v32
	v_exp_f32_e32 v81, v33
	s_addc_u32 s50, s78, s51
	s_waitcnt vmcnt(2) lgkmcnt(0)
	s_barrier
	s_add_u32 s48, s20, s48
	v_add_u32_e32 v142, v18, v104
	s_addc_u32 s49, s50, s49
	v_mov_b32_e32 v144, v0
	s_mov_b32 s12, s48
	s_mov_b32 s13, s49
	v_mov_b32_e32 v18, 0
	v_mov_b32_e32 v19, v227
	v_mov_b32_e32 v20, v227
	v_mov_b32_e32 v21, v227
	v_mov_b32_e32 v22, v227
	v_mov_b32_e32 v23, v227
	v_mov_b32_e32 v24, v227
	v_mov_b32_e32 v25, v227
	v_mov_b32_e32 v26, v227
	v_mov_b32_e32 v27, v227
	v_mov_b32_e32 v28, v227
	v_mov_b32_e32 v29, v227
	v_mov_b32_e32 v30, v227
	v_mov_b32_e32 v31, v227
	v_mov_b32_e32 v32, v227
	v_mov_b32_e32 v33, v227
	v_mov_b32_e32 v34, 0
	v_mov_b32_e32 v35, v227
	v_mov_b32_e32 v36, v227
	v_mov_b32_e32 v37, v227
	v_mov_b32_e32 v38, v227
	v_mov_b32_e32 v39, v227
	v_mov_b32_e32 v40, v227
	v_mov_b32_e32 v41, v227
	v_mov_b32_e32 v42, v227
	v_mov_b32_e32 v43, v227
	v_mov_b32_e32 v44, v227
	v_mov_b32_e32 v45, v227
	v_mov_b32_e32 v46, v227
	v_mov_b32_e32 v47, v227
	v_mov_b32_e32 v48, v227
	v_mov_b32_e32 v49, v227
	v_add_u32_e32 v0, s87, v213
; #define WAIT_BAR(N) asm volatile("s_waitcnt vmcnt(" #N ") lgkmcnt(0)\n\ts_barrier":::"memory")
;   #define RESC() do{ if(!FIXREF&&resc){ asm volatile("s_waitcnt lgkmcnt(0)":::"memory"); \
;       _Pragma("unroll") for(int d_=0;d_<2;++d_) _Pragma("unroll") for(int r=0;r<16;++r)o[d_][r]*=wsf[crow(r,hi)]; } }while(0)
;   #define ROT() do{sl_prev=sl_cur;sl_cur=sl_next;sl_next=(sl_next==(NSLOT-1)*SLOTB)?0:sl_next+SLOTB;}while(0)
; template<int THRL,bool FIXREF,bool HALFK> __device__ __forceinline__ void attn_unit(float mref,long rowbase,int q0,const bf16*Qh,int PQ,const bf16*__restrict__ Kh_,int PK,const bf16*__restrict__ Vh_,int PV,bf16*Oh,int PO,const bf16*Gh,int PG,u32x4(&okeep)[4],int omode,float lam,float oml,const float ...
;     ...
;   for(;t+5<NT;t+=2){
;     STEP(pB0,pB1,pA0,pA1,t,true,true,true);     WAIT_BAR(2); RESC(); ROT();
;     STEP(pA0,pA1,pB0,pB1,t+1,true,true,true);   WAIT_BAR(2); RESC(); ROT();
.LBB0_461:
	ds_read_b64_tr_b16 v[228:229], v0 offset:24576
	ds_read_b64_tr_b16 v[230:231], v0 offset:25088
	v_add_f32_e32 v102, v82, v83
	v_add_f32_e32 v102, v84, v102
	v_add_f32_e32 v102, v85, v102
	v_add_f32_e32 v102, v86, v102
	v_add_f32_e32 v102, v87, v102
	v_cvt_pk_bf16_f32 v158, v82, v83
	v_cvt_pk_bf16_f32 v159, v84, v85
	s_waitcnt lgkmcnt(5)
	v_mfma_f32_32x32x16_bf16 v[114:129], v[98:101], v[166:169], v[50:65]
	ds_read_b64_tr_b16 v[82:83], v0 offset:28672
	ds_read_b64_tr_b16 v[84:85], v0 offset:29184
	v_add_f32_e32 v98, v88, v102
	v_add_f32_e32 v98, v89, v98
	v_add_f32_e32 v98, v90, v98
	v_add_f32_e32 v146, v91, v98
	s_waitcnt lgkmcnt(6)
	v_mfma_f32_32x32x16_bf16 v[98:113], v[134:137], v[166:169], v[50:65]
	v_cvt_pk_bf16_f32 v160, v86, v87
	v_cvt_pk_bf16_f32 v161, v88, v89
	ds_read_b64_tr_b16 v[86:87], v0 offset:25600
	ds_read_b64_tr_b16 v[88:89], v0 offset:26112
	v_add_f32_e32 v134, v92, v146
	v_add_f32_e32 v134, v93, v134
	v_add_f32_e32 v134, v94, v134
	v_add_f32_e32 v134, v95, v134
	v_cvt_pk_bf16_f32 v154, v90, v91
	v_cvt_pk_bf16_f32 v155, v92, v93
	s_waitcnt lgkmcnt(7)
	v_mfma_f32_32x32x16_bf16 v[114:129], v[138:141], v[162:165], v[114:129]
	ds_read_b64_tr_b16 v[90:91], v0 offset:29696
	ds_read_b64_tr_b16 v[92:93], v0 offset:30208
	s_waitcnt lgkmcnt(8)
	v_mfma_f32_32x32x16_bf16 v[98:113], v[130:133], v[162:165], v[98:113]
	v_add_f32_e32 v130, v96, v134
	v_add_f32_e32 v130, v97, v130
	v_add_f32_e32 v130, v66, v130
	v_add_f32_e32 v130, v67, v130
	v_cvt_pk_bf16_f32 v156, v94, v95
	v_cvt_pk_bf16_f32 v157, v96, v97
	ds_read_b64_tr_b16 v[94:95], v0 offset:26624
	ds_read_b64_tr_b16 v[96:97], v0 offset:27136
	v_add_f32_e32 v130, v68, v130
	v_add_f32_e32 v130, v69, v130
	v_add_f32_e32 v130, v70, v130
	v_add_f32_e32 v130, v71, v130
	v_cvt_pk_bf16_f32 v150, v66, v67
	v_cvt_pk_bf16_f32 v151, v68, v69
	ds_read_b64_tr_b16 v[66:67], v0 offset:30720
	ds_read_b64_tr_b16 v[68:69], v0 offset:31232
	v_add_f32_e32 v130, v72, v130
	v_add_f32_e32 v130, v73, v130
	v_add_f32_e32 v130, v74, v130
	v_add_f32_e32 v130, v75, v130
	v_cvt_pk_bf16_f32 v152, v70, v71
	v_cvt_pk_bf16_f32 v153, v72, v73
	ds_read_b64_tr_b16 v[70:71], v0 offset:27648
	ds_read_b64_tr_b16 v[72:73], v0 offset:28160
	v_add_f32_e32 v130, v76, v130
	v_add_f32_e32 v130, v77, v130
	v_add_f32_e32 v130, v78, v130
	v_add_f32_e32 v130, v79, v130
	v_cvt_pk_bf16_f32 v146, v74, v75
	v_cvt_pk_bf16_f32 v147, v76, v77
	ds_read_b64_tr_b16 v[74:75], v0 offset:31744
	ds_read_b64_tr_b16 v[76:77], v0 offset:32256
	v_add_f32_e32 v0, v80, v130
	v_add_f32_e32 v0, v81, v0
	v_cvt_pk_bf16_f32 v148, v78, v79
	v_cvt_pk_bf16_f32 v149, v80, v81
	s_add_u32 s98, s12, s36
	s_addc_u32 s99, s13, s37
	s_add_i32 s20, s86, s81
	s_mov_b32 s48, m0
	s_mov_b32 m0, s20
	s_nop 0
	global_load_lds_dwordx4 v144, s[98:99]
	s_mov_b32 m0, s48
	s_add_u32 s98, s38, s22
	s_addc_u32 s99, s39, s23
	s_add_i32 s20, s85, s80
	s_mov_b32 s48, m0
	s_mov_b32 m0, s20
	s_nop 0
	global_load_lds_dwordx4 v142, s[98:99]
	s_mov_b32 m0, s48
	v_add_f32_e32 v0, v227, v0
	s_waitcnt lgkmcnt(14)
	v_mfma_f32_32x32x16_bf16 v[18:33], v[158:161], v[228:231], v[18:33]
	v_exp_f32_e32 v114, v114
	v_exp_f32_e32 v115, v115
	v_exp_f32_e32 v116, v116
	v_exp_f32_e32 v117, v117
	s_waitcnt lgkmcnt(12)
	v_mfma_f32_32x32x16_bf16 v[34:49], v[158:161], v[82:85], v[34:49]
	v_exp_f32_e32 v118, v118
	v_exp_f32_e32 v119, v119
	v_exp_f32_e32 v120, v120
	v_exp_f32_e32 v121, v121
	v_add_u32_e32 v82, s85, v214
	ds_read_b128 v[78:81], v82
	ds_read_b128 v[130:133], v82 offset:512
	s_waitcnt lgkmcnt(12)
	v_mfma_f32_32x32x16_bf16 v[18:33], v[154:157], v[86:89], v[18:33]
	v_exp_f32_e32 v122, v122
	v_exp_f32_e32 v123, v123
	v_exp_f32_e32 v124, v124
	v_exp_f32_e32 v125, v125
	ds_read_b128 v[134:137], v82 offset:2048
	ds_read_b128 v[138:141], v82 offset:2560
	s_waitcnt lgkmcnt(12)
	v_mfma_f32_32x32x16_bf16 v[34:49], v[154:157], v[90:93], v[34:49]
	v_exp_f32_e32 v126, v126
	v_exp_f32_e32 v127, v127
	v_exp_f32_e32 v128, v128
	v_exp_f32_e32 v129, v129
	s_waitcnt lgkmcnt(10)
	v_mfma_f32_32x32x16_bf16 v[18:33], v[150:153], v[94:97], v[18:33]
	v_exp_f32_e32 v98, v98
	v_exp_f32_e32 v99, v99
	v_exp_f32_e32 v100, v100
	v_exp_f32_e32 v101, v101
	s_waitcnt lgkmcnt(8)
	v_mfma_f32_32x32x16_bf16 v[34:49], v[150:153], v[66:69], v[34:49]
	v_exp_f32_e32 v102, v102
	v_exp_f32_e32 v103, v103
	v_exp_f32_e32 v104, v104
	v_exp_f32_e32 v105, v105
	s_waitcnt lgkmcnt(6)
	v_mfma_f32_32x32x16_bf16 v[18:33], v[146:149], v[70:73], v[18:33]
	v_exp_f32_e32 v106, v106
	v_exp_f32_e32 v107, v107
	v_exp_f32_e32 v108, v108
	v_exp_f32_e32 v109, v109
	s_waitcnt lgkmcnt(4)
	v_mfma_f32_32x32x16_bf16 v[34:49], v[146:149], v[74:77], v[34:49]
	v_exp_f32_e32 v110, v110
	v_exp_f32_e32 v111, v111
	v_exp_f32_e32 v112, v112
	v_exp_f32_e32 v113, v113
	s_add_i32 s20, s85, 0x2000
	s_cmpk_lg_i32 s85, 0x4000
	s_cselect_b32 s20, s20, 0
	v_add_u32_e32 v227, s86, v213
	s_waitcnt vmcnt(2) lgkmcnt(0)
	s_barrier
; #define WAIT_BAR(N) asm volatile("s_waitcnt vmcnt(" #N ") lgkmcnt(0)\n\ts_barrier":::"memory")
;   #define RESC() do{ if(!FIXREF&&resc){ asm volatile("s_waitcnt lgkmcnt(0)":::"memory"); \
;       _Pragma("unroll") for(int d_=0;d_<2;++d_) _Pragma("unroll") for(int r=0;r<16;++r)o[d_][r]*=wsf[crow(r,hi)]; } }while(0)
;   #define ROT() do{sl_prev=sl_cur;sl_cur=sl_next;sl_next=(sl_next==(NSLOT-1)*SLOTB)?0:sl_next+SLOTB;}while(0)
; template<int THRL,bool FIXREF,bool HALFK> __device__ __forceinline__ void attn_unit(float mref,long rowbase,int q0,const bf16*Qh,int PQ,const bf16*__restrict__ Kh_,int PK,const bf16*__restrict__ Vh_,int PV,bf16*Oh,int PO,const bf16*Gh,int PG,u32x4(&okeep)[4],int omode,float lam,float oml,const float ...
;     ...
;   for(;t+5<NT;t+=2){
;     STEP(pB0,pB1,pA0,pA1,t,true,true,true);     WAIT_BAR(2); RESC(); ROT();
;     STEP(pA0,pA1,pB0,pB1,t+1,true,true,true);   WAIT_BAR(2); RESC(); ROT();
;   }
	ds_read_b64_tr_b16 v[228:229], v227 offset:24576
	ds_read_b64_tr_b16 v[230:231], v227 offset:25088
	s_waitcnt lgkmcnt(5)
	v_mfma_f32_32x32x16_bf16 v[82:97], v[78:81], v[166:169], v[50:65]
	v_add_f32_e32 v66, v114, v115
	v_add_f32_e32 v66, v116, v66
	v_add_f32_e32 v66, v117, v66
	v_add_f32_e32 v66, v118, v66
	v_add_f32_e32 v66, v119, v66
	v_cvt_pk_bf16_f32 v158, v114, v115
	v_cvt_pk_bf16_f32 v159, v116, v117
	ds_read_b64_tr_b16 v[114:115], v227 offset:28672
	ds_read_b64_tr_b16 v[116:117], v227 offset:29184
	v_add_f32_e32 v66, v120, v66
	v_add_f32_e32 v66, v121, v66
	v_add_f32_e32 v66, v122, v66
	v_add_f32_e32 v146, v123, v66
	s_waitcnt lgkmcnt(6)
	v_mfma_f32_32x32x16_bf16 v[66:81], v[130:133], v[166:169], v[50:65]
	v_cvt_pk_bf16_f32 v160, v118, v119
	v_cvt_pk_bf16_f32 v161, v120, v121
	ds_read_b64_tr_b16 v[118:119], v227 offset:25600
	ds_read_b64_tr_b16 v[120:121], v227 offset:26112
	s_waitcnt lgkmcnt(7)
	v_mfma_f32_32x32x16_bf16 v[82:97], v[134:137], v[162:165], v[82:97]
	v_add_f32_e32 v130, v124, v146
	v_add_f32_e32 v130, v125, v130
	v_add_f32_e32 v130, v126, v130
	v_add_f32_e32 v130, v127, v130
	v_cvt_pk_bf16_f32 v154, v122, v123
	v_cvt_pk_bf16_f32 v155, v124, v125
	ds_read_b64_tr_b16 v[122:123], v227 offset:29696
	ds_read_b64_tr_b16 v[124:125], v227 offset:30208
	s_waitcnt lgkmcnt(8)
	v_mfma_f32_32x32x16_bf16 v[66:81], v[138:141], v[162:165], v[66:81]
	v_add_f32_e32 v130, v128, v130
	v_add_f32_e32 v130, v129, v130
	v_add_f32_e32 v130, v98, v130
	v_add_f32_e32 v130, v99, v130
	v_cvt_pk_bf16_f32 v156, v126, v127
	v_cvt_pk_bf16_f32 v157, v128, v129
	ds_read_b64_tr_b16 v[126:127], v227 offset:26624
	ds_read_b64_tr_b16 v[128:129], v227 offset:27136
	v_add_f32_e32 v130, v100, v130
	v_add_f32_e32 v130, v101, v130
	v_add_f32_e32 v130, v102, v130
	v_add_f32_e32 v130, v103, v130
	v_cvt_pk_bf16_f32 v150, v98, v99
	v_cvt_pk_bf16_f32 v151, v100, v101
	ds_read_b64_tr_b16 v[232:233], v227 offset:30720
	ds_read_b64_tr_b16 v[234:235], v227 offset:31232
	v_add_f32_e32 v98, v104, v130
	v_add_f32_e32 v98, v105, v98
	v_add_f32_e32 v98, v106, v98
	v_add_f32_e32 v98, v107, v98
	v_cvt_pk_bf16_f32 v152, v102, v103
	v_cvt_pk_bf16_f32 v153, v104, v105
	ds_read_b64_tr_b16 v[102:103], v227 offset:27648
	ds_read_b64_tr_b16 v[104:105], v227 offset:28160
	v_add_f32_e32 v98, v108, v98
	v_add_f32_e32 v98, v109, v98
	v_add_f32_e32 v98, v110, v98
	v_add_f32_e32 v98, v111, v98
	v_cvt_pk_bf16_f32 v146, v106, v107
	v_cvt_pk_bf16_f32 v147, v108, v109
	ds_read_b64_tr_b16 v[106:107], v227 offset:31744
	ds_read_b64_tr_b16 v[108:109], v227 offset:32256
	v_add_f32_e32 v98, v112, v98
	v_add_f32_e32 v98, v113, v98
	v_cvt_pk_bf16_f32 v148, v110, v111
	v_cvt_pk_bf16_f32 v149, v112, v113
	s_nop 0
	v_add_f32_e32 v227, v0, v98
	s_add_u32 s98, s12, s96
	s_addc_u32 s99, s13, s97
	s_add_i32 s48, s85, s81
	s_mov_b32 s49, m0
	s_mov_b32 m0, s48
	s_nop 0
	global_load_lds_dwordx4 v144, s[98:99]
	s_mov_b32 m0, s49
	s_add_u32 s38, s38, s4
	s_addc_u32 s39, s39, s5
	s_add_i32 s48, s20, s80
	s_mov_b32 s49, m0
	s_mov_b32 m0, s48
	s_nop 0
	global_load_lds_dwordx4 v142, s[38:39]
	s_mov_b32 m0, s49
	s_waitcnt lgkmcnt(14)
	v_mfma_f32_32x32x16_bf16 v[18:33], v[158:161], v[228:231], v[18:33]
	v_exp_f32_e32 v82, v82
	v_exp_f32_e32 v83, v83
	v_exp_f32_e32 v84, v84
	v_exp_f32_e32 v85, v85
	s_waitcnt lgkmcnt(12)
	v_mfma_f32_32x32x16_bf16 v[34:49], v[158:161], v[114:117], v[34:49]
	v_exp_f32_e32 v86, v86
	v_exp_f32_e32 v87, v87
	v_exp_f32_e32 v88, v88
	v_exp_f32_e32 v89, v89
	v_add_u32_e32 v0, s20, v214
	ds_read_b128 v[98:101], v0
	ds_read_b128 v[134:137], v0 offset:512
	s_waitcnt lgkmcnt(12)
	v_mfma_f32_32x32x16_bf16 v[18:33], v[154:157], v[118:121], v[18:33]
	v_exp_f32_e32 v90, v90
	v_exp_f32_e32 v91, v91
	v_exp_f32_e32 v92, v92
	v_exp_f32_e32 v93, v93
	ds_read_b128 v[138:141], v0 offset:2048
	ds_read_b128 v[130:133], v0 offset:2560
	s_waitcnt lgkmcnt(12)
	v_mfma_f32_32x32x16_bf16 v[34:49], v[154:157], v[122:125], v[34:49]
	v_exp_f32_e32 v94, v94
	v_exp_f32_e32 v95, v95
	v_exp_f32_e32 v96, v96
	v_exp_f32_e32 v97, v97
	s_waitcnt lgkmcnt(10)
	v_mfma_f32_32x32x16_bf16 v[18:33], v[150:153], v[126:129], v[18:33]
	v_exp_f32_e32 v66, v66
	v_exp_f32_e32 v67, v67
	v_exp_f32_e32 v68, v68
	v_exp_f32_e32 v69, v69
	s_waitcnt lgkmcnt(8)
	v_mfma_f32_32x32x16_bf16 v[34:49], v[150:153], v[232:235], v[34:49]
	v_exp_f32_e32 v70, v70
	v_exp_f32_e32 v71, v71
	v_exp_f32_e32 v72, v72
	v_exp_f32_e32 v73, v73
	s_waitcnt lgkmcnt(6)
	v_mfma_f32_32x32x16_bf16 v[18:33], v[146:149], v[102:105], v[18:33]
	v_exp_f32_e32 v74, v74
	v_exp_f32_e32 v75, v75
	v_exp_f32_e32 v76, v76
	v_exp_f32_e32 v77, v77
	s_waitcnt lgkmcnt(4)
	v_mfma_f32_32x32x16_bf16 v[34:49], v[146:149], v[106:109], v[34:49]
	v_exp_f32_e32 v78, v78
	v_exp_f32_e32 v79, v79
	v_exp_f32_e32 v80, v80
	v_exp_f32_e32 v81, v81
	s_add_i32 s48, s20, 0x2000
	s_cmpk_lg_i32 s20, 0x4000
	s_mov_b32 s87, s85
	v_add_u32_e32 v0, s87, v213
	s_cselect_b32 s85, s48, 0
	s_add_i32 s84, s84, 2
	s_add_u32 s12, s12, s92
	s_addc_u32 s13, s13, s93
	s_mov_b32 s86, s20
	s_cmp_gt_u32 s84, 56
	s_waitcnt vmcnt(2) lgkmcnt(0)
	s_barrier
	s_cbranch_scc0 .LBB0_461
;   #define RESC() do{ if(!FIXREF&&resc){ asm volatile("s_waitcnt lgkmcnt(0)":::"memory"); \
;       _Pragma("unroll") for(int d_=0;d_<2;++d_) _Pragma("unroll") for(int r=0;r<16;++r)o[d_][r]*=wsf[crow(r,hi)]; } }while(0)
;   #define ROT() do{sl_prev=sl_cur;sl_cur=sl_next;sl_next=(sl_next==(NSLOT-1)*SLOTB)?0:sl_next+SLOTB;}while(0)
;   #define ENDW(tt) do{ if((tt)+3<NT){WAIT_BAR(2);} else if((tt)+2<NT){WAIT_BAR(1);} else {WAIT_BAR(0);} }while(0)
; template<int THRL,bool FIXREF,bool HALFK> __device__ __forceinline__ void attn_unit(float mref,long rowbase,int q0,const bf16*Qh,int PQ,const bf16*__restrict__ Kh_,int PK,const bf16*__restrict__ Vh_,int PV,bf16*Oh,int PO,const bf16*Gh,int PG,u32x4(&okeep)[4],int omode,float lam,float oml,const float ...
;     ...
;   for(;t+1<NT;t+=2){
;     STEP(pB0,pB1,pA0,pA1,t,(t+3<NT),(t+1<NT),(t+1<NT));       ENDW(t);   RESC(); ROT();
	s_and_b32 s20, s83, 0x3fffffc0
	s_lshl_b32 s20, s20, 2
	s_add_i32 s20, s20, 0
	s_cmp_lg_u32 0, -1
	s_cselect_b32 s50, 0, 0
	s_add_i32 s48, s50, 0x6000
	v_add_u32_e32 v0, s48, v216
	v_add3_u32 v0, v0, v215, v217
	ds_read_b64_tr_b16 v[142:143], v213 offset:32768
	ds_read_b64_tr_b16 v[144:145], v213 offset:33280
	v_add_f32_e32 v102, v82, v83
	v_add_f32_e32 v102, v84, v102
	v_add_f32_e32 v102, v85, v102
	v_add_f32_e32 v102, v86, v102
	v_add_f32_e32 v102, v87, v102
	v_cvt_pk_bf16_f32 v158, v82, v83
	v_cvt_pk_bf16_f32 v159, v84, v85
	s_waitcnt lgkmcnt(5)
	v_mfma_f32_32x32x16_bf16 v[114:129], v[98:101], v[166:169], v[50:65]
	ds_read_b64_tr_b16 v[82:83], v213 offset:36864
	ds_read_b64_tr_b16 v[84:85], v213 offset:37376
	v_add_f32_e32 v98, v88, v102
	v_add_f32_e32 v98, v89, v98
	v_add_f32_e32 v98, v90, v98
	v_add_f32_e32 v146, v91, v98
	v_cvt_pk_bf16_f32 v160, v86, v87
	v_cvt_pk_bf16_f32 v161, v88, v89
	s_waitcnt lgkmcnt(6)
	v_mfma_f32_32x32x16_bf16 v[98:113], v[134:137], v[166:169], v[50:65]
	ds_read_b64_tr_b16 v[86:87], v213 offset:33792
	ds_read_b64_tr_b16 v[88:89], v213 offset:34304
	v_add_f32_e32 v134, v92, v146
	v_add_f32_e32 v134, v93, v134
	v_add_f32_e32 v134, v94, v134
	v_add_f32_e32 v134, v95, v134
	v_cvt_pk_bf16_f32 v154, v90, v91
	v_cvt_pk_bf16_f32 v155, v92, v93
	s_waitcnt lgkmcnt(7)
	v_mfma_f32_32x32x16_bf16 v[114:129], v[138:141], v[162:165], v[114:129]
	ds_read_b64_tr_b16 v[90:91], v213 offset:37888
	ds_read_b64_tr_b16 v[92:93], v213 offset:38400
	s_waitcnt lgkmcnt(8)
	v_mfma_f32_32x32x16_bf16 v[98:113], v[130:133], v[162:165], v[98:113]
	v_add_f32_e32 v130, v96, v134
	v_add_f32_e32 v130, v97, v130
	v_add_f32_e32 v130, v66, v130
	v_add_f32_e32 v130, v67, v130
	v_cvt_pk_bf16_f32 v156, v94, v95
	v_cvt_pk_bf16_f32 v157, v96, v97
	ds_read_b64_tr_b16 v[94:95], v213 offset:34816
	ds_read_b64_tr_b16 v[96:97], v213 offset:35328
	v_add_f32_e32 v130, v68, v130
	v_add_f32_e32 v130, v69, v130
	v_add_f32_e32 v130, v70, v130
	v_add_f32_e32 v130, v71, v130
	v_cvt_pk_bf16_f32 v150, v66, v67
	v_cvt_pk_bf16_f32 v151, v68, v69
	ds_read_b64_tr_b16 v[66:67], v213 offset:38912
	ds_read_b64_tr_b16 v[68:69], v213 offset:39424
	v_add_f32_e32 v130, v72, v130
	v_add_f32_e32 v130, v73, v130
	v_add_f32_e32 v130, v74, v130
	v_add_f32_e32 v130, v75, v130
	v_cvt_pk_bf16_f32 v152, v70, v71
	v_cvt_pk_bf16_f32 v153, v72, v73
	ds_read_b64_tr_b16 v[70:71], v213 offset:35840
	ds_read_b64_tr_b16 v[72:73], v213 offset:36352
	v_add_f32_e32 v130, v76, v130
	v_add_f32_e32 v130, v77, v130
	v_add_f32_e32 v130, v78, v130
	v_add_f32_e32 v130, v79, v130
	v_cvt_pk_bf16_f32 v146, v74, v75
	v_cvt_pk_bf16_f32 v147, v76, v77
	ds_read_b64_tr_b16 v[74:75], v213 offset:39936
	ds_read_b64_tr_b16 v[76:77], v213 offset:40448
	v_add_f32_e32 v130, v80, v130
	v_add_f32_e32 v130, v81, v130
	v_add_f32_e32 v130, 0, v130
	v_cvt_pk_bf16_f32 v148, v78, v79
	v_cvt_pk_bf16_f32 v149, v80, v81
	s_mov_b64 s[48:49], 0x1f0000
	v_lshl_add_u64 v[78:79], v[174:175], 0, s[48:49]
	s_add_i32 s48, s50, s82
	s_add_i32 s49, s48, 0x4000
	s_mov_b32 s50, m0
	s_mov_b32 m0, s49
	s_nop 0
	global_load_lds_dwordx4 v[78:79], off
	s_mov_b32 m0, s50
	v_lshl_add_u64 v[78:79], v[172:173], 0, s[18:19]
	s_mov_b32 s49, m0
	s_mov_b32 m0, s80
	s_nop 0
	global_load_lds_dwordx4 v[78:79], off
	s_mov_b32 m0, s49
	v_add_f32_e32 v215, v227, v130
	s_waitcnt lgkmcnt(14)
	v_mfma_f32_32x32x16_bf16 v[18:33], v[158:161], v[142:145], v[18:33]
	v_exp_f32_e32 v114, v114
	v_exp_f32_e32 v115, v115
	v_exp_f32_e32 v116, v116
	v_exp_f32_e32 v117, v117
	s_waitcnt lgkmcnt(12)
	v_mfma_f32_32x32x16_bf16 v[34:49], v[158:161], v[82:85], v[34:49]
	v_exp_f32_e32 v118, v118
	v_exp_f32_e32 v119, v119
	v_exp_f32_e32 v120, v120
	v_exp_f32_e32 v121, v121
	ds_read_b128 v[78:81], v214
	ds_read_b128 v[82:85], v214 offset:512
	s_waitcnt lgkmcnt(12)
	v_mfma_f32_32x32x16_bf16 v[18:33], v[154:157], v[86:89], v[18:33]
	v_exp_f32_e32 v122, v122
	v_exp_f32_e32 v123, v123
	v_exp_f32_e32 v124, v124
	v_exp_f32_e32 v125, v125
	ds_read_b128 v[86:89], v214 offset:2048
	ds_read_b128 v[228:231], v214 offset:2560
	s_waitcnt lgkmcnt(12)
	v_mfma_f32_32x32x16_bf16 v[34:49], v[154:157], v[90:93], v[34:49]
	v_exp_f32_e32 v126, v126
	v_exp_f32_e32 v127, v127
	v_exp_f32_e32 v128, v128
	v_exp_f32_e32 v129, v129
	s_waitcnt lgkmcnt(10)
	v_mfma_f32_32x32x16_bf16 v[18:33], v[150:153], v[94:97], v[18:33]
	v_exp_f32_e32 v98, v98
	v_exp_f32_e32 v99, v99
	v_exp_f32_e32 v100, v100
	v_exp_f32_e32 v101, v101
	s_waitcnt lgkmcnt(8)
	v_mfma_f32_32x32x16_bf16 v[34:49], v[150:153], v[66:69], v[34:49]
	v_exp_f32_e32 v102, v102
	v_exp_f32_e32 v103, v103
	v_exp_f32_e32 v104, v104
	v_exp_f32_e32 v105, v105
	s_waitcnt lgkmcnt(6)
	v_mfma_f32_32x32x16_bf16 v[18:33], v[146:149], v[70:73], v[18:33]
	v_exp_f32_e32 v106, v106
	v_exp_f32_e32 v107, v107
	v_exp_f32_e32 v108, v108
	v_exp_f32_e32 v109, v109
	s_waitcnt lgkmcnt(4)
	v_mfma_f32_32x32x16_bf16 v[34:49], v[146:149], v[74:77], v[34:49]
	v_exp_f32_e32 v110, v110
	v_exp_f32_e32 v111, v111
	v_exp_f32_e32 v112, v112
	v_exp_f32_e32 v113, v113
	s_waitcnt vmcnt(2) lgkmcnt(0)
	s_barrier
;   #define RESC() do{ if(!FIXREF&&resc){ asm volatile("s_waitcnt lgkmcnt(0)":::"memory"); \
;       _Pragma("unroll") for(int d_=0;d_<2;++d_) _Pragma("unroll") for(int r=0;r<16;++r)o[d_][r]*=wsf[crow(r,hi)]; } }while(0)
;   #define ROT() do{sl_prev=sl_cur;sl_cur=sl_next;sl_next=(sl_next==(NSLOT-1)*SLOTB)?0:sl_next+SLOTB;}while(0)
;   #define ENDW(tt) do{ if((tt)+3<NT){WAIT_BAR(2);} else if((tt)+2<NT){WAIT_BAR(1);} else {WAIT_BAR(0);} }while(0)
; template<int THRL,bool FIXREF,bool HALFK> __device__ __forceinline__ void attn_unit(float mref,long rowbase,int q0,const bf16*Qh,int PQ,const bf16*__restrict__ Kh_,int PK,const bf16*__restrict__ Vh_,int PV,bf16*Oh,int PO,const bf16*Gh,int PG,u32x4(&okeep)[4],int omode,float lam,float oml,const float ...
;     ...
;   for(;t+1<NT;t+=2){
;     STEP(pB0,pB1,pA0,pA1,t,(t+3<NT),(t+1<NT),(t+1<NT));       ENDW(t);   RESC(); ROT();
	ds_read_b64_tr_b16 v[90:91], v213 offset:40960
	ds_read_b64_tr_b16 v[92:93], v213 offset:41472
	v_add_f32_e32 v66, v114, v115
	v_add_f32_e32 v66, v116, v66
	v_add_f32_e32 v66, v117, v66
	v_add_f32_e32 v66, v118, v66
	v_add_f32_e32 v66, v119, v66
	v_cvt_pk_bf16_f32 v158, v114, v115
	v_cvt_pk_bf16_f32 v159, v116, v117
	s_waitcnt lgkmcnt(5)
	v_mfma_f32_32x32x16_bf16 v[130:145], v[78:81], v[166:169], v[50:65]
	ds_read_b64_tr_b16 v[94:95], v213 offset:45056
	ds_read_b64_tr_b16 v[96:97], v213 offset:45568
	v_add_f32_e32 v66, v120, v66
	v_add_f32_e32 v66, v121, v66
	v_add_f32_e32 v66, v122, v66
	v_add_f32_e32 v114, v123, v66
	s_waitcnt lgkmcnt(6)
	v_mfma_f32_32x32x16_bf16 v[66:81], v[82:85], v[166:169], v[50:65]
	v_cvt_pk_bf16_f32 v160, v118, v119
	v_cvt_pk_bf16_f32 v161, v120, v121
	ds_read_b64_tr_b16 v[82:83], v213 offset:41984
	ds_read_b64_tr_b16 v[84:85], v213 offset:42496
	s_waitcnt lgkmcnt(7)
	v_mfma_f32_32x32x16_bf16 v[130:145], v[86:89], v[162:165], v[130:145]
	v_add_f32_e32 v86, v124, v114
	v_add_f32_e32 v86, v125, v86
	v_add_f32_e32 v86, v126, v86
	v_add_f32_e32 v114, v127, v86
	v_cvt_pk_bf16_f32 v154, v122, v123
	v_cvt_pk_bf16_f32 v155, v124, v125
	ds_read_b64_tr_b16 v[86:87], v213 offset:46080
	ds_read_b64_tr_b16 v[88:89], v213 offset:46592
	s_waitcnt lgkmcnt(8)
	v_mfma_f32_32x32x16_bf16 v[66:81], v[228:231], v[162:165], v[66:81]
	v_add_f32_e32 v114, v128, v114
	v_add_f32_e32 v114, v129, v114
	v_add_f32_e32 v114, v98, v114
	v_add_f32_e32 v118, v99, v114
	v_cvt_pk_bf16_f32 v156, v126, v127
	v_cvt_pk_bf16_f32 v157, v128, v129
	ds_read_b64_tr_b16 v[114:115], v213 offset:43008
	ds_read_b64_tr_b16 v[116:117], v213 offset:43520
	v_add_f32_e32 v118, v100, v118
	v_add_f32_e32 v118, v101, v118
	v_add_f32_e32 v118, v102, v118
	v_add_f32_e32 v118, v103, v118
	v_cvt_pk_bf16_f32 v150, v98, v99
	v_cvt_pk_bf16_f32 v151, v100, v101
	ds_read_b64_tr_b16 v[98:99], v213 offset:47104
	ds_read_b64_tr_b16 v[100:101], v213 offset:47616
	v_add_f32_e32 v118, v104, v118
	v_add_f32_e32 v118, v105, v118
	v_add_f32_e32 v118, v106, v118
	v_add_f32_e32 v118, v107, v118
	v_cvt_pk_bf16_f32 v152, v102, v103
	v_cvt_pk_bf16_f32 v153, v104, v105
	ds_read_b64_tr_b16 v[102:103], v213 offset:44032
	ds_read_b64_tr_b16 v[104:105], v213 offset:44544
	v_add_f32_e32 v118, v108, v118
	v_add_f32_e32 v118, v109, v118
	v_add_f32_e32 v118, v110, v118
	v_add_f32_e32 v118, v111, v118
	v_cvt_pk_bf16_f32 v146, v106, v107
	v_cvt_pk_bf16_f32 v147, v108, v109
	ds_read_b64_tr_b16 v[106:107], v213 offset:48128
	ds_read_b64_tr_b16 v[108:109], v213 offset:48640
	v_add_f32_e32 v118, v112, v118
	v_add_f32_e32 v118, v113, v118
	v_add_f32_e32 v118, 0, v118
	v_cvt_pk_bf16_f32 v148, v110, v111
	v_cvt_pk_bf16_f32 v149, v112, v113
	s_mov_b64 s[50:51], 0x1f8000
	v_lshl_add_u64 v[110:111], v[174:175], 0, s[50:51]
	s_mov_b32 s49, m0
	s_mov_b32 m0, s81
	s_nop 0
	global_load_lds_dwordx4 v[110:111], off
	s_mov_b32 m0, s49
	v_lshl_add_u64 v[110:111], v[172:173], 0, s[6:7]
	s_add_i32 s49, s48, 0x8000
	s_mov_b32 s50, m0
	s_mov_b32 m0, s49
	s_nop 0
	global_load_lds_dwordx4 v[110:111], off
	s_mov_b32 m0, s50
	v_add_f32_e32 v215, v215, v118
	s_waitcnt lgkmcnt(14)
	v_mfma_f32_32x32x16_bf16 v[18:33], v[158:161], v[90:93], v[18:33]
	v_exp_f32_e32 v130, v130
	v_exp_f32_e32 v131, v131
	v_exp_f32_e32 v132, v132
	v_exp_f32_e32 v133, v133
	s_waitcnt lgkmcnt(12)
	v_mfma_f32_32x32x16_bf16 v[34:49], v[158:161], v[94:97], v[34:49]
	v_exp_f32_e32 v134, v134
	v_exp_f32_e32 v135, v135
	v_exp_f32_e32 v136, v136
	v_exp_f32_e32 v137, v137
	ds_read_b128 v[90:93], v214 offset:8192
	ds_read_b128 v[110:113], v214 offset:8704
	s_waitcnt lgkmcnt(12)
	v_mfma_f32_32x32x16_bf16 v[18:33], v[154:157], v[82:85], v[18:33]
	v_exp_f32_e32 v138, v138
	v_exp_f32_e32 v139, v139
	v_exp_f32_e32 v140, v140
	v_exp_f32_e32 v141, v141
	ds_read_b128 v[228:231], v214 offset:10240
	ds_read_b128 v[232:235], v214 offset:10752
	s_waitcnt lgkmcnt(12)
	v_mfma_f32_32x32x16_bf16 v[34:49], v[154:157], v[86:89], v[34:49]
	v_exp_f32_e32 v142, v142
	v_exp_f32_e32 v143, v143
	v_exp_f32_e32 v144, v144
	v_exp_f32_e32 v145, v145
	s_waitcnt lgkmcnt(10)
	v_mfma_f32_32x32x16_bf16 v[18:33], v[150:153], v[114:117], v[18:33]
	v_exp_f32_e32 v66, v66
	v_exp_f32_e32 v67, v67
	v_exp_f32_e32 v68, v68
	v_exp_f32_e32 v69, v69
	s_waitcnt lgkmcnt(8)
	v_mfma_f32_32x32x16_bf16 v[34:49], v[150:153], v[98:101], v[34:49]
	v_exp_f32_e32 v70, v70
	v_exp_f32_e32 v71, v71
	v_exp_f32_e32 v72, v72
	v_exp_f32_e32 v73, v73
	s_waitcnt lgkmcnt(6)
	v_mfma_f32_32x32x16_bf16 v[18:33], v[146:149], v[102:105], v[18:33]
	v_exp_f32_e32 v74, v74
	v_exp_f32_e32 v75, v75
	v_exp_f32_e32 v76, v76
	v_exp_f32_e32 v77, v77
	s_waitcnt lgkmcnt(4)
	v_mfma_f32_32x32x16_bf16 v[34:49], v[146:149], v[106:109], v[34:49]
	v_exp_f32_e32 v78, v78
	v_exp_f32_e32 v79, v79
	v_exp_f32_e32 v80, v80
	v_exp_f32_e32 v81, v81
	s_waitcnt vmcnt(2) lgkmcnt(0)
	s_barrier
;   #define RESC() do{ if(!FIXREF&&resc){ asm volatile("s_waitcnt lgkmcnt(0)":::"memory"); \
;       _Pragma("unroll") for(int d_=0;d_<2;++d_) _Pragma("unroll") for(int r=0;r<16;++r)o[d_][r]*=wsf[crow(r,hi)]; } }while(0)
;   #define ROT() do{sl_prev=sl_cur;sl_cur=sl_next;sl_next=(sl_next==(NSLOT-1)*SLOTB)?0:sl_next+SLOTB;}while(0)
;   #define ENDW(tt) do{ if((tt)+3<NT){WAIT_BAR(2);} else if((tt)+2<NT){WAIT_BAR(1);} else {WAIT_BAR(0);} }while(0)
; template<int THRL,bool FIXREF,bool HALFK> __device__ __forceinline__ void attn_unit(float mref,long rowbase,int q0,const bf16*Qh,int PQ,const bf16*__restrict__ Kh_,int PK,const bf16*__restrict__ Vh_,int PV,bf16*Oh,int PO,const bf16*Gh,int PG,u32x4(&okeep)[4],int omode,float lam,float oml,const float ...
;     ...
;   for(;t+1<NT;t+=2){
;     STEP(pB0,pB1,pA0,pA1,t,(t+3<NT),(t+1<NT),(t+1<NT));       ENDW(t);   RESC(); ROT();
;     STEP(pA0,pA1,pB0,pB1,t+1,(t+4<NT),(t+2<NT),(t+2<NT));     ENDW(t+1); RESC(); ROT();
	ds_read_b64_tr_b16 v[98:99], v213 offset:24576
	ds_read_b64_tr_b16 v[100:101], v213 offset:25088
	v_add_f32_e32 v82, v130, v131
	v_add_f32_e32 v82, v132, v82
	v_add_f32_e32 v82, v133, v82
	v_add_f32_e32 v82, v134, v82
	v_add_f32_e32 v82, v135, v82
	v_cvt_pk_bf16_f32 v158, v130, v131
	v_cvt_pk_bf16_f32 v159, v132, v133
	s_waitcnt lgkmcnt(5)
	v_mfma_f32_32x32x16_bf16 v[114:129], v[90:93], v[166:169], v[50:65]
	ds_read_b64_tr_b16 v[102:103], v213 offset:28672
	ds_read_b64_tr_b16 v[104:105], v213 offset:29184
	v_add_f32_e32 v82, v136, v82
	v_add_f32_e32 v82, v137, v82
	v_add_f32_e32 v82, v138, v82
	v_add_f32_e32 v130, v139, v82
	v_cvt_pk_bf16_f32 v160, v134, v135
	v_cvt_pk_bf16_f32 v161, v136, v137
	s_waitcnt lgkmcnt(6)
	v_mfma_f32_32x32x16_bf16 v[82:97], v[110:113], v[166:169], v[50:65]
	ds_read_b64_tr_b16 v[106:107], v213 offset:25600
	ds_read_b64_tr_b16 v[108:109], v213 offset:26112
	v_add_f32_e32 v110, v140, v130
	v_add_f32_e32 v110, v141, v110
	v_add_f32_e32 v110, v142, v110
	v_add_f32_e32 v130, v143, v110
	v_cvt_pk_bf16_f32 v154, v138, v139
	v_cvt_pk_bf16_f32 v155, v140, v141
	s_waitcnt lgkmcnt(7)
	v_mfma_f32_32x32x16_bf16 v[114:129], v[228:231], v[162:165], v[114:129]
	ds_read_b64_tr_b16 v[110:111], v213 offset:29696
	ds_read_b64_tr_b16 v[112:113], v213 offset:30208
	v_add_f32_e32 v130, v144, v130
	v_add_f32_e32 v130, v145, v130
	v_add_f32_e32 v130, v66, v130
	v_add_f32_e32 v134, v67, v130
	v_cvt_pk_bf16_f32 v156, v142, v143
	v_cvt_pk_bf16_f32 v157, v144, v145
	s_waitcnt lgkmcnt(8)
	v_mfma_f32_32x32x16_bf16 v[82:97], v[232:235], v[162:165], v[82:97]
	ds_read_b64_tr_b16 v[130:131], v213 offset:26624
	ds_read_b64_tr_b16 v[132:133], v213 offset:27136
	v_add_f32_e32 v134, v68, v134
	v_add_f32_e32 v134, v69, v134
	v_add_f32_e32 v134, v70, v134
	v_add_f32_e32 v134, v71, v134
	v_cvt_pk_bf16_f32 v150, v66, v67
	v_cvt_pk_bf16_f32 v151, v68, v69
	ds_read_b64_tr_b16 v[66:67], v213 offset:30720
	ds_read_b64_tr_b16 v[68:69], v213 offset:31232
	v_add_f32_e32 v134, v72, v134
	v_add_f32_e32 v134, v73, v134
	v_add_f32_e32 v134, v74, v134
	v_add_f32_e32 v134, v75, v134
	v_cvt_pk_bf16_f32 v152, v70, v71
	v_cvt_pk_bf16_f32 v153, v72, v73
	ds_read_b64_tr_b16 v[70:71], v213 offset:27648
	ds_read_b64_tr_b16 v[72:73], v213 offset:28160
	v_add_f32_e32 v134, v76, v134
	v_add_f32_e32 v134, v77, v134
	v_add_f32_e32 v134, v78, v134
	v_add_f32_e32 v134, v79, v134
	v_cvt_pk_bf16_f32 v146, v74, v75
	v_cvt_pk_bf16_f32 v147, v76, v77
	ds_read_b64_tr_b16 v[74:75], v213 offset:31744
	ds_read_b64_tr_b16 v[76:77], v213 offset:32256
	v_add_f32_e32 v134, v80, v134
	v_add_f32_e32 v134, v81, v134
	v_add_f32_e32 v134, 0, v134
	v_cvt_pk_bf16_f32 v148, v78, v79
	v_cvt_pk_bf16_f32 v149, v80, v81
	v_lshl_add_u64 v[78:79], v[172:173], 0, s[94:95]
	s_add_i32 s48, s48, 0xa000
	s_mov_b32 s49, m0
	s_mov_b32 m0, s48
	s_nop 0
	global_load_lds_dwordx4 v[78:79], off
	s_mov_b32 m0, s49
	v_add_f32_e32 v174, v215, v134
	s_waitcnt lgkmcnt(14)
	v_mfma_f32_32x32x16_bf16 v[18:33], v[158:161], v[98:101], v[18:33]
	v_exp_f32_e32 v114, v114
	v_exp_f32_e32 v115, v115
	v_exp_f32_e32 v116, v116
	v_exp_f32_e32 v117, v117
	s_waitcnt lgkmcnt(12)
	v_mfma_f32_32x32x16_bf16 v[34:49], v[158:161], v[102:105], v[34:49]
	v_exp_f32_e32 v118, v118
	v_exp_f32_e32 v119, v119
	v_exp_f32_e32 v120, v120
	v_exp_f32_e32 v121, v121
	ds_read_b128 v[78:81], v214 offset:16384
	ds_read_b128 v[134:137], v214 offset:16896
	s_waitcnt lgkmcnt(12)
	v_mfma_f32_32x32x16_bf16 v[18:33], v[154:157], v[106:109], v[18:33]
	v_exp_f32_e32 v122, v122
	v_exp_f32_e32 v123, v123
	v_exp_f32_e32 v124, v124
	v_exp_f32_e32 v125, v125
	ds_read_b128 v[138:141], v214 offset:18432
	ds_read_b128 v[142:145], v214 offset:18944
	s_waitcnt lgkmcnt(12)
	v_mfma_f32_32x32x16_bf16 v[34:49], v[154:157], v[110:113], v[34:49]
	v_exp_f32_e32 v126, v126
	v_exp_f32_e32 v127, v127
	v_exp_f32_e32 v128, v128
	v_exp_f32_e32 v129, v129
	s_waitcnt lgkmcnt(10)
	v_mfma_f32_32x32x16_bf16 v[18:33], v[150:153], v[130:133], v[18:33]
	v_exp_f32_e32 v82, v82
	v_exp_f32_e32 v83, v83
	v_exp_f32_e32 v84, v84
	v_exp_f32_e32 v85, v85
	s_waitcnt lgkmcnt(8)
	v_mfma_f32_32x32x16_bf16 v[34:49], v[150:153], v[66:69], v[34:49]
	v_exp_f32_e32 v86, v86
	v_exp_f32_e32 v87, v87
	v_exp_f32_e32 v88, v88
	v_exp_f32_e32 v89, v89
	s_waitcnt lgkmcnt(6)
	v_mfma_f32_32x32x16_bf16 v[18:33], v[146:149], v[70:73], v[18:33]
	v_exp_f32_e32 v90, v90
	v_exp_f32_e32 v91, v91
	v_exp_f32_e32 v92, v92
	v_exp_f32_e32 v93, v93
	s_waitcnt lgkmcnt(4)
	v_mfma_f32_32x32x16_bf16 v[34:49], v[146:149], v[74:77], v[34:49]
	v_exp_f32_e32 v94, v94
	v_exp_f32_e32 v95, v95
	v_exp_f32_e32 v96, v96
	v_exp_f32_e32 v97, v97
	s_waitcnt vmcnt(1) lgkmcnt(0)
	s_barrier
	ds_read_b64_tr_b16 v[130:131], v213 offset:32768
	ds_read_b64_tr_b16 v[132:133], v213 offset:33280
	v_add_f32_e32 v66, v114, v115
	v_add_f32_e32 v66, v116, v66
	v_add_f32_e32 v66, v117, v66
	v_add_f32_e32 v66, v118, v66
	v_add_f32_e32 v66, v119, v66
	v_cvt_pk_bf16_f32 v158, v114, v115
	v_cvt_pk_bf16_f32 v159, v116, v117
	s_waitcnt lgkmcnt(5)
	v_mfma_f32_32x32x16_bf16 v[98:113], v[78:81], v[166:169], v[50:65]
	ds_read_b64_tr_b16 v[114:115], v213 offset:36864
	ds_read_b64_tr_b16 v[116:117], v213 offset:37376
	v_add_f32_e32 v66, v120, v66
	v_add_f32_e32 v66, v121, v66
	v_add_f32_e32 v66, v122, v66
	v_add_f32_e32 v146, v123, v66
	s_waitcnt lgkmcnt(6)
	v_mfma_f32_32x32x16_bf16 v[66:81], v[134:137], v[166:169], v[50:65]
	v_cvt_pk_bf16_f32 v160, v118, v119
	v_cvt_pk_bf16_f32 v161, v120, v121
	ds_read_b64_tr_b16 v[118:119], v213 offset:33792
	ds_read_b64_tr_b16 v[120:121], v213 offset:34304
	v_add_f32_e32 v134, v124, v146
	v_add_f32_e32 v134, v125, v134
	v_add_f32_e32 v134, v126, v134
	s_waitcnt lgkmcnt(7)
	v_mfma_f32_32x32x16_bf16 v[98:113], v[138:141], v[162:165], v[98:113]
	v_add_f32_e32 v138, v127, v134
	v_cvt_pk_bf16_f32 v154, v122, v123
	v_cvt_pk_bf16_f32 v155, v124, v125
	ds_read_b64_tr_b16 v[134:135], v213 offset:37888
	ds_read_b64_tr_b16 v[136:137], v213 offset:38400
	s_waitcnt lgkmcnt(8)
	v_mfma_f32_32x32x16_bf16 v[66:81], v[142:145], v[162:165], v[66:81]
	v_add_f32_e32 v122, v128, v138
	v_add_f32_e32 v122, v129, v122
	v_add_f32_e32 v122, v82, v122
	v_add_f32_e32 v122, v83, v122
	v_cvt_pk_bf16_f32 v156, v126, v127
	v_cvt_pk_bf16_f32 v157, v128, v129
	ds_read_b64_tr_b16 v[124:125], v213 offset:34816
	ds_read_b64_tr_b16 v[126:127], v213 offset:35328
	v_add_f32_e32 v122, v84, v122
	v_add_f32_e32 v122, v85, v122
	v_add_f32_e32 v122, v86, v122
	v_add_f32_e32 v122, v87, v122
	v_cvt_pk_bf16_f32 v150, v82, v83
	v_cvt_pk_bf16_f32 v151, v84, v85
	ds_read_b64_tr_b16 v[82:83], v213 offset:38912
	ds_read_b64_tr_b16 v[84:85], v213 offset:39424
	v_add_f32_e32 v122, v88, v122
	v_add_f32_e32 v122, v89, v122
	v_add_f32_e32 v122, v90, v122
	v_add_f32_e32 v122, v91, v122
	v_cvt_pk_bf16_f32 v152, v86, v87
	v_cvt_pk_bf16_f32 v153, v88, v89
	ds_read_b64_tr_b16 v[86:87], v213 offset:35840
	ds_read_b64_tr_b16 v[88:89], v213 offset:36352
	v_add_f32_e32 v122, v92, v122
	v_add_f32_e32 v122, v93, v122
	v_add_f32_e32 v122, v94, v122
	v_add_f32_e32 v122, v95, v122
	v_cvt_pk_bf16_f32 v146, v90, v91
	v_cvt_pk_bf16_f32 v147, v92, v93
	ds_read_b64_tr_b16 v[90:91], v213 offset:39936
	ds_read_b64_tr_b16 v[92:93], v213 offset:40448
	v_add_f32_e32 v122, v96, v122
	v_add_f32_e32 v122, v97, v122
	v_add_f32_e32 v122, 0, v122
	v_cvt_pk_bf16_f32 v148, v94, v95
	v_cvt_pk_bf16_f32 v149, v96, v97
	v_lshl_add_u64 v[94:95], v[172:173], 0, s[26:27]
	s_mov_b32 s48, m0
	s_mov_b32 m0, s80
	s_nop 0
	global_load_lds_dwordx4 v[94:95], off
	s_mov_b32 m0, s48
	v_add_f32_e32 v122, v174, v122
	s_waitcnt lgkmcnt(14)
	v_mfma_f32_32x32x16_bf16 v[18:33], v[158:161], v[130:133], v[18:33]
	v_exp_f32_e32 v98, v98
	v_exp_f32_e32 v99, v99
	v_exp_f32_e32 v100, v100
	v_exp_f32_e32 v101, v101
	s_waitcnt lgkmcnt(12)
	v_mfma_f32_32x32x16_bf16 v[34:49], v[158:161], v[114:117], v[34:49]
	v_exp_f32_e32 v102, v102
	v_exp_f32_e32 v103, v103
	v_exp_f32_e32 v104, v104
	v_exp_f32_e32 v105, v105
	ds_read_b128 v[128:131], v214
	ds_read_b128 v[138:141], v214 offset:512
	s_waitcnt lgkmcnt(12)
	v_mfma_f32_32x32x16_bf16 v[18:33], v[154:157], v[118:121], v[18:33]
	v_exp_f32_e32 v106, v106
	v_exp_f32_e32 v107, v107
	v_exp_f32_e32 v108, v108
	v_exp_f32_e32 v109, v109
	ds_read_b128 v[142:145], v214 offset:2048
	ds_read_b128 v[172:175], v214 offset:2560
	s_waitcnt lgkmcnt(12)
	v_mfma_f32_32x32x16_bf16 v[34:49], v[154:157], v[134:137], v[34:49]
	v_exp_f32_e32 v110, v110
	v_exp_f32_e32 v111, v111
	v_exp_f32_e32 v112, v112
	v_exp_f32_e32 v113, v113
	s_waitcnt lgkmcnt(10)
	v_mfma_f32_32x32x16_bf16 v[18:33], v[150:153], v[124:127], v[18:33]
	v_exp_f32_e32 v66, v66
	v_exp_f32_e32 v67, v67
	v_exp_f32_e32 v68, v68
	v_exp_f32_e32 v69, v69
	s_waitcnt lgkmcnt(8)
	v_mfma_f32_32x32x16_bf16 v[34:49], v[150:153], v[82:85], v[34:49]
	v_exp_f32_e32 v70, v70
	v_exp_f32_e32 v71, v71
	v_exp_f32_e32 v72, v72
	v_exp_f32_e32 v73, v73
	s_waitcnt lgkmcnt(6)
	v_mfma_f32_32x32x16_bf16 v[18:33], v[146:149], v[86:89], v[18:33]
	v_exp_f32_e32 v74, v74
	v_exp_f32_e32 v75, v75
	v_exp_f32_e32 v76, v76
	v_exp_f32_e32 v77, v77
	s_waitcnt lgkmcnt(4)
	v_mfma_f32_32x32x16_bf16 v[34:49], v[146:149], v[90:93], v[34:49]
	v_exp_f32_e32 v78, v78
	v_exp_f32_e32 v79, v79
	v_exp_f32_e32 v80, v80
	v_exp_f32_e32 v81, v81
	s_waitcnt vmcnt(0) lgkmcnt(0)
	s_barrier
; #define SBAR() __builtin_amdgcn_sched_barrier(0)
;   #define RESC() do{ if(!FIXREF&&resc){ asm volatile("s_waitcnt lgkmcnt(0)":::"memory"); \
;       _Pragma("unroll") for(int d_=0;d_<2;++d_) _Pragma("unroll") for(int r=0;r<16;++r)o[d_][r]*=wsf[crow(r,hi)]; } }while(0)
;   #define PKW(P,B) cvtpk_s(P[B],P[B+1])
; template<int THRL,bool FIXREF,bool HALFK> __device__ __forceinline__ void attn_unit(float mref,long rowbase,int q0,const bf16*Qh,int PQ,const bf16*__restrict__ Kh_,int PK,const bf16*__restrict__ Vh_,int PV,bf16*Oh,int PO,const bf16*Gh,int PG,u32x4(&okeep)[4],int omode,float lam,float oml,const float ...
;     ...
;   STEP(pB0,pB1,pA0,pA1,NT-1,false,false,false); RESC();
;   { float sacc=pB0[0]+pB0[1]; _Pragma("unroll") for(int r=2;r<16;++r)sacc+=pB0[r]; _Pragma("unroll") for(int r=0;r<16;++r)sacc+=pB1[r]; l_reg+=sacc;
;     pw0=(u32x4){PKW(pB0,0),PKW(pB0,2),PKW(pB0,4),PKW(pB0,6)};pw1=(u32x4){PKW(pB0,8),PKW(pB0,10),PKW(pB0,12),PKW(pB0,14)};pw2=(u32x4){PKW(pB1,0),PKW(pB1,2),PKW(pB1,4),PKW(pB1,6)};pw3=(u32x4){PKW(pB1,8),PKW(pB1,10),PKW(pB1,12),PKW(pB1,14)};
;     SBAR(); pv(o,vb0+sl_cur,PAF(0),PAF(1),PAF(2),PAF(3)); }
	ds_read_b64_tr_b16 v[114:115], v213 offset:40960
	ds_read_b64_tr_b16 v[116:117], v213 offset:41472
	v_add_f32_e32 v82, v98, v99
	v_add_f32_e32 v82, v100, v82
	v_add_f32_e32 v82, v101, v82
	v_add_f32_e32 v82, v102, v82
	v_add_f32_e32 v118, v103, v82
	v_cvt_pk_bf16_f32 v158, v98, v99
	v_cvt_pk_bf16_f32 v159, v100, v101
	s_waitcnt lgkmcnt(5)
	v_mfma_f32_32x32x16_bf16 v[82:97], v[128:131], v[166:169], v[50:65]
	ds_read_b64_tr_b16 v[98:99], v213 offset:45056
	ds_read_b64_tr_b16 v[100:101], v213 offset:45568
	v_add_f32_e32 v118, v104, v118
	v_add_f32_e32 v118, v105, v118
	v_add_f32_e32 v118, v106, v118
	v_add_f32_e32 v123, v107, v118
	v_cvt_pk_bf16_f32 v160, v102, v103
	v_cvt_pk_bf16_f32 v161, v104, v105
	s_waitcnt lgkmcnt(6)
	v_mfma_f32_32x32x16_bf16 v[50:65], v[138:141], v[166:169], v[50:65]
	ds_read_b64_tr_b16 v[118:119], v213 offset:41984
	ds_read_b64_tr_b16 v[120:121], v213 offset:42496
	v_add_f32_e32 v102, v108, v123
	v_add_f32_e32 v102, v109, v102
	v_add_f32_e32 v102, v110, v102
	v_add_f32_e32 v123, v111, v102
	v_cvt_pk_bf16_f32 v154, v106, v107
	v_cvt_pk_bf16_f32 v155, v108, v109
	s_waitcnt lgkmcnt(7)
	v_mfma_f32_32x32x16_bf16 v[82:97], v[142:145], v[162:165], v[82:97]
	ds_read_b64_tr_b16 v[102:103], v213 offset:46080
	ds_read_b64_tr_b16 v[104:105], v213 offset:46592
	v_add_f32_e32 v106, v112, v123
	v_add_f32_e32 v106, v113, v106
	v_add_f32_e32 v106, v66, v106
	v_add_f32_e32 v123, v67, v106
	v_cvt_pk_bf16_f32 v156, v110, v111
	v_cvt_pk_bf16_f32 v157, v112, v113
	s_waitcnt lgkmcnt(8)
	v_mfma_f32_32x32x16_bf16 v[50:65], v[172:175], v[162:165], v[50:65]
	ds_read_b64_tr_b16 v[106:107], v213 offset:43008
	ds_read_b64_tr_b16 v[108:109], v213 offset:43520
	v_add_f32_e32 v110, v68, v123
	v_add_f32_e32 v110, v69, v110
	v_add_f32_e32 v110, v70, v110
	v_add_f32_e32 v110, v71, v110
	v_cvt_pk_bf16_f32 v150, v66, v67
	v_cvt_pk_bf16_f32 v151, v68, v69
	ds_read_b64_tr_b16 v[66:67], v213 offset:47104
	ds_read_b64_tr_b16 v[68:69], v213 offset:47616
	v_add_f32_e32 v110, v72, v110
	v_add_f32_e32 v110, v73, v110
	v_add_f32_e32 v110, v74, v110
	v_add_f32_e32 v123, v75, v110
	v_cvt_pk_bf16_f32 v152, v70, v71
	v_cvt_pk_bf16_f32 v153, v72, v73
	ds_read_b64_tr_b16 v[110:111], v213 offset:44032
	ds_read_b64_tr_b16 v[112:113], v213 offset:44544
	v_add_f32_e32 v70, v76, v123
	v_add_f32_e32 v70, v77, v70
	v_add_f32_e32 v70, v78, v70
	v_add_f32_e32 v123, v79, v70
	v_cvt_pk_bf16_f32 v146, v74, v75
	v_cvt_pk_bf16_f32 v147, v76, v77
	ds_read_b64_tr_b16 v[70:71], v213 offset:48128
	ds_read_b64_tr_b16 v[72:73], v213 offset:48640
	v_add_f32_e32 v74, v80, v123
	v_add_f32_e32 v74, v81, v74
	v_add_f32_e32 v74, 0, v74
	v_cvt_pk_bf16_f32 v148, v78, v79
	v_cvt_pk_bf16_f32 v149, v80, v81
	v_exp_f32_e32 v82, v82
	v_exp_f32_e32 v83, v83
	v_exp_f32_e32 v84, v84
	v_exp_f32_e32 v85, v85
	s_nop 0
	v_exp_f32_e32 v86, v86
	v_exp_f32_e32 v87, v87
	v_exp_f32_e32 v88, v88
	v_exp_f32_e32 v89, v89
	s_nop 0
	v_exp_f32_e32 v90, v90
	v_exp_f32_e32 v91, v91
	v_exp_f32_e32 v92, v92
	v_exp_f32_e32 v93, v93
	s_nop 0
	v_exp_f32_e32 v94, v94
	v_exp_f32_e32 v95, v95
	v_exp_f32_e32 v96, v96
	v_exp_f32_e32 v97, v97
	v_exp_f32_e32 v50, v50
	v_exp_f32_e32 v51, v51
	v_exp_f32_e32 v52, v52
	v_exp_f32_e32 v53, v53
	s_nop 0
	v_exp_f32_e32 v54, v54
	v_exp_f32_e32 v55, v55
	v_exp_f32_e32 v56, v56
	v_exp_f32_e32 v57, v57
	s_nop 0
	v_exp_f32_e32 v58, v58
	v_exp_f32_e32 v59, v59
	v_exp_f32_e32 v60, v60
	v_exp_f32_e32 v61, v61
	s_nop 0
	v_exp_f32_e32 v62, v62
	v_exp_f32_e32 v63, v63
	v_exp_f32_e32 v64, v64
	v_exp_f32_e32 v65, v65
	s_waitcnt lgkmcnt(14)
	v_mfma_f32_32x32x16_bf16 v[18:33], v[158:161], v[114:117], v[18:33]
	v_add_f32_e32 v75, v82, v83
	v_add_f32_e32 v75, v84, v75
	v_add_f32_e32 v75, v85, v75
	v_add_f32_e32 v75, v86, v75
	v_add_f32_e32 v75, v87, v75
	v_add_f32_e32 v75, v88, v75
	v_add_f32_e32 v75, v89, v75
	s_waitcnt lgkmcnt(12)
	v_mfma_f32_32x32x16_bf16 v[34:49], v[158:161], v[98:101], v[34:49]
	v_add_f32_e32 v75, v90, v75
	v_add_f32_e32 v75, v91, v75
	v_add_f32_e32 v75, v92, v75
	v_add_f32_e32 v75, v93, v75
	v_add_f32_e32 v75, v94, v75
	v_add_f32_e32 v75, v95, v75
	v_add_f32_e32 v75, v96, v75
	s_waitcnt lgkmcnt(10)
	v_mfma_f32_32x32x16_bf16 v[18:33], v[154:157], v[118:121], v[18:33]
	v_add_f32_e32 v75, v97, v75
	v_add_f32_e32 v75, v50, v75
	v_add_f32_e32 v75, v51, v75
	v_add_f32_e32 v75, v52, v75
	v_add_f32_e32 v75, v53, v75
	v_add_f32_e32 v75, v54, v75
	v_add_f32_e32 v75, v55, v75
	s_waitcnt lgkmcnt(8)
	v_mfma_f32_32x32x16_bf16 v[34:49], v[154:157], v[102:105], v[34:49]
	v_add_f32_e32 v75, v56, v75
	v_add_f32_e32 v75, v57, v75
	v_add_f32_e32 v75, v58, v75
	v_add_f32_e32 v75, v59, v75
	v_add_f32_e32 v75, v60, v75
	v_add_f32_e32 v75, v61, v75
	v_add_f32_e32 v75, v62, v75
	s_waitcnt lgkmcnt(6)
	v_mfma_f32_32x32x16_bf16 v[18:33], v[150:153], v[106:109], v[18:33]
	v_add_f32_e32 v75, v63, v75
	v_add_f32_e32 v75, v64, v75
	v_add_f32_e32 v75, v65, v75
	v_add_f32_e32 v74, v122, v74
	v_add_f32_e32 v74, v74, v75
	v_cvt_pk_bf16_f32 v76, v82, v83
	v_cvt_pk_bf16_f32 v77, v84, v85
	s_waitcnt lgkmcnt(4)
	v_mfma_f32_32x32x16_bf16 v[34:49], v[150:153], v[66:69], v[34:49]
	v_cvt_pk_bf16_f32 v78, v86, v87
	v_cvt_pk_bf16_f32 v79, v88, v89
	v_cvt_pk_bf16_f32 v80, v90, v91
	v_cvt_pk_bf16_f32 v81, v92, v93
	v_cvt_pk_bf16_f32 v82, v94, v95
	v_cvt_pk_bf16_f32 v83, v96, v97
	v_cvt_pk_bf16_f32 v50, v50, v51
	s_waitcnt lgkmcnt(2)
	v_mfma_f32_32x32x16_bf16 v[18:33], v[146:149], v[110:113], v[18:33]
	v_cvt_pk_bf16_f32 v51, v52, v53
	v_cvt_pk_bf16_f32 v52, v54, v55
	v_cvt_pk_bf16_f32 v53, v56, v57
	v_cvt_pk_bf16_f32 v54, v58, v59
	v_cvt_pk_bf16_f32 v55, v60, v61
	v_cvt_pk_bf16_f32 v56, v62, v63
	v_cvt_pk_bf16_f32 v57, v64, v65
	s_waitcnt lgkmcnt(0)
; __device__ __forceinline__ int crow(int r,int hi){return (r&3)+8*(r>>2)+4*hi;}
; #define SBAR() __builtin_amdgcn_sched_barrier(0)
; __device__ __forceinline__ void pv(f32x16*o,int vb,bf16x8 pa0,bf16x8 pa1,bf16x8 pa2,bf16x8 pa3){
;   #pragma unroll
;   for(int d0=0;d0<2;++d0){s16x4 lo[4],hi[4];
;     #pragma unroll
;     for(int ks=0;ks<4;++ks){
;       asm volatile("ds_read_b64_tr_b16 %0,%1 offset:%c2":"=&v"(lo[ks]):"v"(vb),"i"(d0*4096+ks*1024):"memory");
;       asm volatile("ds_read_b64_tr_b16 %0,%1 offset:%c2":"=&v"(hi[ks]):"v"(vb),"i"(d0*4096+ks*1024+512):"memory");}
;     asm volatile("s_waitcnt lgkmcnt(0)":::"memory");SBAR();
;     ...
;     o[d0]=__builtin_amdgcn_mfma_f32_32x32x16_bf16(pa0,PK(0),o[d0],0,0,0);
;     o[d0]=__builtin_amdgcn_mfma_f32_32x32x16_bf16(pa1,PK(1),o[d0],0,0,0);
;     o[d0]=__builtin_amdgcn_mfma_f32_32x32x16_bf16(pa2,PK(2),o[d0],0,0,0);
;     o[d0]=__builtin_amdgcn_mfma_f32_32x32x16_bf16(pa3,PK(3),o[d0],0,0,0);
;     ...
;   }
; }
; template<int THRL,bool FIXREF,bool HALFK> __device__ __forceinline__ void attn_unit(float mref,long rowbase,int q0,const bf16*Qh,int PQ,const bf16*__restrict__ Kh_,int PK,const bf16*__restrict__ Vh_,int PV,bf16*Oh,int PO,const bf16*Gh,int PG,u32x4(&okeep)[4],int omode,float lam,float oml,const float ...
;     ...
;   {auto rr=__builtin_amdgcn_permlane32_swap(__float_as_uint(l_reg),__float_as_uint(l_reg),false,false);l_reg=__uint_as_float(rr[0])+__uint_as_float(rr[1]);}
;   if(hi==0)wsf[32+r32]=l_reg;asm volatile("s_waitcnt lgkmcnt(0)":::"memory");
;   float rli[16];
;   #pragma unroll
;   for(int r=0;r<16;++r)rli[r]=__builtin_amdgcn_rcpf(wsf[32+crow(r,hi)]);
;   bf16*Ow=Oh+(rowbase+q0+wid*QBLK)*PO;
;   { bf16*stg=(bf16*)(shm+LDS_OST)+wid*2048;
;     #pragma unroll
;     for(int r=0;r<16;++r){const int orow=crow(r,hi);
;       #pragma unroll
;       for(int d0=0;d0<2;++d0)stg[orow*64+d0*32+r32]=__float2bfloat16(o[d0][r]*rli[r]);}
;     asm volatile("s_waitcnt lgkmcnt(0)":::"memory");
	v_mfma_f32_32x32x16_bf16 v[34:49], v[146:149], v[70:73], v[34:49]
	ds_read_b64_tr_b16 v[58:59],v0 offset:0
	ds_read_b64_tr_b16 v[60:61],v0 offset:512
	ds_read_b64_tr_b16 v[62:63],v0 offset:1024
	ds_read_b64_tr_b16 v[64:65],v0 offset:1536
	ds_read_b64_tr_b16 v[66:67],v0 offset:2048
	ds_read_b64_tr_b16 v[68:69],v0 offset:2560
	ds_read_b64_tr_b16 v[70:71],v0 offset:3072
	ds_read_b64_tr_b16 v[72:73],v0 offset:3584
	s_waitcnt lgkmcnt(0)
	s_nop 0
	v_mfma_f32_32x32x16_bf16 v[18:33], v[76:79], v[58:61], v[18:33]
	ds_read_b64_tr_b16 v[58:59],v0 offset:4096
	ds_read_b64_tr_b16 v[60:61],v0 offset:4608
	v_mfma_f32_32x32x16_bf16 v[18:33], v[80:83], v[62:65], v[18:33]
	ds_read_b64_tr_b16 v[62:63],v0 offset:5120
	ds_read_b64_tr_b16 v[64:65],v0 offset:5632
	v_mfma_f32_32x32x16_bf16 v[18:33], v[50:53], v[66:69], v[18:33]
	ds_read_b64_tr_b16 v[66:67],v0 offset:6144
	ds_read_b64_tr_b16 v[68:69],v0 offset:6656
	v_mfma_f32_32x32x16_bf16 v[18:33], v[54:57], v[70:73], v[18:33]
	ds_read_b64_tr_b16 v[70:71],v0 offset:7168
	ds_read_b64_tr_b16 v[72:73],v0 offset:7680
	s_waitcnt lgkmcnt(0)
	v_mfma_f32_32x32x16_bf16 v[34:49], v[76:79], v[58:61], v[34:49]
	v_mov_b32_e32 v0, v74
	s_nop 1
	v_permlane32_swap_b32_e32 v74, v0
	v_cmp_gt_u32_e32 vcc, 32, v209
	v_mfma_f32_32x32x16_bf16 v[34:49], v[80:83], v[62:65], v[34:49]
	v_mfma_f32_32x32x16_bf16 v[34:49], v[50:53], v[66:69], v[34:49]
	v_mfma_f32_32x32x16_bf16 v[34:49], v[54:57], v[70:73], v[34:49]
	s_and_saveexec_b64 s[48:49], vcc
	v_lshl_add_u32 v50, v171, 2, s20
	v_add_f32_e32 v0, v74, v0
	ds_write_b32 v50, v0 offset:49280
	s_or_b64 exec, exec, s[48:49]
	s_waitcnt lgkmcnt(0)
	v_lshl_add_u32 v0, v212, 4, s20
	ds_read_b128 v[50:53], v0 offset:49280
	ds_read_b128 v[54:57], v0 offset:49312
	s_lshl_b32 s20, s79, 12
	s_add_i32 s20, s20, 0
	v_lshlrev_b32_e32 v66, 1, v171
	s_waitcnt lgkmcnt(1)
	v_rcp_f32_e32 v58, v50
	v_rcp_f32_e32 v59, v51
	v_rcp_f32_e32 v60, v52
	v_rcp_f32_e32 v61, v53
	s_waitcnt lgkmcnt(0)
	v_rcp_f32_e32 v62, v54
	ds_read_b128 v[50:53], v0 offset:49344
	v_rcp_f32_e32 v63, v55
	v_rcp_f32_e32 v64, v56
	v_rcp_f32_e32 v65, v57
	ds_read_b128 v[54:57], v0 offset:49376
	s_waitcnt lgkmcnt(1)
	v_rcp_f32_e32 v0, v50
	v_rcp_f32_e32 v50, v51
	v_rcp_f32_e32 v51, v52
	v_rcp_f32_e32 v52, v53
	s_waitcnt lgkmcnt(0)
	v_rcp_f32_e32 v53, v54
	v_rcp_f32_e32 v54, v55
	v_rcp_f32_e32 v55, v56
	v_rcp_f32_e32 v56, v57
	v_lshlrev_b32_e32 v57, 9, v212
	v_mul_f32_e32 v18, v18, v58
	v_add3_u32 v57, s20, v57, v66
	v_cvt_pk_bf16_f32 v18, v18, s0
	ds_write_b16 v57, v18 offset:51200
	v_mul_f32_e32 v18, v34, v58
	v_cvt_pk_bf16_f32 v18, v18, s0
	ds_write_b16 v57, v18 offset:51264
	v_mul_f32_e32 v18, v19, v59
	v_cvt_pk_bf16_f32 v18, v18, s0
	ds_write_b16 v57, v18 offset:51328
	v_mul_f32_e32 v18, v35, v59
	v_cvt_pk_bf16_f32 v18, v18, s0
	ds_write_b16 v57, v18 offset:51392
	v_mul_f32_e32 v18, v20, v60
	v_cvt_pk_bf16_f32 v18, v18, s0
	ds_write_b16 v57, v18 offset:51456
	v_mul_f32_e32 v18, v36, v60
	v_cvt_pk_bf16_f32 v18, v18, s0
	ds_write_b16 v57, v18 offset:51520
	v_mul_f32_e32 v18, v21, v61
	v_cvt_pk_bf16_f32 v18, v18, s0
	ds_write_b16 v57, v18 offset:51584
	v_mul_f32_e32 v18, v37, v61
	v_cvt_pk_bf16_f32 v18, v18, s0
	ds_write_b16 v57, v18 offset:51648
	v_mul_f32_e32 v18, v22, v62
	v_cvt_pk_bf16_f32 v18, v18, s0
	ds_write_b16 v57, v18 offset:52224
	v_mul_f32_e32 v18, v38, v62
	v_cvt_pk_bf16_f32 v18, v18, s0
	ds_write_b16 v57, v18 offset:52288
	v_mul_f32_e32 v18, v23, v63
	v_cvt_pk_bf16_f32 v18, v18, s0
	ds_write_b16 v57, v18 offset:52352
	v_mul_f32_e32 v18, v39, v63
	v_cvt_pk_bf16_f32 v18, v18, s0
	ds_write_b16 v57, v18 offset:52416
	v_mul_f32_e32 v18, v24, v64
	v_cvt_pk_bf16_f32 v18, v18, s0
	ds_write_b16 v57, v18 offset:52480
	v_mul_f32_e32 v18, v40, v64
	v_cvt_pk_bf16_f32 v18, v18, s0
	ds_write_b16 v57, v18 offset:52544
	v_mul_f32_e32 v18, v25, v65
	v_cvt_pk_bf16_f32 v18, v18, s0
	ds_write_b16 v57, v18 offset:52608
	v_mul_f32_e32 v18, v41, v65
	v_cvt_pk_bf16_f32 v18, v18, s0
	ds_write_b16 v57, v18 offset:52672
	v_mul_f32_e32 v18, v26, v0
	v_mul_f32_e32 v0, v42, v0
	v_cvt_pk_bf16_f32 v0, v0, s0
	ds_write_b16 v57, v0 offset:53312
	v_mul_f32_e32 v0, v27, v50
	v_cvt_pk_bf16_f32 v0, v0, s0
	ds_write_b16 v57, v0 offset:53376
	v_mul_f32_e32 v0, v43, v50
	v_cvt_pk_bf16_f32 v0, v0, s0
	ds_write_b16 v57, v0 offset:53440
	v_mul_f32_e32 v0, v28, v51
	v_cvt_pk_bf16_f32 v0, v0, s0
	ds_write_b16 v57, v0 offset:53504
	v_mul_f32_e32 v0, v44, v51
	v_cvt_pk_bf16_f32 v0, v0, s0
	ds_write_b16 v57, v0 offset:53568
	v_mul_f32_e32 v0, v29, v52
	v_cvt_pk_bf16_f32 v0, v0, s0
	ds_write_b16 v57, v0 offset:53632
	v_mul_f32_e32 v0, v45, v52
	v_cvt_pk_bf16_f32 v0, v0, s0
	ds_write_b16 v57, v0 offset:53696
	v_mul_f32_e32 v0, v30, v53
	v_cvt_pk_bf16_f32 v0, v0, s0
	ds_write_b16 v57, v0 offset:54272
	v_mul_f32_e32 v0, v46, v53
	v_cvt_pk_bf16_f32 v0, v0, s0
	ds_write_b16 v57, v0 offset:54336
	v_mul_f32_e32 v0, v31, v54
	v_cvt_pk_bf16_f32 v0, v0, s0
	ds_write_b16 v57, v0 offset:54400
	v_mul_f32_e32 v0, v47, v54
	v_cvt_pk_bf16_f32 v0, v0, s0
	ds_write_b16 v57, v0 offset:54464
	v_mul_f32_e32 v0, v32, v55
	v_cvt_pk_bf16_f32 v0, v0, s0
	ds_write_b16 v57, v0 offset:54528
	v_mul_f32_e32 v0, v48, v55
	v_cvt_pk_bf16_f32 v0, v0, s0
	ds_write_b16 v57, v0 offset:54592
	v_mul_f32_e32 v0, v33, v56
	v_cvt_pk_bf16_f32 v0, v0, s0
	ds_write_b16 v57, v0 offset:54656
	v_mul_f32_e32 v0, v49, v56
	v_cvt_pk_bf16_f32 v18, v18, s0
	v_cvt_pk_bf16_f32 v0, v0, s0
	ds_write_b16 v57, v18 offset:53248
	ds_write_b16 v57, v0 offset:54720
	s_lshl_b64 s[46:47], s[46:47], 11
	s_waitcnt lgkmcnt(0)
	s_add_u32 s46, s69, s46
	s_addc_u32 s47, s70, s47
	s_mov_b64 s[48:49], -1
	s_and_b64 vcc, exec, s[42:43]
	s_cbranch_vccz .LBB0_470
; __device__ __forceinline__ unsigned cvtpk_s(float lo,float hi){f32x2_t v={lo,hi};bf16x2_t b=__builtin_convertvector(v,bf16x2_t);return __builtin_bit_cast(unsigned,b);}
; template<int THRL,bool FIXREF,bool HALFK> __device__ __forceinline__ void attn_unit(float mref,long rowbase,int q0,const bf16*Qh,int PQ,const bf16*__restrict__ Kh_,int PK,const bf16*__restrict__ Vh_,int PV,bf16*Oh,int PO,const bf16*Gh,int PG,u32x4(&okeep)[4],int omode,float lam,float oml,const float ...
;     ...
;     else if(Gh){
;       u32x4 gv[4]; const char*gst=shm+LDS_GST+wid*4096+lane*16;
;       #pragma unroll
;       for(int i=0;i<4;++i) gv[i]=*(const u32x4*)(gst+i*1024);
;       #pragma unroll
;       for(int i=0;i<4;++i){const int row=i*8+(lane>>3),ch=lane&7; u32x4 v=*(const u32x4*)(stg+row*64+ch*8);
;         #pragma unroll
;         for(int k=0;k<4;++k){ const float g0=__uint_as_float(gv[i][k]<<16),g1=__uint_as_float(gv[i][k]&0xffff0000u),o0=__uint_as_float(v[k]<<16),o1=__uint_as_float(v[k]&0xffff0000u);
;           v[k]=cvtpk_s(o0*g0*__builtin_amdgcn_rcpf(1.f+__builtin_amdgcn_exp2f(-1.4426950408889634f*g0)),o1*g1*__builtin_amdgcn_rcpf(1.f+__builtin_amdgcn_exp2f(-1.4426950408889634f*g1))); }
;         ATTN_STORE16(Ow+(long)row*PO+ch*8,v);} }
	s_mov_b64 s[42:43], -1
	s_and_b64 vcc, exec, s[40:41]
	s_cbranch_vccz .LBB0_467
	v_lshl_add_u32 v0, v209, 4, s20
	v_add_u32_e32 v0, 0x14800, v0
	ds_read_b128 v[30:33], v0
	ds_read_b128 v[26:29], v0 offset:1024
	ds_read_b128 v[22:25], v0 offset:2048
	ds_read_b128 v[18:21], v0 offset:3072
	v_lshlrev_b32_e32 v0, 1, v211
	v_and_b32_e32 v0, 0x70, v0
	v_add_u32_e32 v36, s20, v0
	v_lshl_add_u64 v[34:35], s[46:47], 0, v[0:1]
	v_lshl_add_u32 v0, v208, 7, v36
	s_waitcnt lgkmcnt(3)
	v_lshlrev_b32_e32 v44, 16, v30
	ds_read_b128 v[38:41], v0 offset:51200
	v_mul_f32_e32 v0, 0xbfb8aa3b, v44
	v_exp_f32_e32 v0, v0
	v_and_b32_e32 v43, 0xffff0000, v30
	s_mov_b64 s[42:43], 0
	s_waitcnt lgkmcnt(0)
	v_lshlrev_b32_e32 v42, 16, v38
	v_add_f32_e32 v0, 1.0, v0
	v_rcp_f32_e32 v46, v0
	v_mul_f32_e32 v0, 0xbfb8aa3b, v43
	v_exp_f32_e32 v0, v0
	v_and_b32_e32 v45, 0xffff0000, v38
	v_lshlrev_b32_e32 v38, 16, v31
	v_pk_mul_f32 v[44:45], v[42:43], v[44:45]
	v_add_f32_e32 v0, 1.0, v0
	v_rcp_f32_e32 v47, v0
	v_mul_f32_e32 v0, 0xbfb8aa3b, v38
	v_exp_f32_e32 v0, v0
	v_pk_mul_f32 v[42:43], v[46:47], v[44:45]
	s_nop 0
	v_cvt_pk_bf16_f32 v30, v42, v43
	v_and_b32_e32 v43, 0xffff0000, v31
	v_add_f32_e32 v0, 1.0, v0
	v_rcp_f32_e32 v44, v0
	v_mul_f32_e32 v0, 0xbfb8aa3b, v43
	v_exp_f32_e32 v0, v0
	v_lshlrev_b32_e32 v42, 16, v39
	v_and_b32_e32 v39, 0xffff0000, v39
	v_pk_mul_f32 v[38:39], v[42:43], v[38:39]
	v_add_f32_e32 v0, 1.0, v0
	v_lshlrev_b32_e32 v42, 16, v32
	v_rcp_f32_e32 v45, v0
	v_mul_f32_e32 v0, 0xbfb8aa3b, v42
	v_exp_f32_e32 v0, v0
	v_and_b32_e32 v43, 0xffff0000, v40
	v_pk_mul_f32 v[38:39], v[44:45], v[38:39]
	v_add_f32_e32 v0, 1.0, v0
	v_cvt_pk_bf16_f32 v31, v38, v39
	v_and_b32_e32 v39, 0xffff0000, v32
	v_rcp_f32_e32 v44, v0
	v_mul_f32_e32 v0, 0xbfb8aa3b, v39
	v_exp_f32_e32 v0, v0
	v_lshlrev_b32_e32 v38, 16, v40
	v_lshlrev_b32_e32 v40, 16, v33
	v_pk_mul_f32 v[42:43], v[38:39], v[42:43]
	v_add_f32_e32 v0, 1.0, v0
	v_rcp_f32_e32 v45, v0
	v_mul_f32_e32 v0, 0xbfb8aa3b, v40
	v_exp_f32_e32 v0, v0
	v_pk_mul_f32 v[38:39], v[44:45], v[42:43]
	s_nop 0
	v_cvt_pk_bf16_f32 v32, v38, v39
	v_and_b32_e32 v39, 0xffff0000, v33
	v_add_f32_e32 v0, 1.0, v0
	v_rcp_f32_e32 v42, v0
	v_mul_f32_e32 v0, 0xbfb8aa3b, v39
	v_exp_f32_e32 v0, v0
	v_lshlrev_b32_e32 v38, 16, v41
	v_and_b32_e32 v41, 0xffff0000, v41
	v_pk_mul_f32 v[40:41], v[38:39], v[40:41]
	v_add_f32_e32 v0, 1.0, v0
	v_rcp_f32_e32 v43, v0
	v_lshlrev_b32_e32 v0, 11, v208
	v_pk_mul_f32 v[38:39], v[42:43], v[40:41]
	s_nop 0
	v_cvt_pk_bf16_f32 v33, v38, v39
	v_lshl_add_u64 v[38:39], v[34:35], 0, v[0:1]
	v_lshlrev_b32_e32 v40, 16, v26
	global_store_dwordx4 v[38:39], v[30:33], off
	v_and_b32_e32 v39, 0xffff0000, v26
	v_mul_f32_e32 v26, 0xbfb8aa3b, v40
	v_exp_f32_e32 v26, v26
	v_or_b32_e32 v0, 8, v208
	v_lshl_add_u32 v30, v0, 7, v36
	ds_read_b128 v[30:33], v30 offset:51200
	v_add_f32_e32 v26, 1.0, v26
	v_rcp_f32_e32 v42, v26
	v_mul_f32_e32 v26, 0xbfb8aa3b, v39
	v_exp_f32_e32 v26, v26
	s_waitcnt lgkmcnt(0)
	v_lshlrev_b32_e32 v38, 16, v30
	v_and_b32_e32 v41, 0xffff0000, v30
	v_pk_mul_f32 v[40:41], v[38:39], v[40:41]
	v_add_f32_e32 v26, 1.0, v26
	v_rcp_f32_e32 v43, v26
	v_lshlrev_b32_e32 v30, 16, v27
	v_lshlrev_b32_e32 v0, 11, v0
	v_pk_mul_f32 v[38:39], v[42:43], v[40:41]
	s_nop 0
	v_cvt_pk_bf16_f32 v26, v38, v39
	v_and_b32_e32 v39, 0xffff0000, v27
	v_mul_f32_e32 v27, 0xbfb8aa3b, v30
	v_exp_f32_e32 v27, v27
	v_lshlrev_b32_e32 v38, 16, v31
	v_and_b32_e32 v31, 0xffff0000, v31
	v_pk_mul_f32 v[30:31], v[38:39], v[30:31]
	v_add_f32_e32 v27, 1.0, v27
	v_rcp_f32_e32 v40, v27
	v_mul_f32_e32 v27, 0xbfb8aa3b, v39
	v_exp_f32_e32 v27, v27
	v_lshlrev_b32_e32 v38, 16, v28
	v_and_b32_e32 v39, 0xffff0000, v32
	v_add_f32_e32 v27, 1.0, v27
	v_rcp_f32_e32 v41, v27
	s_nop 0
	v_pk_mul_f32 v[30:31], v[40:41], v[30:31]
	s_nop 0
	v_cvt_pk_bf16_f32 v27, v30, v31
	v_and_b32_e32 v31, 0xffff0000, v28
	v_mul_f32_e32 v28, 0xbfb8aa3b, v38
	v_exp_f32_e32 v28, v28
	v_lshlrev_b32_e32 v30, 16, v32
	v_pk_mul_f32 v[38:39], v[30:31], v[38:39]
	v_lshlrev_b32_e32 v32, 16, v29
	v_add_f32_e32 v28, 1.0, v28
	v_rcp_f32_e32 v40, v28
	v_mul_f32_e32 v28, 0xbfb8aa3b, v31
	v_exp_f32_e32 v28, v28
	s_nop 0
	v_add_f32_e32 v28, 1.0, v28
	v_rcp_f32_e32 v41, v28
	s_nop 0
	v_pk_mul_f32 v[30:31], v[40:41], v[38:39]
	s_nop 0
	v_cvt_pk_bf16_f32 v28, v30, v31
	v_and_b32_e32 v31, 0xffff0000, v29
	v_mul_f32_e32 v29, 0xbfb8aa3b, v32
	v_exp_f32_e32 v29, v29
	v_lshlrev_b32_e32 v30, 16, v33
	v_and_b32_e32 v33, 0xffff0000, v33
	v_pk_mul_f32 v[32:33], v[30:31], v[32:33]
	v_add_f32_e32 v29, 1.0, v29
	v_rcp_f32_e32 v38, v29
	v_mul_f32_e32 v29, 0xbfb8aa3b, v31
	v_exp_f32_e32 v29, v29
	s_nop 0
	v_add_f32_e32 v29, 1.0, v29
	v_rcp_f32_e32 v39, v29
	s_nop 0
	v_pk_mul_f32 v[30:31], v[38:39], v[32:33]
	s_nop 0
	v_cvt_pk_bf16_f32 v29, v30, v31
	v_lshl_add_u64 v[30:31], v[34:35], 0, v[0:1]
	v_lshlrev_b32_e32 v32, 16, v22
	global_store_dwordx4 v[30:31], v[26:29], off
	v_and_b32_e32 v31, 0xffff0000, v22
	v_mul_f32_e32 v22, 0xbfb8aa3b, v32
	v_exp_f32_e32 v22, v22
	v_or_b32_e32 v0, 16, v208
	v_lshl_add_u32 v26, v0, 7, v36
	ds_read_b128 v[26:29], v26 offset:51200
	v_add_f32_e32 v22, 1.0, v22
	v_rcp_f32_e32 v38, v22
	v_mul_f32_e32 v22, 0xbfb8aa3b, v31
	v_exp_f32_e32 v22, v22
	s_waitcnt lgkmcnt(0)
; __device__ __forceinline__ unsigned cvtpk_s(float lo,float hi){f32x2_t v={lo,hi};bf16x2_t b=__builtin_convertvector(v,bf16x2_t);return __builtin_bit_cast(unsigned,b);}
; template<int THRL,bool FIXREF,bool HALFK> __device__ __forceinline__ void attn_unit(float mref,long rowbase,int q0,const bf16*Qh,int PQ,const bf16*__restrict__ Kh_,int PK,const bf16*__restrict__ Vh_,int PV,bf16*Oh,int PO,const bf16*Gh,int PG,u32x4(&okeep)[4],int omode,float lam,float oml,const float ...
;     ...
;       for(int i=0;i<4;++i){const int row=i*8+(lane>>3),ch=lane&7; u32x4 v=*(const u32x4*)(stg+row*64+ch*8);
;         #pragma unroll
;         for(int k=0;k<4;++k){ const float g0=__uint_as_float(gv[i][k]<<16),g1=__uint_as_float(gv[i][k]&0xffff0000u),o0=__uint_as_float(v[k]<<16),o1=__uint_as_float(v[k]&0xffff0000u);
;           v[k]=cvtpk_s(o0*g0*__builtin_amdgcn_rcpf(1.f+__builtin_amdgcn_exp2f(-1.4426950408889634f*g0)),o1*g1*__builtin_amdgcn_rcpf(1.f+__builtin_amdgcn_exp2f(-1.4426950408889634f*g1))); }
;         ATTN_STORE16(Ow+(long)row*PO+ch*8,v);} }
	v_lshlrev_b32_e32 v30, 16, v26
	v_and_b32_e32 v33, 0xffff0000, v26
	v_pk_mul_f32 v[32:33], v[30:31], v[32:33]
	v_add_f32_e32 v22, 1.0, v22
	v_rcp_f32_e32 v39, v22
	v_lshlrev_b32_e32 v26, 16, v23
	v_lshlrev_b32_e32 v0, 11, v0
	v_pk_mul_f32 v[30:31], v[38:39], v[32:33]
	s_nop 0
	v_cvt_pk_bf16_f32 v22, v30, v31
	v_and_b32_e32 v31, 0xffff0000, v23
	v_mul_f32_e32 v23, 0xbfb8aa3b, v26
	v_exp_f32_e32 v23, v23
	v_lshlrev_b32_e32 v30, 16, v27
	v_and_b32_e32 v27, 0xffff0000, v27
	v_pk_mul_f32 v[26:27], v[30:31], v[26:27]
	v_add_f32_e32 v23, 1.0, v23
	v_rcp_f32_e32 v32, v23
	v_mul_f32_e32 v23, 0xbfb8aa3b, v31
	v_exp_f32_e32 v23, v23
	v_lshlrev_b32_e32 v30, 16, v24
	v_and_b32_e32 v31, 0xffff0000, v28
	v_add_f32_e32 v23, 1.0, v23
	v_rcp_f32_e32 v33, v23
	s_nop 0
	v_pk_mul_f32 v[26:27], v[32:33], v[26:27]
	s_nop 0
	v_cvt_pk_bf16_f32 v23, v26, v27
	v_and_b32_e32 v27, 0xffff0000, v24
	v_mul_f32_e32 v24, 0xbfb8aa3b, v30
	v_exp_f32_e32 v24, v24
	v_lshlrev_b32_e32 v26, 16, v28
	v_pk_mul_f32 v[30:31], v[26:27], v[30:31]
	v_lshlrev_b32_e32 v28, 16, v25
	v_add_f32_e32 v24, 1.0, v24
	v_rcp_f32_e32 v32, v24
	v_mul_f32_e32 v24, 0xbfb8aa3b, v27
	v_exp_f32_e32 v24, v24
	s_nop 0
	v_add_f32_e32 v24, 1.0, v24
	v_rcp_f32_e32 v33, v24
	s_nop 0
	v_pk_mul_f32 v[26:27], v[32:33], v[30:31]
	s_nop 0
	v_cvt_pk_bf16_f32 v24, v26, v27
	v_and_b32_e32 v27, 0xffff0000, v25
	v_mul_f32_e32 v25, 0xbfb8aa3b, v28
	v_exp_f32_e32 v25, v25
	v_lshlrev_b32_e32 v26, 16, v29
	v_and_b32_e32 v29, 0xffff0000, v29
	v_pk_mul_f32 v[28:29], v[26:27], v[28:29]
	v_add_f32_e32 v25, 1.0, v25
	v_rcp_f32_e32 v30, v25
	v_mul_f32_e32 v25, 0xbfb8aa3b, v27
	v_exp_f32_e32 v25, v25
	s_nop 0
	v_add_f32_e32 v25, 1.0, v25
	v_rcp_f32_e32 v31, v25
	s_nop 0
	v_pk_mul_f32 v[26:27], v[30:31], v[28:29]
	s_nop 0
	v_cvt_pk_bf16_f32 v25, v26, v27
	v_lshl_add_u64 v[26:27], v[34:35], 0, v[0:1]
	v_lshlrev_b32_e32 v28, 16, v18
	global_store_dwordx4 v[26:27], v[22:25], off
	v_and_b32_e32 v27, 0xffff0000, v18
	v_mul_f32_e32 v18, 0xbfb8aa3b, v28
	v_exp_f32_e32 v18, v18
	v_or_b32_e32 v0, 24, v208
	v_lshl_add_u32 v22, v0, 7, v36
	ds_read_b128 v[22:25], v22 offset:51200
	v_add_f32_e32 v18, 1.0, v18
	v_rcp_f32_e32 v30, v18
	v_mul_f32_e32 v18, 0xbfb8aa3b, v27
	v_exp_f32_e32 v18, v18
	s_waitcnt lgkmcnt(0)
	v_lshlrev_b32_e32 v26, 16, v22
	v_and_b32_e32 v29, 0xffff0000, v22
	v_pk_mul_f32 v[28:29], v[26:27], v[28:29]
	v_add_f32_e32 v18, 1.0, v18
	v_rcp_f32_e32 v31, v18
	v_lshlrev_b32_e32 v22, 16, v19
	v_lshlrev_b32_e32 v0, 11, v0
	v_pk_mul_f32 v[26:27], v[30:31], v[28:29]
	s_nop 0
	v_cvt_pk_bf16_f32 v18, v26, v27
	v_and_b32_e32 v27, 0xffff0000, v19
	v_mul_f32_e32 v19, 0xbfb8aa3b, v22
	v_exp_f32_e32 v19, v19
	v_lshlrev_b32_e32 v26, 16, v23
	v_and_b32_e32 v23, 0xffff0000, v23
	v_pk_mul_f32 v[22:23], v[26:27], v[22:23]
	v_add_f32_e32 v19, 1.0, v19
	v_rcp_f32_e32 v28, v19
	v_mul_f32_e32 v19, 0xbfb8aa3b, v27
	v_exp_f32_e32 v19, v19
	v_lshlrev_b32_e32 v26, 16, v20
	v_and_b32_e32 v27, 0xffff0000, v24
	v_add_f32_e32 v19, 1.0, v19
	v_rcp_f32_e32 v29, v19
	s_nop 0
	v_pk_mul_f32 v[22:23], v[28:29], v[22:23]
	s_nop 0
	v_cvt_pk_bf16_f32 v19, v22, v23
	v_and_b32_e32 v23, 0xffff0000, v20
	v_mul_f32_e32 v20, 0xbfb8aa3b, v26
	v_exp_f32_e32 v20, v20
	v_lshlrev_b32_e32 v22, 16, v24
	v_pk_mul_f32 v[26:27], v[22:23], v[26:27]
	v_lshlrev_b32_e32 v24, 16, v21
	v_add_f32_e32 v20, 1.0, v20
	v_rcp_f32_e32 v28, v20
	v_mul_f32_e32 v20, 0xbfb8aa3b, v23
	v_exp_f32_e32 v20, v20
	s_nop 0
	v_add_f32_e32 v20, 1.0, v20
	v_rcp_f32_e32 v29, v20
	s_nop 0
	v_pk_mul_f32 v[22:23], v[28:29], v[26:27]
	s_nop 0
	v_cvt_pk_bf16_f32 v20, v22, v23
	v_and_b32_e32 v23, 0xffff0000, v21
	v_mul_f32_e32 v21, 0xbfb8aa3b, v24
	v_exp_f32_e32 v21, v21
	v_lshlrev_b32_e32 v22, 16, v25
	v_and_b32_e32 v25, 0xffff0000, v25
	v_pk_mul_f32 v[24:25], v[22:23], v[24:25]
	v_add_f32_e32 v21, 1.0, v21
	v_rcp_f32_e32 v26, v21
	v_mul_f32_e32 v21, 0xbfb8aa3b, v23
	v_exp_f32_e32 v21, v21
	s_nop 0
	v_add_f32_e32 v21, 1.0, v21
	v_rcp_f32_e32 v27, v21
	s_nop 0
	v_pk_mul_f32 v[22:23], v[26:27], v[24:25]
	s_nop 0
	v_cvt_pk_bf16_f32 v21, v22, v23
	v_lshl_add_u64 v[22:23], v[34:35], 0, v[0:1]
	global_store_dwordx4 v[22:23], v[18:21], off
